# xattn V^T staging remapped to avoid 32-way LDS bank conflicts on the transposing 2-byte writes (on top of scan rewrite)
# speedup vs baseline: 1.0050x; 1.0050x over previous
; #define LAS __attribute__((address_space(3)))
; __device__ __forceinline__ void xattn_lds(const Ctx& C, const bf16* P, int cqoff, const bf16* MEMKV, const bf16* MEMVT, bf16* CAT, int ldc, int catoff, int u0, int ustride) {
;     ...
;     for (int u = u0; u < 256; u += ustride) {
;         const int b = u >> 7, xh = (u >> 5) & 3, qb = u & 31;
;         const int qrow = b * SEQ + qb * 128 + w * 16 + c;
;         bf16x8v qf[8];
;         { const bf16* qp = P + (size_t)qrow * LDP + cqoff + xh * 256 + 8 * g;
; #pragma unroll
;           for (int ks = 0; ks < 8; ++ks) qf[ks] = *(const bf16x8v*)(qp + 32 * ks); }
;         f32x4 s[16];
; #pragma unroll
;         for (int kt = 0; kt < 16; ++kt) s[kt] = (f32x4){0.f, 0.f, 0.f, 0.f};
; #pragma unroll
;         for (int half = 0; half < 2; ++half) {
;             v4u stg[8];
; #pragma unroll
;             for (int it = 0; it < 8; ++it) { const int idx = it * 512 + tid, row = idx >> 5, c16 = idx & 31;
;                 stg[it] = *(const v4u*)(MEMKV + (size_t)(b * 256 + half * 128 + row) * 2048 + xh * 256 + c16 * 8); }
;             __syncthreads();
; #pragma unroll
;             for (int it = 0; it < 8; ++it) { const int idx = it * 512 + tid, row = idx >> 5, c16 = idx & 31; *(LAS v4u*)(Ls + row * KP + c16 * 16) = stg[it]; }
;             __syncthreads();
; #pragma unroll
;             for (int kt = 0; kt < 8; ++kt) {
; #pragma unroll
;                 for (int ks = 0; ks < 8; ++ks) { const bf16x8v kf = *(const LAS bf16x8v*)(Ls + (16 * kt + c) * KP + (32 * ks + 8 * g) * 2);
;                     s[8 * half + kt] = __builtin_amdgcn_mfma_f32_16x16x32_bf16(kf, qf[ks], s[8 * half + kt], 0, 0, 0); }
;                 asm volatile("" ::: "memory"); }
.LBB0_466:
	s_ashr_i32 s17, s8, 7
	s_lshl_b32 s0, s17, 12
	s_and_b32 s1, s11, 0xf80
	s_or_b32 s0, s0, s1
	v_add_u32_e32 v104, s0, v1
	v_mad_i64_i32 v[2:3], s[0:1], v104, s13, v[98:99]
	s_and_b32 s0, s9, 0x300
	s_lshl_b32 s6, s0, 1
	v_lshl_add_u64 v[2:3], v[2:3], 0, s[6:7]
	v_lshl_add_u64 v[2:3], v[2:3], 0, v[94:95]
	s_lshl_b32 s0, s17, 8
	global_load_dwordx4 v[70:73], v[2:3], off
	global_load_dwordx4 v[62:65], v[2:3], off offset:64
	global_load_dwordx4 v[54:57], v[2:3], off offset:128
	global_load_dwordx4 v[50:53], v[2:3], off offset:192
	global_load_dwordx4 v[46:49], v[2:3], off offset:256
	global_load_dwordx4 v[42:45], v[2:3], off offset:320
	global_load_dwordx4 v[38:41], v[2:3], off offset:384
	global_load_dwordx4 v[34:37], v[2:3], off offset:448
	v_add_u32_e32 v2, s0, v138
	v_ashrrev_i32_e32 v3, 31, v2
	v_add_u32_e32 v6, s0, v139
	v_lshl_add_u64 v[58:59], v[96:97], 0, s[6:7]
	v_lshlrev_b64 v[122:123], 12, v[2:3]
	v_ashrrev_i32_e32 v7, 31, v6
	v_add_u32_e32 v10, s0, v140
	v_lshl_add_u64 v[2:3], v[58:59], 0, v[122:123]
	v_lshlrev_b64 v[124:125], 12, v[6:7]
	v_ashrrev_i32_e32 v11, 31, v10
	v_add_u32_e32 v14, s0, v141
	global_load_dwordx4 v[2:5], v[2:3], off
	v_lshl_add_u64 v[6:7], v[58:59], 0, v[124:125]
	v_lshlrev_b64 v[126:127], 12, v[10:11]
	v_ashrrev_i32_e32 v15, 31, v14
	v_add_u32_e32 v18, s0, v142
	global_load_dwordx4 v[6:9], v[6:7], off
	v_lshl_add_u64 v[10:11], v[58:59], 0, v[126:127]
	v_lshlrev_b64 v[128:129], 12, v[14:15]
	v_ashrrev_i32_e32 v19, 31, v18
	v_add_u32_e32 v22, s0, v143
	global_load_dwordx4 v[10:13], v[10:11], off
	v_lshl_add_u64 v[14:15], v[58:59], 0, v[128:129]
	v_lshlrev_b64 v[130:131], 12, v[18:19]
	v_ashrrev_i32_e32 v23, 31, v22
	v_add_u32_e32 v26, s0, v144
	global_load_dwordx4 v[14:17], v[14:15], off
	v_lshl_add_u64 v[18:19], v[58:59], 0, v[130:131]
	v_lshlrev_b64 v[132:133], 12, v[22:23]
	v_ashrrev_i32_e32 v27, 31, v26
	v_add_u32_e32 v30, s0, v145
	global_load_dwordx4 v[18:21], v[18:19], off
	v_lshl_add_u64 v[22:23], v[58:59], 0, v[132:133]
	v_lshlrev_b64 v[134:135], 12, v[26:27]
	v_ashrrev_i32_e32 v31, 31, v30
	global_load_dwordx4 v[22:25], v[22:23], off
	v_lshl_add_u64 v[26:27], v[58:59], 0, v[134:135]
	v_lshlrev_b64 v[136:137], 12, v[30:31]
	global_load_dwordx4 v[26:29], v[26:27], off
	v_lshl_add_u64 v[30:31], v[58:59], 0, v[136:137]
	global_load_dwordx4 v[30:33], v[30:31], off
	s_barrier
	s_bitset1_b32 s0, 7
	v_add_u32_e32 v60, s0, v138
	v_ashrrev_i32_e32 v61, 31, v60
	v_lshlrev_b64 v[106:107], 12, v[60:61]
	v_lshl_add_u64 v[60:61], v[58:59], 0, v[106:107]
	v_cmp_lt_i32_e32 vcc, v166, v167
	v_ashrrev_i32_e32 v105, 31, v104
	s_add_i32 s8, s8, s86
	s_add_i32 s9, s9, s10
	s_add_i32 s11, s11, s12
	s_cmpk_lt_i32 s8, 0x100
	s_waitcnt vmcnt(7)
	ds_write_b128 v147, v[2:5]
	s_waitcnt vmcnt(6)
	ds_write_b128 v148, v[6:9]
	s_waitcnt vmcnt(5)
	ds_write_b128 v149, v[10:13]
	s_waitcnt vmcnt(4)
	ds_write_b128 v150, v[14:17]
	s_waitcnt vmcnt(3)
	ds_write_b128 v151, v[18:21]
	s_waitcnt vmcnt(2)
	ds_write_b128 v152, v[22:25]
	s_waitcnt vmcnt(1)
	ds_write_b128 v153, v[26:29]
	s_waitcnt vmcnt(0)
	ds_write_b128 v154, v[30:33]
	s_waitcnt lgkmcnt(0)
	s_barrier
	ds_read_b128 v[2:5], v155
	ds_read_b128 v[6:9], v155 offset:64
	s_waitcnt lgkmcnt(1)
	v_mfma_f32_16x16x32_bf16 v[2:5], v[2:5], v[70:73], 0
	s_waitcnt lgkmcnt(0)
	v_mfma_f32_16x16x32_bf16 v[2:5], v[6:9], v[62:65], v[2:5]
	ds_read_b128 v[6:9], v155 offset:128
	s_waitcnt lgkmcnt(0)
	v_mfma_f32_16x16x32_bf16 v[2:5], v[6:9], v[54:57], v[2:5]
	ds_read_b128 v[6:9], v155 offset:192
	s_waitcnt lgkmcnt(0)
	v_mfma_f32_16x16x32_bf16 v[2:5], v[6:9], v[50:53], v[2:5]
	ds_read_b128 v[6:9], v155 offset:256
	s_waitcnt lgkmcnt(0)
	v_mfma_f32_16x16x32_bf16 v[2:5], v[6:9], v[46:49], v[2:5]
	ds_read_b128 v[6:9], v155 offset:320
	s_waitcnt lgkmcnt(0)
	v_mfma_f32_16x16x32_bf16 v[2:5], v[6:9], v[42:45], v[2:5]
	ds_read_b128 v[6:9], v155 offset:384
	s_waitcnt lgkmcnt(0)
	v_mfma_f32_16x16x32_bf16 v[2:5], v[6:9], v[38:41], v[2:5]
	ds_read_b128 v[6:9], v155 offset:448
	ds_read_b128 v[10:13], v155 offset:8512
	s_waitcnt lgkmcnt(1)
	v_mfma_f32_16x16x32_bf16 v[2:5], v[6:9], v[34:37], v[2:5]
	ds_read_b128 v[6:9], v155 offset:8448
	s_waitcnt lgkmcnt(0)
	v_mfma_f32_16x16x32_bf16 v[6:9], v[6:9], v[70:73], 0
	v_mfma_f32_16x16x32_bf16 v[6:9], v[10:13], v[62:65], v[6:9]
	ds_read_b128 v[10:13], v155 offset:8576
	s_waitcnt lgkmcnt(0)
	v_mfma_f32_16x16x32_bf16 v[6:9], v[10:13], v[54:57], v[6:9]
	ds_read_b128 v[10:13], v155 offset:8640
	s_waitcnt lgkmcnt(0)
	v_mfma_f32_16x16x32_bf16 v[6:9], v[10:13], v[50:53], v[6:9]
	ds_read_b128 v[10:13], v155 offset:8704
	s_waitcnt lgkmcnt(0)
	v_mfma_f32_16x16x32_bf16 v[6:9], v[10:13], v[46:49], v[6:9]
	ds_read_b128 v[10:13], v155 offset:8768
	s_waitcnt lgkmcnt(0)
	v_mfma_f32_16x16x32_bf16 v[6:9], v[10:13], v[42:45], v[6:9]
	ds_read_b128 v[10:13], v155 offset:8832
	s_waitcnt lgkmcnt(0)
	v_mfma_f32_16x16x32_bf16 v[6:9], v[10:13], v[38:41], v[6:9]
	ds_read_b128 v[10:13], v155 offset:8896
	ds_read_b128 v[14:17], v155 offset:16960
	s_waitcnt lgkmcnt(1)
	v_mfma_f32_16x16x32_bf16 v[10:13], v[10:13], v[34:37], v[6:9]
	s_nop 3
	ds_read_b128 v[6:9], v155 offset:16896
	s_waitcnt lgkmcnt(0)
	v_mfma_f32_16x16x32_bf16 v[6:9], v[6:9], v[70:73], 0
	v_mfma_f32_16x16x32_bf16 v[6:9], v[14:17], v[62:65], v[6:9]
	ds_read_b128 v[14:17], v155 offset:17024
	s_waitcnt lgkmcnt(0)
	v_mfma_f32_16x16x32_bf16 v[6:9], v[14:17], v[54:57], v[6:9]
	ds_read_b128 v[14:17], v155 offset:17088
	s_waitcnt lgkmcnt(0)
	v_mfma_f32_16x16x32_bf16 v[6:9], v[14:17], v[50:53], v[6:9]
	ds_read_b128 v[14:17], v155 offset:17152
	s_waitcnt lgkmcnt(0)
	v_mfma_f32_16x16x32_bf16 v[6:9], v[14:17], v[46:49], v[6:9]
	ds_read_b128 v[14:17], v155 offset:17216
	s_waitcnt lgkmcnt(0)
; #define LAS __attribute__((address_space(3)))
; __device__ __forceinline__ void xattn_lds(const Ctx& C, const bf16* P, int cqoff, const bf16* MEMKV, const bf16* MEMVT, bf16* CAT, int ldc, int catoff, int u0, int ustride) {
;     ...
;         for (int half = 0; half < 2; ++half) {
;             v4u stg[8];
; #pragma unroll
;             for (int it = 0; it < 8; ++it) { const int idx = it * 512 + tid, row = idx >> 5, c16 = idx & 31;
;                 stg[it] = *(const v4u*)(MEMKV + (size_t)(b * 256 + half * 128 + row) * 2048 + xh * 256 + c16 * 8); }
;             __syncthreads();
; #pragma unroll
;             for (int it = 0; it < 8; ++it) { const int idx = it * 512 + tid, row = idx >> 5, c16 = idx & 31; *(LAS v4u*)(Ls + row * KP + c16 * 16) = stg[it]; }
;             __syncthreads();
; #pragma unroll
;             for (int kt = 0; kt < 8; ++kt) {
; #pragma unroll
;                 for (int ks = 0; ks < 8; ++ks) { const bf16x8v kf = *(const LAS bf16x8v*)(Ls + (16 * kt + c) * KP + (32 * ks + 8 * g) * 2);
;                     s[8 * half + kt] = __builtin_amdgcn_mfma_f32_16x16x32_bf16(kf, qf[ks], s[8 * half + kt], 0, 0, 0); }
;                 asm volatile("" ::: "memory"); }
	v_mfma_f32_16x16x32_bf16 v[6:9], v[14:17], v[42:45], v[6:9]
	ds_read_b128 v[14:17], v155 offset:17280
	s_waitcnt lgkmcnt(0)
	v_mfma_f32_16x16x32_bf16 v[6:9], v[14:17], v[38:41], v[6:9]
	ds_read_b128 v[14:17], v155 offset:17344
	ds_read_b128 v[18:21], v155 offset:25408
	s_waitcnt lgkmcnt(1)
	v_mfma_f32_16x16x32_bf16 v[6:9], v[14:17], v[34:37], v[6:9]
	ds_read_b128 v[14:17], v155 offset:25344
	s_waitcnt lgkmcnt(0)
	v_mfma_f32_16x16x32_bf16 v[14:17], v[14:17], v[70:73], 0
	v_mfma_f32_16x16x32_bf16 v[14:17], v[18:21], v[62:65], v[14:17]
	ds_read_b128 v[18:21], v155 offset:25472
	s_waitcnt lgkmcnt(0)
	v_mfma_f32_16x16x32_bf16 v[14:17], v[18:21], v[54:57], v[14:17]
	ds_read_b128 v[18:21], v155 offset:25536
	s_waitcnt lgkmcnt(0)
	v_mfma_f32_16x16x32_bf16 v[14:17], v[18:21], v[50:53], v[14:17]
	ds_read_b128 v[18:21], v155 offset:25600
	s_waitcnt lgkmcnt(0)
	v_mfma_f32_16x16x32_bf16 v[14:17], v[18:21], v[46:49], v[14:17]
	ds_read_b128 v[18:21], v155 offset:25664
	s_waitcnt lgkmcnt(0)
	v_mfma_f32_16x16x32_bf16 v[14:17], v[18:21], v[42:45], v[14:17]
	ds_read_b128 v[18:21], v155 offset:25728
	s_waitcnt lgkmcnt(0)
	v_mfma_f32_16x16x32_bf16 v[14:17], v[18:21], v[38:41], v[14:17]
	ds_read_b128 v[18:21], v155 offset:25792
	ds_read_b128 v[22:25], v155 offset:33856
	s_waitcnt lgkmcnt(1)
	v_mfma_f32_16x16x32_bf16 v[18:21], v[18:21], v[34:37], v[14:17]
	s_nop 3
	ds_read_b128 v[14:17], v155 offset:33792
	s_waitcnt lgkmcnt(0)
	v_mfma_f32_16x16x32_bf16 v[14:17], v[14:17], v[70:73], 0
	v_mfma_f32_16x16x32_bf16 v[14:17], v[22:25], v[62:65], v[14:17]
	ds_read_b128 v[22:25], v155 offset:33920
	s_waitcnt lgkmcnt(0)
	v_mfma_f32_16x16x32_bf16 v[14:17], v[22:25], v[54:57], v[14:17]
	ds_read_b128 v[22:25], v155 offset:33984
	s_waitcnt lgkmcnt(0)
	v_mfma_f32_16x16x32_bf16 v[14:17], v[22:25], v[50:53], v[14:17]
	ds_read_b128 v[22:25], v155 offset:34048
	s_waitcnt lgkmcnt(0)
	v_mfma_f32_16x16x32_bf16 v[14:17], v[22:25], v[46:49], v[14:17]
	ds_read_b128 v[22:25], v155 offset:34112
	s_waitcnt lgkmcnt(0)
	v_mfma_f32_16x16x32_bf16 v[14:17], v[22:25], v[42:45], v[14:17]
	ds_read_b128 v[22:25], v155 offset:34176
	s_waitcnt lgkmcnt(0)
	v_mfma_f32_16x16x32_bf16 v[14:17], v[22:25], v[38:41], v[14:17]
	ds_read_b128 v[22:25], v155 offset:34240
	ds_read_b128 v[26:29], v155 offset:42304
	s_waitcnt lgkmcnt(1)
	v_mfma_f32_16x16x32_bf16 v[14:17], v[22:25], v[34:37], v[14:17]
	ds_read_b128 v[22:25], v155 offset:42240
	s_waitcnt lgkmcnt(0)
	v_mfma_f32_16x16x32_bf16 v[22:25], v[22:25], v[70:73], 0
	v_mfma_f32_16x16x32_bf16 v[22:25], v[26:29], v[62:65], v[22:25]
	ds_read_b128 v[26:29], v155 offset:42368
	s_waitcnt lgkmcnt(0)
	v_mfma_f32_16x16x32_bf16 v[22:25], v[26:29], v[54:57], v[22:25]
	ds_read_b128 v[26:29], v155 offset:42432
	s_waitcnt lgkmcnt(0)
	v_mfma_f32_16x16x32_bf16 v[22:25], v[26:29], v[50:53], v[22:25]
	ds_read_b128 v[26:29], v155 offset:42496
	s_waitcnt lgkmcnt(0)
	v_mfma_f32_16x16x32_bf16 v[22:25], v[26:29], v[46:49], v[22:25]
	ds_read_b128 v[26:29], v155 offset:42560
	s_waitcnt lgkmcnt(0)
	v_mfma_f32_16x16x32_bf16 v[22:25], v[26:29], v[42:45], v[22:25]
	ds_read_b128 v[26:29], v155 offset:42624
	s_waitcnt lgkmcnt(0)
	v_mfma_f32_16x16x32_bf16 v[22:25], v[26:29], v[38:41], v[22:25]
	ds_read_b128 v[26:29], v155 offset:42688
	ds_read_b128 v[30:33], v155 offset:50752
	s_waitcnt lgkmcnt(1)
	v_mfma_f32_16x16x32_bf16 v[26:29], v[26:29], v[34:37], v[22:25]
	s_nop 3
	ds_read_b128 v[22:25], v155 offset:50688
	s_waitcnt lgkmcnt(0)
	v_mfma_f32_16x16x32_bf16 v[22:25], v[22:25], v[70:73], 0
	v_mfma_f32_16x16x32_bf16 v[22:25], v[30:33], v[62:65], v[22:25]
	ds_read_b128 v[30:33], v155 offset:50816
	s_waitcnt lgkmcnt(0)
	v_mfma_f32_16x16x32_bf16 v[22:25], v[30:33], v[54:57], v[22:25]
	ds_read_b128 v[30:33], v155 offset:50880
	s_waitcnt lgkmcnt(0)
	v_mfma_f32_16x16x32_bf16 v[22:25], v[30:33], v[50:53], v[22:25]
	ds_read_b128 v[30:33], v155 offset:50944
	s_waitcnt lgkmcnt(0)
	v_mfma_f32_16x16x32_bf16 v[22:25], v[30:33], v[46:49], v[22:25]
	ds_read_b128 v[30:33], v155 offset:51008
	s_waitcnt lgkmcnt(0)
	v_mfma_f32_16x16x32_bf16 v[22:25], v[30:33], v[42:45], v[22:25]
	ds_read_b128 v[30:33], v155 offset:51072
	s_waitcnt lgkmcnt(0)
	v_mfma_f32_16x16x32_bf16 v[22:25], v[30:33], v[38:41], v[22:25]
	ds_read_b128 v[30:33], v155 offset:51136
	ds_read_b128 v[66:69], v155 offset:59200
	s_waitcnt lgkmcnt(1)
	v_mfma_f32_16x16x32_bf16 v[22:25], v[30:33], v[34:37], v[22:25]
	ds_read_b128 v[30:33], v155 offset:59136
	s_waitcnt lgkmcnt(0)
	v_mfma_f32_16x16x32_bf16 v[30:33], v[30:33], v[70:73], 0
	v_mfma_f32_16x16x32_bf16 v[30:33], v[66:69], v[62:65], v[30:33]
	ds_read_b128 v[66:69], v155 offset:59264
	s_waitcnt lgkmcnt(0)
	v_mfma_f32_16x16x32_bf16 v[30:33], v[66:69], v[54:57], v[30:33]
	ds_read_b128 v[66:69], v155 offset:59328
	s_waitcnt lgkmcnt(0)
	v_mfma_f32_16x16x32_bf16 v[30:33], v[66:69], v[50:53], v[30:33]
	ds_read_b128 v[66:69], v155 offset:59392
	s_waitcnt lgkmcnt(0)
	v_mfma_f32_16x16x32_bf16 v[30:33], v[66:69], v[46:49], v[30:33]
	ds_read_b128 v[66:69], v155 offset:59456
	s_waitcnt lgkmcnt(0)
	v_mfma_f32_16x16x32_bf16 v[30:33], v[66:69], v[42:45], v[30:33]
	ds_read_b128 v[66:69], v155 offset:59520
	s_waitcnt lgkmcnt(0)
	v_mfma_f32_16x16x32_bf16 v[30:33], v[66:69], v[38:41], v[30:33]
	ds_read_b128 v[66:69], v155 offset:59584
	s_waitcnt lgkmcnt(0)
	v_mfma_f32_16x16x32_bf16 v[30:33], v[66:69], v[34:37], v[30:33]
	global_load_dwordx4 v[66:69], v[60:61], off
	v_add_u32_e32 v60, s0, v139
	v_ashrrev_i32_e32 v61, 31, v60
	v_lshlrev_b64 v[108:109], 12, v[60:61]
	v_lshl_add_u64 v[60:61], v[58:59], 0, v[108:109]
	global_load_dwordx4 v[74:77], v[60:61], off
	v_add_u32_e32 v60, s0, v140
	v_ashrrev_i32_e32 v61, 31, v60
	v_lshlrev_b64 v[110:111], 12, v[60:61]
	v_lshl_add_u64 v[60:61], v[58:59], 0, v[110:111]
	global_load_dwordx4 v[78:81], v[60:61], off
	v_add_u32_e32 v60, s0, v141
	v_ashrrev_i32_e32 v61, 31, v60
	v_lshlrev_b64 v[112:113], 12, v[60:61]
	v_lshl_add_u64 v[60:61], v[58:59], 0, v[112:113]
	global_load_dwordx4 v[82:85], v[60:61], off
	v_add_u32_e32 v60, s0, v142
	v_ashrrev_i32_e32 v61, 31, v60
	v_lshlrev_b64 v[114:115], 12, v[60:61]
	v_lshl_add_u64 v[60:61], v[58:59], 0, v[114:115]
	global_load_dwordx4 v[86:89], v[60:61], off
	v_add_u32_e32 v60, s0, v143
	v_ashrrev_i32_e32 v61, 31, v60
	v_lshlrev_b64 v[116:117], 12, v[60:61]
	v_lshl_add_u64 v[60:61], v[58:59], 0, v[116:117]
	global_load_dwordx4 v[90:93], v[60:61], off
	v_add_u32_e32 v60, s0, v144
	v_ashrrev_i32_e32 v61, 31, v60
	v_lshlrev_b64 v[118:119], 12, v[60:61]
	v_lshl_add_u64 v[60:61], v[58:59], 0, v[118:119]
	global_load_dwordx4 v[174:177], v[60:61], off
	v_add_u32_e32 v60, s0, v145
	v_ashrrev_i32_e32 v61, 31, v60
	v_lshlrev_b64 v[120:121], 12, v[60:61]
	v_lshl_add_u64 v[58:59], v[58:59], 0, v[120:121]
	global_load_dwordx4 v[58:61], v[58:59], off
	s_barrier
; #define LAS __attribute__((address_space(3)))
; __device__ __forceinline__ void xattn_lds(const Ctx& C, const bf16* P, int cqoff, const bf16* MEMKV, const bf16* MEMVT, bf16* CAT, int ldc, int catoff, int u0, int ustride) {
;     ...
;             __syncthreads();
; #pragma unroll
;             for (int it = 0; it < 8; ++it) { const int idx = it * 512 + tid, row = idx >> 5, c16 = idx & 31; *(LAS v4u*)(Ls + row * KP + c16 * 16) = stg[it]; }
;             __syncthreads();
; #pragma unroll
;             for (int kt = 0; kt < 8; ++kt) {
; #pragma unroll
;                 for (int ks = 0; ks < 8; ++ks) { const bf16x8v kf = *(const LAS bf16x8v*)(Ls + (16 * kt + c) * KP + (32 * ks + 8 * g) * 2);
;                     s[8 * half + kt] = __builtin_amdgcn_mfma_f32_16x16x32_bf16(kf, qf[ks], s[8 * half + kt], 0, 0, 0); }
;                 asm volatile("" ::: "memory"); }
	s_waitcnt vmcnt(7)
	ds_write_b128 v147, v[66:69]
	s_waitcnt vmcnt(6)
	ds_write_b128 v148, v[74:77]
	s_waitcnt vmcnt(5)
	ds_write_b128 v149, v[78:81]
	s_waitcnt vmcnt(4)
	ds_write_b128 v150, v[82:85]
	s_waitcnt vmcnt(3)
	ds_write_b128 v151, v[86:89]
	s_waitcnt vmcnt(2)
	ds_write_b128 v152, v[90:93]
	s_waitcnt vmcnt(1)
	ds_write_b128 v153, v[174:177]
	s_waitcnt vmcnt(0)
	ds_write_b128 v154, v[58:61]
	s_waitcnt lgkmcnt(0)
	s_barrier
	ds_read_b128 v[58:61], v155
	ds_read_b128 v[66:69], v155 offset:64
	s_waitcnt lgkmcnt(1)
	v_mfma_f32_16x16x32_bf16 v[58:61], v[58:61], v[70:73], 0
	s_waitcnt lgkmcnt(0)
	v_mfma_f32_16x16x32_bf16 v[58:61], v[66:69], v[62:65], v[58:61]
	ds_read_b128 v[66:69], v155 offset:128
	s_waitcnt lgkmcnt(0)
	v_mfma_f32_16x16x32_bf16 v[58:61], v[66:69], v[54:57], v[58:61]
	ds_read_b128 v[66:69], v155 offset:192
	s_waitcnt lgkmcnt(0)
	v_mfma_f32_16x16x32_bf16 v[58:61], v[66:69], v[50:53], v[58:61]
	ds_read_b128 v[66:69], v155 offset:256
	s_waitcnt lgkmcnt(0)
	v_mfma_f32_16x16x32_bf16 v[58:61], v[66:69], v[46:49], v[58:61]
	ds_read_b128 v[66:69], v155 offset:320
	s_waitcnt lgkmcnt(0)
	v_mfma_f32_16x16x32_bf16 v[58:61], v[66:69], v[42:45], v[58:61]
	ds_read_b128 v[66:69], v155 offset:384
	s_waitcnt lgkmcnt(0)
	v_mfma_f32_16x16x32_bf16 v[58:61], v[66:69], v[38:41], v[58:61]
	ds_read_b128 v[66:69], v155 offset:448
	ds_read_b128 v[74:77], v155 offset:8512
	s_waitcnt lgkmcnt(1)
	v_mfma_f32_16x16x32_bf16 v[58:61], v[66:69], v[34:37], v[58:61]
	ds_read_b128 v[66:69], v155 offset:8448
	s_waitcnt lgkmcnt(0)
	v_mfma_f32_16x16x32_bf16 v[66:69], v[66:69], v[70:73], 0
	v_mfma_f32_16x16x32_bf16 v[66:69], v[74:77], v[62:65], v[66:69]
	ds_read_b128 v[74:77], v155 offset:8576
	s_waitcnt lgkmcnt(0)
	v_mfma_f32_16x16x32_bf16 v[66:69], v[74:77], v[54:57], v[66:69]
	ds_read_b128 v[74:77], v155 offset:8640
	s_waitcnt lgkmcnt(0)
	v_mfma_f32_16x16x32_bf16 v[66:69], v[74:77], v[50:53], v[66:69]
	ds_read_b128 v[74:77], v155 offset:8704
	s_waitcnt lgkmcnt(0)
	v_mfma_f32_16x16x32_bf16 v[66:69], v[74:77], v[46:49], v[66:69]
	ds_read_b128 v[74:77], v155 offset:8768
	s_waitcnt lgkmcnt(0)
	v_mfma_f32_16x16x32_bf16 v[66:69], v[74:77], v[42:45], v[66:69]
	ds_read_b128 v[74:77], v155 offset:8832
	s_waitcnt lgkmcnt(0)
	v_mfma_f32_16x16x32_bf16 v[66:69], v[74:77], v[38:41], v[66:69]
	ds_read_b128 v[74:77], v155 offset:8896
	ds_read_b128 v[78:81], v155 offset:16960
	s_waitcnt lgkmcnt(1)
	v_mfma_f32_16x16x32_bf16 v[74:77], v[74:77], v[34:37], v[66:69]
	s_nop 3
	ds_read_b128 v[66:69], v155 offset:16896
	s_waitcnt lgkmcnt(0)
	v_mfma_f32_16x16x32_bf16 v[66:69], v[66:69], v[70:73], 0
	v_mfma_f32_16x16x32_bf16 v[66:69], v[78:81], v[62:65], v[66:69]
	ds_read_b128 v[78:81], v155 offset:17024
	s_waitcnt lgkmcnt(0)
	v_mfma_f32_16x16x32_bf16 v[66:69], v[78:81], v[54:57], v[66:69]
	ds_read_b128 v[78:81], v155 offset:17088
	s_waitcnt lgkmcnt(0)
	v_mfma_f32_16x16x32_bf16 v[66:69], v[78:81], v[50:53], v[66:69]
	ds_read_b128 v[78:81], v155 offset:17152
	s_waitcnt lgkmcnt(0)
	v_mfma_f32_16x16x32_bf16 v[66:69], v[78:81], v[46:49], v[66:69]
	ds_read_b128 v[78:81], v155 offset:17216
	s_waitcnt lgkmcnt(0)
	v_mfma_f32_16x16x32_bf16 v[66:69], v[78:81], v[42:45], v[66:69]
	ds_read_b128 v[78:81], v155 offset:17280
	s_waitcnt lgkmcnt(0)
	v_mfma_f32_16x16x32_bf16 v[66:69], v[78:81], v[38:41], v[66:69]
	ds_read_b128 v[78:81], v155 offset:17344
	ds_read_b128 v[82:85], v155 offset:25408
	s_waitcnt lgkmcnt(1)
	v_mfma_f32_16x16x32_bf16 v[66:69], v[78:81], v[34:37], v[66:69]
	ds_read_b128 v[78:81], v155 offset:25344
	s_waitcnt lgkmcnt(0)
	v_mfma_f32_16x16x32_bf16 v[78:81], v[78:81], v[70:73], 0
	v_mfma_f32_16x16x32_bf16 v[78:81], v[82:85], v[62:65], v[78:81]
	ds_read_b128 v[82:85], v155 offset:25472
	s_waitcnt lgkmcnt(0)
	v_mfma_f32_16x16x32_bf16 v[78:81], v[82:85], v[54:57], v[78:81]
	ds_read_b128 v[82:85], v155 offset:25536
	s_waitcnt lgkmcnt(0)
	v_mfma_f32_16x16x32_bf16 v[78:81], v[82:85], v[50:53], v[78:81]
	ds_read_b128 v[82:85], v155 offset:25600
	s_waitcnt lgkmcnt(0)
	v_mfma_f32_16x16x32_bf16 v[78:81], v[82:85], v[46:49], v[78:81]
	ds_read_b128 v[82:85], v155 offset:25664
	s_waitcnt lgkmcnt(0)
	v_mfma_f32_16x16x32_bf16 v[78:81], v[82:85], v[42:45], v[78:81]
	ds_read_b128 v[82:85], v155 offset:25728
	s_waitcnt lgkmcnt(0)
	v_mfma_f32_16x16x32_bf16 v[78:81], v[82:85], v[38:41], v[78:81]
	ds_read_b128 v[82:85], v155 offset:25792
	ds_read_b128 v[86:89], v155 offset:33856
	s_waitcnt lgkmcnt(1)
	v_mfma_f32_16x16x32_bf16 v[82:85], v[82:85], v[34:37], v[78:81]
	s_nop 3
	ds_read_b128 v[78:81], v155 offset:33792
	s_waitcnt lgkmcnt(0)
	v_mfma_f32_16x16x32_bf16 v[78:81], v[78:81], v[70:73], 0
	v_mfma_f32_16x16x32_bf16 v[78:81], v[86:89], v[62:65], v[78:81]
	ds_read_b128 v[86:89], v155 offset:33920
	s_waitcnt lgkmcnt(0)
	v_mfma_f32_16x16x32_bf16 v[78:81], v[86:89], v[54:57], v[78:81]
	ds_read_b128 v[86:89], v155 offset:33984
	s_waitcnt lgkmcnt(0)
	v_mfma_f32_16x16x32_bf16 v[78:81], v[86:89], v[50:53], v[78:81]
	ds_read_b128 v[86:89], v155 offset:34048
	s_waitcnt lgkmcnt(0)
	v_mfma_f32_16x16x32_bf16 v[78:81], v[86:89], v[46:49], v[78:81]
	ds_read_b128 v[86:89], v155 offset:34112
	s_waitcnt lgkmcnt(0)
	v_mfma_f32_16x16x32_bf16 v[78:81], v[86:89], v[42:45], v[78:81]
	ds_read_b128 v[86:89], v155 offset:34176
	s_waitcnt lgkmcnt(0)
	v_mfma_f32_16x16x32_bf16 v[78:81], v[86:89], v[38:41], v[78:81]
	ds_read_b128 v[86:89], v155 offset:34240
	ds_read_b128 v[90:93], v155 offset:42304
	s_waitcnt lgkmcnt(1)
	v_mfma_f32_16x16x32_bf16 v[78:81], v[86:89], v[34:37], v[78:81]
	ds_read_b128 v[86:89], v155 offset:42240
	s_waitcnt lgkmcnt(0)
; #define LAS __attribute__((address_space(3)))
; __device__ __forceinline__ void xattn_lds(const Ctx& C, const bf16* P, int cqoff, const bf16* MEMKV, const bf16* MEMVT, bf16* CAT, int ldc, int catoff, int u0, int ustride) {
;     ...
;             for (int kt = 0; kt < 8; ++kt) {
; #pragma unroll
;                 for (int ks = 0; ks < 8; ++ks) { const bf16x8v kf = *(const LAS bf16x8v*)(Ls + (16 * kt + c) * KP + (32 * ks + 8 * g) * 2);
;                     s[8 * half + kt] = __builtin_amdgcn_mfma_f32_16x16x32_bf16(kf, qf[ks], s[8 * half + kt], 0, 0, 0); }
;                 asm volatile("" ::: "memory"); }
;         }
;         float m = -1e30f;
; #pragma unroll
;         for (int kt = 0; kt < 16; ++kt) m = fmaxf(fmaxf(m, fmaxf(s[kt][0], s[kt][1])), fmaxf(s[kt][2], s[kt][3]));
;         m = fmaxf(m, __shfl_xor(m, 16)); m = fmaxf(m, __shfl_xor(m, 32));
	v_mfma_f32_16x16x32_bf16 v[86:89], v[86:89], v[70:73], 0
	v_mfma_f32_16x16x32_bf16 v[86:89], v[90:93], v[62:65], v[86:89]
	ds_read_b128 v[90:93], v155 offset:42368
	s_waitcnt lgkmcnt(0)
	v_mfma_f32_16x16x32_bf16 v[86:89], v[90:93], v[54:57], v[86:89]
	ds_read_b128 v[90:93], v155 offset:42432
	s_waitcnt lgkmcnt(0)
	v_mfma_f32_16x16x32_bf16 v[86:89], v[90:93], v[50:53], v[86:89]
	ds_read_b128 v[90:93], v155 offset:42496
	s_waitcnt lgkmcnt(0)
	v_mfma_f32_16x16x32_bf16 v[86:89], v[90:93], v[46:49], v[86:89]
	ds_read_b128 v[90:93], v155 offset:42560
	s_waitcnt lgkmcnt(0)
	v_mfma_f32_16x16x32_bf16 v[86:89], v[90:93], v[42:45], v[86:89]
	ds_read_b128 v[90:93], v155 offset:42624
	s_waitcnt lgkmcnt(0)
	v_mfma_f32_16x16x32_bf16 v[86:89], v[90:93], v[38:41], v[86:89]
	ds_read_b128 v[90:93], v155 offset:42688
	ds_read_b128 v[174:177], v155 offset:50752
	s_waitcnt lgkmcnt(1)
	v_mfma_f32_16x16x32_bf16 v[90:93], v[90:93], v[34:37], v[86:89]
	s_nop 3
	ds_read_b128 v[86:89], v155 offset:50688
	s_waitcnt lgkmcnt(0)
	v_mfma_f32_16x16x32_bf16 v[86:89], v[86:89], v[70:73], 0
	v_mfma_f32_16x16x32_bf16 v[86:89], v[174:177], v[62:65], v[86:89]
	ds_read_b128 v[174:177], v155 offset:50816
	s_waitcnt lgkmcnt(0)
	v_mfma_f32_16x16x32_bf16 v[86:89], v[174:177], v[54:57], v[86:89]
	ds_read_b128 v[174:177], v155 offset:50880
	s_waitcnt lgkmcnt(0)
	v_mfma_f32_16x16x32_bf16 v[86:89], v[174:177], v[50:53], v[86:89]
	ds_read_b128 v[174:177], v155 offset:50944
	s_waitcnt lgkmcnt(0)
	v_mfma_f32_16x16x32_bf16 v[86:89], v[174:177], v[46:49], v[86:89]
	ds_read_b128 v[174:177], v155 offset:51008
	s_waitcnt lgkmcnt(0)
	v_mfma_f32_16x16x32_bf16 v[86:89], v[174:177], v[42:45], v[86:89]
	ds_read_b128 v[174:177], v155 offset:51072
	s_waitcnt lgkmcnt(0)
	v_mfma_f32_16x16x32_bf16 v[86:89], v[174:177], v[38:41], v[86:89]
	ds_read_b128 v[174:177], v155 offset:51136
	s_waitcnt lgkmcnt(0)
	v_mfma_f32_16x16x32_bf16 v[86:89], v[174:177], v[34:37], v[86:89]
	ds_read_b128 v[174:177], v155 offset:59136
	s_waitcnt lgkmcnt(0)
	v_mfma_f32_16x16x32_bf16 v[70:73], v[174:177], v[70:73], 0
	ds_read_b128 v[174:177], v155 offset:59200
	s_waitcnt lgkmcnt(0)
	v_mfma_f32_16x16x32_bf16 v[62:65], v[174:177], v[62:65], v[70:73]
	s_nop 4
	ds_read_b128 v[70:73], v155 offset:59264
	s_waitcnt lgkmcnt(0)
	v_mfma_f32_16x16x32_bf16 v[54:57], v[70:73], v[54:57], v[62:65]
	s_nop 2
	ds_read_b128 v[62:65], v155 offset:59328
	s_waitcnt lgkmcnt(0)
	v_mfma_f32_16x16x32_bf16 v[50:53], v[62:65], v[50:53], v[54:57]
	s_nop 2
	ds_read_b128 v[54:57], v155 offset:59392
	s_waitcnt lgkmcnt(0)
	v_mfma_f32_16x16x32_bf16 v[46:49], v[54:57], v[46:49], v[50:53]
	s_nop 2
	ds_read_b128 v[50:53], v155 offset:59456
	s_waitcnt lgkmcnt(0)
	v_mfma_f32_16x16x32_bf16 v[42:45], v[50:53], v[42:45], v[46:49]
	s_nop 2
	ds_read_b128 v[46:49], v155 offset:59520
	s_waitcnt lgkmcnt(0)
	v_mfma_f32_16x16x32_bf16 v[38:41], v[46:49], v[38:41], v[42:45]
	s_nop 2
	ds_read_b128 v[42:45], v155 offset:59584
	s_waitcnt lgkmcnt(0)
	v_mfma_f32_16x16x32_bf16 v[34:37], v[42:45], v[34:37], v[38:41]
	s_nop 2
	v_max_f32_e32 v38, v3, v3
	v_max_f32_e32 v39, v2, v2
	v_max_f32_e32 v38, v39, v38
	v_max_f32_e32 v39, v5, v5
	v_max_f32_e32 v40, v4, v4
	v_max_f32_e32 v39, v40, v39
	v_max3_f32 v38, v38, s14, v39
	v_max_f32_e32 v39, v11, v11
	v_max_f32_e32 v40, v10, v10
	v_max_f32_e32 v39, v40, v39
	v_max_f32_e32 v40, v13, v13
	v_max_f32_e32 v41, v12, v12
	v_max_f32_e32 v40, v41, v40
	v_max3_f32 v38, v38, v39, v40
	v_max_f32_e32 v39, v7, v7
	v_max_f32_e32 v40, v6, v6
	v_max_f32_e32 v39, v40, v39
	v_max_f32_e32 v40, v9, v9
	v_max_f32_e32 v41, v8, v8
	v_max_f32_e32 v40, v41, v40
	v_max3_f32 v38, v38, v39, v40
	v_max_f32_e32 v39, v19, v19
	v_max_f32_e32 v40, v18, v18
	v_max_f32_e32 v39, v40, v39
	v_max_f32_e32 v40, v21, v21
	v_max_f32_e32 v41, v20, v20
	v_max_f32_e32 v40, v41, v40
	v_max3_f32 v38, v38, v39, v40
	v_max_f32_e32 v39, v15, v15
	v_max_f32_e32 v40, v14, v14
	v_max_f32_e32 v39, v40, v39
	v_max_f32_e32 v40, v17, v17
	v_max_f32_e32 v41, v16, v16
	v_max_f32_e32 v40, v41, v40
	v_max3_f32 v38, v38, v39, v40
	v_max_f32_e32 v39, v27, v27
	v_max_f32_e32 v40, v26, v26
	v_max_f32_e32 v39, v40, v39
	v_max_f32_e32 v40, v29, v29
	v_max_f32_e32 v41, v28, v28
	v_max_f32_e32 v40, v41, v40
	v_max3_f32 v38, v38, v39, v40
	v_max_f32_e32 v39, v23, v23
	v_max_f32_e32 v40, v22, v22
	v_max_f32_e32 v39, v40, v39
	v_max_f32_e32 v40, v25, v25
	v_max_f32_e32 v41, v24, v24
	v_max_f32_e32 v40, v41, v40
	v_max3_f32 v38, v38, v39, v40
	v_max_f32_e32 v39, v31, v31
	v_max_f32_e32 v40, v30, v30
	v_max_f32_e32 v39, v40, v39
	v_max_f32_e32 v40, v33, v33
	v_max_f32_e32 v41, v32, v32
	v_max_f32_e32 v40, v41, v40
	v_max3_f32 v38, v38, v39, v40
	v_max_f32_e32 v39, v59, v59
	v_max_f32_e32 v40, v58, v58
	v_max_f32_e32 v39, v40, v39
	v_max_f32_e32 v40, v61, v61
	v_max_f32_e32 v41, v60, v60
	v_max_f32_e32 v40, v41, v40
	v_max3_f32 v38, v38, v39, v40
	v_max_f32_e32 v39, v75, v75
	v_max_f32_e32 v40, v74, v74
	v_max_f32_e32 v39, v40, v39
	v_max_f32_e32 v40, v77, v77
	v_max_f32_e32 v41, v76, v76
	v_max_f32_e32 v40, v41, v40
	v_max3_f32 v38, v38, v39, v40
	v_max_f32_e32 v39, v67, v67
	v_max_f32_e32 v40, v66, v66
	v_max_f32_e32 v39, v40, v39
	v_max_f32_e32 v40, v69, v69
	v_max_f32_e32 v41, v68, v68
	v_max_f32_e32 v40, v41, v40
	v_max3_f32 v38, v38, v39, v40
	v_max_f32_e32 v39, v83, v83
	v_max_f32_e32 v40, v82, v82
	v_max_f32_e32 v39, v40, v39
	v_max_f32_e32 v40, v85, v85
	v_max_f32_e32 v41, v84, v84
	v_max_f32_e32 v40, v41, v40
	v_max3_f32 v38, v38, v39, v40
	v_max_f32_e32 v39, v79, v79
	v_max_f32_e32 v40, v78, v78
	v_max_f32_e32 v39, v40, v39
	v_max_f32_e32 v40, v81, v81
	v_max_f32_e32 v41, v80, v80
	v_max_f32_e32 v40, v41, v40
	v_max3_f32 v38, v38, v39, v40
	v_max_f32_e32 v39, v91, v91
	v_max_f32_e32 v40, v90, v90
	v_max_f32_e32 v39, v40, v39
	v_max_f32_e32 v40, v93, v93
	v_max_f32_e32 v41, v92, v92
	v_max_f32_e32 v40, v41, v40
	v_max3_f32 v38, v38, v39, v40
	v_max_f32_e32 v39, v87, v87
	v_max_f32_e32 v40, v86, v86
	v_max_f32_e32 v39, v40, v39
	v_max_f32_e32 v40, v89, v89
	v_max_f32_e32 v41, v88, v88
	v_max_f32_e32 v40, v41, v40
	v_max3_f32 v38, v38, v39, v40
	v_max_f32_e32 v39, v35, v35
	v_max_f32_e32 v40, v34, v34
	v_max_f32_e32 v39, v40, v39
	v_max_f32_e32 v40, v37, v37
	v_max_f32_e32 v41, v36, v36
	v_max_f32_e32 v40, v41, v40
	v_max3_f32 v38, v38, v39, v40
	v_cndmask_b32_e32 v39, v156, v166, vcc
	v_lshlrev_b32_e32 v39, 2, v39
	ds_bpermute_b32 v40, v39, v38
	v_cmp_lt_i32_e32 vcc, v168, v167
	s_waitcnt lgkmcnt(0)
; __device__ __forceinline__ unsigned pk2(float lo, float hi) { return f2bf(lo) | (f2bf(hi) << 16); }
; __device__ __forceinline__ void xattn_lds(const Ctx& C, const bf16* P, int cqoff, const bf16* MEMKV, const bf16* MEMVT, bf16* CAT, int ldc, int catoff, int u0, int ustride) {
;     ...
;         m = fmaxf(m, __shfl_xor(m, 16)); m = fmaxf(m, __shfl_xor(m, 32));
;         float l = 0.f; const float sc = 0.0625f * 1.4426950408889634f;
;         bf16x8v pf[8];
; #pragma unroll
;         for (int kk = 0; kk < 8; ++kk) { float p[8];
; #pragma unroll
;             for (int r = 0; r < 4; ++r) { p[r] = __builtin_amdgcn_exp2f((s[2 * kk][r] - m) * sc); p[4 + r] = __builtin_amdgcn_exp2f((s[2 * kk + 1][r] - m) * sc); }
; #pragma unroll
;             for (int r = 0; r < 8; ++r) l += p[r];
;             v4u pw; pw.x = pk2(p[0], p[1]); pw.y = pk2(p[2], p[3]); pw.z = pk2(p[4], p[5]); pw.w = pk2(p[6], p[7]);
;             pf[kk] = __builtin_bit_cast(bf16x8v, pw); }
	v_max_f32_e32 v40, v40, v40
	v_max_f32_e32 v38, v38, v40
	v_cndmask_b32_e32 v40, v156, v168, vcc
	v_lshlrev_b32_e32 v40, 2, v40
	ds_bpermute_b32 v41, v40, v38
	s_waitcnt lgkmcnt(0)
	v_max_f32_e32 v41, v41, v41
	v_max_f32_e32 v38, v38, v41
	v_sub_f32_e32 v2, v2, v38
	v_mul_f32_e32 v2, 0x3db8aa3b, v2
	v_sub_f32_e32 v3, v3, v38
	v_exp_f32_e32 v2, v2
	v_mul_f32_e32 v3, 0x3db8aa3b, v3
	v_sub_f32_e32 v4, v4, v38
	v_exp_f32_e32 v3, v3
	v_mul_f32_e32 v4, 0x3db8aa3b, v4
	v_sub_f32_e32 v5, v5, v38
	v_sub_f32_e32 v10, v10, v38
	v_exp_f32_e32 v4, v4
	v_mul_f32_e32 v5, 0x3db8aa3b, v5
	v_mul_f32_e32 v10, 0x3db8aa3b, v10
	v_sub_f32_e32 v11, v11, v38
	v_exp_f32_e32 v5, v5
	v_exp_f32_e32 v10, v10
	v_mul_f32_e32 v11, 0x3db8aa3b, v11
	v_sub_f32_e32 v12, v12, v38
	v_sub_f32_e32 v13, v13, v38
	v_add_f32_e32 v41, 0, v2
	v_exp_f32_e32 v11, v11
	v_mul_f32_e32 v12, 0x3db8aa3b, v12
	v_mul_f32_e32 v13, 0x3db8aa3b, v13
	v_add_f32_e32 v41, v3, v41
	v_exp_f32_e32 v12, v12
	v_exp_f32_e32 v13, v13
	v_add_f32_e32 v41, v4, v41
	v_add_f32_e32 v41, v5, v41
	v_add_f32_e32 v41, v10, v41
	v_add_f32_e32 v41, v11, v41
	v_add_f32_e32 v41, v12, v41
	v_bfe_u32 v42, v13, 16, 1
	v_add_f32_e32 v41, v13, v41
	v_bfe_u32 v43, v11, 16, 1
	v_add3_u32 v13, v13, v42, s15
	v_bfe_u32 v42, v2, 16, 1
	v_bfe_u32 v45, v3, 16, 1
	v_add3_u32 v11, v11, v43, s15
	v_bfe_u32 v43, v4, 16, 1
	v_add3_u32 v2, v2, v42, s15
	v_bfe_u32 v44, v5, 16, 1
	v_add3_u32 v3, v3, v45, s15
	v_add3_u32 v4, v4, v43, s15
	v_lshrrev_b32_e32 v2, 16, v2
	v_add3_u32 v5, v5, v44, s15
	v_lshrrev_b32_e32 v4, 16, v4
	v_and_or_b32 v50, v3, s16, v2
	v_sub_f32_e32 v2, v6, v38
	v_and_or_b32 v51, v5, s16, v4
	v_mul_f32_e32 v2, 0x3db8aa3b, v2
	v_sub_f32_e32 v4, v7, v38
	v_exp_f32_e32 v2, v2
	v_mul_f32_e32 v4, 0x3db8aa3b, v4
	v_sub_f32_e32 v6, v8, v38
	v_bfe_u32 v44, v10, 16, 1
	v_exp_f32_e32 v4, v4
	v_mul_f32_e32 v6, 0x3db8aa3b, v6
	v_sub_f32_e32 v8, v9, v38
	v_add3_u32 v10, v10, v44, s15
	v_sub_f32_e32 v3, v18, v38
	v_exp_f32_e32 v6, v6
	v_mul_f32_e32 v8, 0x3db8aa3b, v8
	v_lshrrev_b32_e32 v10, 16, v10
	v_mul_f32_e32 v3, 0x3db8aa3b, v3
	v_sub_f32_e32 v5, v19, v38
	v_exp_f32_e32 v8, v8
	v_and_or_b32 v52, v11, s16, v10
	v_exp_f32_e32 v3, v3
	v_mul_f32_e32 v5, 0x3db8aa3b, v5
	v_sub_f32_e32 v7, v20, v38
	v_sub_f32_e32 v9, v21, v38
	v_add_f32_e32 v10, v2, v41
	v_exp_f32_e32 v5, v5
	v_mul_f32_e32 v7, 0x3db8aa3b, v7
	v_mul_f32_e32 v9, 0x3db8aa3b, v9
	v_add_f32_e32 v10, v4, v10
	v_exp_f32_e32 v7, v7
	v_exp_f32_e32 v9, v9
	v_add_f32_e32 v10, v6, v10
	v_add_f32_e32 v10, v8, v10
	v_add_f32_e32 v10, v3, v10
	v_bfe_u32 v45, v12, 16, 1
	v_add_f32_e32 v10, v5, v10
	v_add3_u32 v12, v12, v45, s15
	v_add_f32_e32 v10, v7, v10
	v_bfe_u32 v11, v9, 16, 1
	v_lshrrev_b32_e32 v12, 16, v12
	v_add_f32_e32 v10, v9, v10
	v_add3_u32 v9, v9, v11, s15
	v_bfe_u32 v11, v2, 16, 1
	v_and_or_b32 v53, v13, s16, v12
	v_bfe_u32 v12, v5, 16, 1
	v_bfe_u32 v18, v4, 16, 1
	v_add3_u32 v2, v2, v11, s15
	v_add3_u32 v4, v4, v18, s15
	v_add3_u32 v5, v5, v12, s15
	v_bfe_u32 v12, v6, 16, 1
	v_lshrrev_b32_e32 v2, 16, v2
	v_bfe_u32 v13, v8, 16, 1
	v_add3_u32 v6, v6, v12, s15
	v_and_or_b32 v54, v4, s16, v2
	v_sub_f32_e32 v2, v14, v38
	v_add3_u32 v8, v8, v13, s15
	v_bfe_u32 v13, v3, 16, 1
	v_lshrrev_b32_e32 v6, 16, v6
	v_mul_f32_e32 v2, 0x3db8aa3b, v2
	v_sub_f32_e32 v4, v15, v38
	v_add3_u32 v3, v3, v13, s15
	v_and_or_b32 v55, v8, s16, v6
	v_exp_f32_e32 v2, v2
	v_mul_f32_e32 v4, 0x3db8aa3b, v4
	v_sub_f32_e32 v6, v16, v38
	v_bfe_u32 v18, v7, 16, 1
	v_lshrrev_b32_e32 v3, 16, v3
	v_exp_f32_e32 v4, v4
	v_mul_f32_e32 v6, 0x3db8aa3b, v6
	v_sub_f32_e32 v8, v17, v38
	v_add3_u32 v7, v7, v18, s15
	v_and_or_b32 v56, v5, s16, v3
	v_sub_f32_e32 v3, v26, v38
	v_exp_f32_e32 v6, v6
	v_mul_f32_e32 v8, 0x3db8aa3b, v8
	v_lshrrev_b32_e32 v7, 16, v7
	v_mul_f32_e32 v3, 0x3db8aa3b, v3
	v_sub_f32_e32 v5, v27, v38
	v_exp_f32_e32 v8, v8
	v_and_or_b32 v57, v9, s16, v7
	v_exp_f32_e32 v3, v3
	v_mul_f32_e32 v5, 0x3db8aa3b, v5
	v_sub_f32_e32 v7, v28, v38
	v_sub_f32_e32 v9, v29, v38
	v_add_f32_e32 v10, v2, v10
	v_exp_f32_e32 v5, v5
	v_mul_f32_e32 v7, 0x3db8aa3b, v7
	v_mul_f32_e32 v9, 0x3db8aa3b, v9
	v_add_f32_e32 v10, v4, v10
	v_exp_f32_e32 v7, v7
	v_exp_f32_e32 v9, v9
	v_add_f32_e32 v10, v6, v10
	v_add_f32_e32 v10, v8, v10
	v_add_f32_e32 v10, v3, v10
	v_add_f32_e32 v10, v5, v10
	v_add_f32_e32 v10, v7, v10
	v_bfe_u32 v11, v9, 16, 1
	v_add_f32_e32 v10, v9, v10
	v_add3_u32 v9, v9, v11, s15
	v_bfe_u32 v11, v2, 16, 1
	v_bfe_u32 v12, v5, 16, 1
	v_bfe_u32 v14, v4, 16, 1
	v_add3_u32 v2, v2, v11, s15
	v_add3_u32 v4, v4, v14, s15
	v_add3_u32 v5, v5, v12, s15
	v_bfe_u32 v12, v6, 16, 1
	v_lshrrev_b32_e32 v2, 16, v2
	v_bfe_u32 v13, v8, 16, 1
	v_add3_u32 v6, v6, v12, s15
	v_and_or_b32 v42, v4, s16, v2
	v_sub_f32_e32 v2, v22, v38
	v_add3_u32 v8, v8, v13, s15
	v_bfe_u32 v13, v3, 16, 1
	v_lshrrev_b32_e32 v6, 16, v6
	v_mul_f32_e32 v2, 0x3db8aa3b, v2
	v_sub_f32_e32 v4, v23, v38
	v_add3_u32 v3, v3, v13, s15
	v_and_or_b32 v43, v8, s16, v6
	v_exp_f32_e32 v2, v2
	v_mul_f32_e32 v4, 0x3db8aa3b, v4
	v_sub_f32_e32 v6, v24, v38
	v_bfe_u32 v14, v7, 16, 1
	v_lshrrev_b32_e32 v3, 16, v3
	v_exp_f32_e32 v4, v4
	v_mul_f32_e32 v6, 0x3db8aa3b, v6
	v_sub_f32_e32 v8, v25, v38
	v_add3_u32 v7, v7, v14, s15
	v_and_or_b32 v44, v5, s16, v3
	v_sub_f32_e32 v3, v30, v38
	v_exp_f32_e32 v6, v6
	v_mul_f32_e32 v8, 0x3db8aa3b, v8
	v_lshrrev_b32_e32 v7, 16, v7
	v_mul_f32_e32 v3, 0x3db8aa3b, v3
	v_sub_f32_e32 v5, v31, v38
	v_exp_f32_e32 v8, v8
	v_and_or_b32 v45, v9, s16, v7
	v_exp_f32_e32 v3, v3
	v_mul_f32_e32 v5, 0x3db8aa3b, v5
	v_sub_f32_e32 v7, v32, v38
	v_sub_f32_e32 v9, v33, v38
	v_add_f32_e32 v10, v2, v10
	v_exp_f32_e32 v5, v5
	v_mul_f32_e32 v7, 0x3db8aa3b, v7
; __device__ __forceinline__ unsigned pk2(float lo, float hi) { return f2bf(lo) | (f2bf(hi) << 16); }
; __device__ __forceinline__ void xattn_lds(const Ctx& C, const bf16* P, int cqoff, const bf16* MEMKV, const bf16* MEMVT, bf16* CAT, int ldc, int catoff, int u0, int ustride) {
;     ...
; #pragma unroll
;         for (int kk = 0; kk < 8; ++kk) { float p[8];
; #pragma unroll
;             for (int r = 0; r < 4; ++r) { p[r] = __builtin_amdgcn_exp2f((s[2 * kk][r] - m) * sc); p[4 + r] = __builtin_amdgcn_exp2f((s[2 * kk + 1][r] - m) * sc); }
; #pragma unroll
;             for (int r = 0; r < 8; ++r) l += p[r];
;             v4u pw; pw.x = pk2(p[0], p[1]); pw.y = pk2(p[2], p[3]); pw.z = pk2(p[4], p[5]); pw.w = pk2(p[6], p[7]);
;             pf[kk] = __builtin_bit_cast(bf16x8v, pw); }
	v_mul_f32_e32 v9, 0x3db8aa3b, v9
	v_add_f32_e32 v10, v4, v10
	v_exp_f32_e32 v7, v7
	v_exp_f32_e32 v9, v9
	v_add_f32_e32 v10, v6, v10
	v_add_f32_e32 v10, v8, v10
	v_add_f32_e32 v10, v3, v10
	v_add_f32_e32 v10, v5, v10
	v_add_f32_e32 v10, v7, v10
	v_bfe_u32 v11, v9, 16, 1
	v_add_f32_e32 v10, v9, v10
	v_add3_u32 v9, v9, v11, s15
	v_bfe_u32 v11, v2, 16, 1
	v_bfe_u32 v12, v5, 16, 1
	v_bfe_u32 v14, v4, 16, 1
	v_add3_u32 v2, v2, v11, s15
	v_add3_u32 v4, v4, v14, s15
	v_add3_u32 v5, v5, v12, s15
	v_bfe_u32 v12, v6, 16, 1
	v_lshrrev_b32_e32 v2, 16, v2
	v_bfe_u32 v13, v8, 16, 1
	v_add3_u32 v6, v6, v12, s15
	v_and_or_b32 v46, v4, s16, v2
	v_sub_f32_e32 v2, v58, v38
	v_add3_u32 v8, v8, v13, s15
	v_bfe_u32 v13, v3, 16, 1
	v_bfe_u32 v14, v7, 16, 1
	v_lshrrev_b32_e32 v6, 16, v6
	v_mul_f32_e32 v2, 0x3db8aa3b, v2
	v_sub_f32_e32 v4, v59, v38
	v_add3_u32 v7, v7, v14, s15
	v_add3_u32 v3, v3, v13, s15
	v_and_or_b32 v47, v8, s16, v6
	v_exp_f32_e32 v2, v2
	v_mul_f32_e32 v4, 0x3db8aa3b, v4
	v_sub_f32_e32 v6, v60, v38
	v_lshrrev_b32_e32 v3, 16, v3
	v_lshrrev_b32_e32 v7, 16, v7
	v_exp_f32_e32 v4, v4
	v_mul_f32_e32 v6, 0x3db8aa3b, v6
	v_sub_f32_e32 v8, v61, v38
	v_and_or_b32 v49, v9, s16, v7
	v_and_or_b32 v48, v5, s16, v3
	v_sub_f32_e32 v3, v74, v38
	v_sub_f32_e32 v5, v75, v38
	v_exp_f32_e32 v6, v6
	v_mul_f32_e32 v8, 0x3db8aa3b, v8
	v_sub_f32_e32 v9, v77, v38
	v_mul_f32_e32 v3, 0x3db8aa3b, v3
	v_mul_f32_e32 v5, 0x3db8aa3b, v5
	v_exp_f32_e32 v8, v8
	v_mul_f32_e32 v9, 0x3db8aa3b, v9
	v_exp_f32_e32 v3, v3
	v_exp_f32_e32 v5, v5
	v_exp_f32_e32 v9, v9
	v_add_f32_e32 v10, v2, v10
	v_add_f32_e32 v10, v4, v10
	v_sub_f32_e32 v7, v76, v38
	v_add_f32_e32 v10, v6, v10
	v_mul_f32_e32 v7, 0x3db8aa3b, v7
	v_add_f32_e32 v10, v8, v10
	v_exp_f32_e32 v7, v7
	v_add_f32_e32 v10, v3, v10
	v_bfe_u32 v11, v9, 16, 1
	v_bfe_u32 v12, v5, 16, 1
	v_bfe_u32 v14, v4, 16, 1
	v_add_f32_e32 v10, v5, v10
	v_add3_u32 v14, v4, v14, s15
	v_add3_u32 v4, v5, v12, s15
	v_add3_u32 v5, v9, v11, s15
	v_bfe_u32 v11, v6, 16, 1
	v_bfe_u32 v12, v3, 16, 1
	v_bfe_u32 v13, v8, 16, 1
	v_add3_u32 v3, v3, v12, s15
	v_add3_u32 v6, v6, v11, s15
	v_add3_u32 v8, v8, v13, s15
	v_lshrrev_b32_e32 v6, 16, v6
	v_lshrrev_b32_e32 v3, 16, v3
	v_add_f32_e32 v10, v7, v10
	v_and_or_b32 v4, v4, s16, v3
	v_and_or_b32 v3, v8, s16, v6
	v_sub_f32_e32 v6, v66, v38
	v_add_f32_e32 v10, v9, v10
	v_bfe_u32 v9, v2, 16, 1
	v_bfe_u32 v13, v7, 16, 1
	v_mul_f32_e32 v6, 0x3db8aa3b, v6
	v_sub_f32_e32 v8, v67, v38
	v_add3_u32 v7, v7, v13, s15
	v_add3_u32 v2, v2, v9, s15
	v_exp_f32_e32 v6, v6
	v_mul_f32_e32 v8, 0x3db8aa3b, v8
	v_sub_f32_e32 v11, v68, v38
	v_lshrrev_b32_e32 v2, 16, v2
	v_lshrrev_b32_e32 v7, 16, v7
	v_exp_f32_e32 v8, v8
	v_mul_f32_e32 v11, 0x3db8aa3b, v11
	v_sub_f32_e32 v13, v69, v38
	v_and_or_b32 v5, v5, s16, v7
	v_and_or_b32 v2, v14, s16, v2
	v_sub_f32_e32 v7, v82, v38
	v_sub_f32_e32 v9, v83, v38
	v_exp_f32_e32 v11, v11
	v_mul_f32_e32 v13, 0x3db8aa3b, v13
	v_sub_f32_e32 v14, v85, v38
	v_mul_f32_e32 v7, 0x3db8aa3b, v7
	v_mul_f32_e32 v9, 0x3db8aa3b, v9
	v_exp_f32_e32 v13, v13
	v_mul_f32_e32 v14, 0x3db8aa3b, v14
	v_exp_f32_e32 v7, v7
	v_exp_f32_e32 v9, v9
	v_exp_f32_e32 v14, v14
	v_add_f32_e32 v10, v6, v10
	v_add_f32_e32 v10, v8, v10
	v_add_f32_e32 v10, v11, v10
	v_sub_f32_e32 v12, v84, v38
	v_add_f32_e32 v10, v13, v10
	v_mul_f32_e32 v12, 0x3db8aa3b, v12
	v_add_f32_e32 v10, v7, v10
	v_bfe_u32 v15, v14, 16, 1
	v_bfe_u32 v16, v9, 16, 1
	v_bfe_u32 v18, v8, 16, 1
	v_exp_f32_e32 v12, v12
	v_add_f32_e32 v10, v9, v10
	v_add3_u32 v18, v8, v18, s15
	v_add3_u32 v8, v9, v16, s15
	v_add3_u32 v9, v14, v15, s15
	v_bfe_u32 v15, v11, 16, 1
	v_bfe_u32 v16, v7, 16, 1
	v_bfe_u32 v17, v13, 16, 1
	v_add3_u32 v7, v7, v16, s15
	v_add3_u32 v11, v11, v15, s15
	v_add3_u32 v13, v13, v17, s15
	v_lshrrev_b32_e32 v11, 16, v11
	v_lshrrev_b32_e32 v7, 16, v7
	v_and_or_b32 v8, v8, s16, v7
	v_and_or_b32 v7, v13, s16, v11
	v_sub_f32_e32 v11, v78, v38
	v_bfe_u32 v17, v12, 16, 1
	v_mul_f32_e32 v11, 0x3db8aa3b, v11
	v_sub_f32_e32 v13, v79, v38
	v_add_f32_e32 v10, v12, v10
	v_add3_u32 v12, v12, v17, s15
	v_exp_f32_e32 v11, v11
	v_mul_f32_e32 v13, 0x3db8aa3b, v13
	v_sub_f32_e32 v15, v80, v38
	v_add_f32_e32 v10, v14, v10
	v_bfe_u32 v14, v6, 16, 1
	v_lshrrev_b32_e32 v12, 16, v12
	v_exp_f32_e32 v13, v13
	v_mul_f32_e32 v15, 0x3db8aa3b, v15
	v_sub_f32_e32 v17, v81, v38
	v_add3_u32 v6, v6, v14, s15
	v_and_or_b32 v9, v9, s16, v12
	v_sub_f32_e32 v12, v90, v38
	v_sub_f32_e32 v14, v91, v38
	v_exp_f32_e32 v15, v15
	v_mul_f32_e32 v17, 0x3db8aa3b, v17
	v_mul_f32_e32 v12, 0x3db8aa3b, v12
	v_mul_f32_e32 v14, 0x3db8aa3b, v14
	v_exp_f32_e32 v17, v17
	v_lshrrev_b32_e32 v6, 16, v6
	v_exp_f32_e32 v12, v12
	v_exp_f32_e32 v14, v14
	v_sub_f32_e32 v16, v92, v38
	v_add_f32_e32 v10, v11, v10
	v_and_or_b32 v6, v18, s16, v6
	v_mul_f32_e32 v16, 0x3db8aa3b, v16
	v_sub_f32_e32 v18, v93, v38
	v_add_f32_e32 v10, v13, v10
	v_exp_f32_e32 v16, v16
	v_mul_f32_e32 v18, 0x3db8aa3b, v18
	v_add_f32_e32 v10, v15, v10
	v_exp_f32_e32 v18, v18
	v_add_f32_e32 v10, v17, v10
	v_add_f32_e32 v10, v12, v10
	v_bfe_u32 v20, v14, 16, 1
	v_add_f32_e32 v10, v14, v10
	v_add3_u32 v14, v14, v20, s15
	v_bfe_u32 v20, v12, 16, 1
	v_add_f32_e32 v10, v16, v10
	v_bfe_u32 v21, v17, 16, 1
	v_bfe_u32 v22, v13, 16, 1
	v_add3_u32 v12, v12, v20, s15
	v_add_f32_e32 v19, v18, v10
	v_bfe_u32 v10, v18, 16, 1
	v_add3_u32 v22, v13, v22, s15
	v_add3_u32 v17, v17, v21, s15
	v_bfe_u32 v13, v11, 16, 1
	v_bfe_u32 v21, v16, 16, 1
	v_lshrrev_b32_e32 v12, 16, v12
	v_add3_u32 v10, v18, v10, s15
	v_bfe_u32 v18, v15, 16, 1
	v_add3_u32 v16, v16, v21, s15
	v_add3_u32 v11, v11, v13, s15
	v_and_or_b32 v12, v14, s16, v12
	v_sub_f32_e32 v14, v86, v38
; #define LAS __attribute__((address_space(3)))
; __device__ __forceinline__ unsigned pk2(float lo, float hi) { return f2bf(lo) | (f2bf(hi) << 16); }
; __device__ __forceinline__ void xattn_lds(const Ctx& C, const bf16* P, int cqoff, const bf16* MEMKV, const bf16* MEMVT, bf16* CAT, int ldc, int catoff, int u0, int ustride) {
;     ...
;         for (int kk = 0; kk < 8; ++kk) { float p[8];
; #pragma unroll
;             for (int r = 0; r < 4; ++r) { p[r] = __builtin_amdgcn_exp2f((s[2 * kk][r] - m) * sc); p[4 + r] = __builtin_amdgcn_exp2f((s[2 * kk + 1][r] - m) * sc); }
; #pragma unroll
;             for (int r = 0; r < 8; ++r) l += p[r];
;             v4u pw; pw.x = pk2(p[0], p[1]); pw.y = pk2(p[2], p[3]); pw.z = pk2(p[4], p[5]); pw.w = pk2(p[6], p[7]);
;             pf[kk] = __builtin_bit_cast(bf16x8v, pw); }
;         l += __shfl_xor(l, 16); l += __shfl_xor(l, 32);
;         const float inv = 1.f / l;
;     ...
;         for (int half = 0; half < 2; ++half) {
;             v4u stg[8];
; #pragma unroll
;             for (int it = 0; it < 8; ++it) { const int idx = it * 512 + tid, key = idx >> 5, d8 = idx & 31;
;                 stg[it] = *(const v4u*)(MEMKV + (size_t)(b * 256 + half * 128 + key) * 2048 + 1024 + xh * 256 + d8 * 8); }
;             __syncthreads();
; #pragma unroll
;             for (int it = 0; it < 8; ++it) { const int idx = it * 512 + tid, key = idx >> 5, d8 = idx & 31;
; #pragma unroll
;                 for (int e = 0; e < 8; ++e) { const unsigned wv = stg[it][e >> 1]; *(LAS unsigned short*)(Ls + (8 * d8 + e) * VP + key * 2) = (unsigned short)((e & 1) ? (wv >> 16) : (wv & 0xffffu)); } }
;             __syncthreads();
	v_add3_u32 v15, v15, v18, s15
	v_lshrrev_b32_e32 v18, 16, v11
	v_lshrrev_b32_e32 v13, 16, v16
	v_mul_f32_e32 v14, 0x3db8aa3b, v14
	v_sub_f32_e32 v16, v87, v38
	v_and_or_b32 v13, v10, s16, v13
	v_and_or_b32 v10, v22, s16, v18
	v_exp_f32_e32 v14, v14
	v_mul_f32_e32 v16, 0x3db8aa3b, v16
	v_sub_f32_e32 v18, v88, v38
	v_lshrrev_b32_e32 v11, 16, v15
	v_exp_f32_e32 v16, v16
	v_mul_f32_e32 v18, 0x3db8aa3b, v18
	v_sub_f32_e32 v21, v89, v38
	v_and_or_b32 v11, v17, s16, v11
	v_sub_f32_e32 v15, v34, v38
	v_sub_f32_e32 v17, v35, v38
	v_exp_f32_e32 v18, v18
	v_mul_f32_e32 v21, 0x3db8aa3b, v21
	v_sub_f32_e32 v22, v37, v38
	v_mul_f32_e32 v15, 0x3db8aa3b, v15
	v_mul_f32_e32 v17, 0x3db8aa3b, v17
	v_sub_f32_e32 v20, v36, v38
	v_exp_f32_e32 v21, v21
	v_mul_f32_e32 v22, 0x3db8aa3b, v22
	v_exp_f32_e32 v15, v15
	v_exp_f32_e32 v17, v17
	v_mul_f32_e32 v20, 0x3db8aa3b, v20
	v_exp_f32_e32 v22, v22
	v_add_f32_e32 v19, v14, v19
	v_exp_f32_e32 v20, v20
	v_add_f32_e32 v19, v16, v19
	v_add_f32_e32 v19, v18, v19
	v_add_f32_e32 v19, v21, v19
	v_add_f32_e32 v19, v15, v19
	v_bfe_u32 v23, v22, 16, 1
	v_bfe_u32 v24, v17, 16, 1
	v_bfe_u32 v25, v21, 16, 1
	v_bfe_u32 v26, v16, 16, 1
	v_add_f32_e32 v19, v17, v19
	v_add3_u32 v26, v16, v26, s15
	v_add3_u32 v21, v21, v25, s15
	v_add3_u32 v16, v17, v24, s15
	v_add3_u32 v17, v22, v23, s15
	v_bfe_u32 v23, v18, 16, 1
	v_bfe_u32 v24, v15, 16, 1
	v_bfe_u32 v25, v20, 16, 1
	v_add_f32_e32 v19, v20, v19
	v_add3_u32 v20, v20, v25, s15
	v_add3_u32 v15, v15, v24, s15
	v_add3_u32 v18, v18, v23, s15
	v_lshrrev_b32_e32 v18, 16, v18
	v_lshrrev_b32_e32 v15, 16, v15
	v_lshrrev_b32_e32 v20, 16, v20
	v_add_f32_e32 v19, v22, v19
	v_and_or_b32 v17, v17, s16, v20
	v_and_or_b32 v16, v16, s16, v15
	v_and_or_b32 v15, v21, s16, v18
	v_and_b32_e32 v230, 0x7f, v0
	v_lshrrev_b32_e32 v231, 5, v0
	v_sub_u32_e32 v230, v230, v231
	v_lshlrev_b32_e32 v230, 12, v230
	v_lshrrev_b32_e32 v234, 7, v0
	v_lshl_add_u32 v230, v234, 4, v230
	v_ashrrev_i32_e32 v231, 31, v230
	v_lshl_add_u64 v[232:233], s[2:3], 0, v[122:123]
	v_lshl_add_u64 v[232:233], v[232:233], 0, s[6:7]
	v_lshl_add_u64 v[232:233], v[232:233], 0, v[230:231]
	v_and_b32_e32 v235, 0x7f, v0
	v_mul_u32_u24_e32 v236, 0x880, v234
	v_lshl_add_u32 v236, v235, 1, v236
	v_lshl_add_u64 v[20:21], s[2:3], 0, v[124:125]
	ds_bpermute_b32 v18, v39, v19
	v_lshl_add_u64 v[20:21], v[20:21], 0, s[6:7]
	v_lshl_add_u64 v[30:31], v[20:21], 0, v[100:101]
	v_lshl_add_u64 v[20:21], s[2:3], 0, v[126:127]
	v_lshl_add_u64 v[20:21], v[20:21], 0, s[6:7]
	v_lshl_add_u64 v[32:33], v[20:21], 0, v[100:101]
	v_lshl_add_u64 v[20:21], s[2:3], 0, v[128:129]
	v_lshl_add_u64 v[20:21], v[20:21], 0, s[6:7]
	s_waitcnt lgkmcnt(0)
	v_add_f32_e32 v18, v19, v18
	v_lshl_add_u64 v[34:35], v[20:21], 0, v[100:101]
	v_lshl_add_u64 v[20:21], s[2:3], 0, v[130:131]
	ds_bpermute_b32 v19, v40, v18
	v_lshl_add_u64 v[20:21], v[20:21], 0, s[6:7]
	v_lshl_add_u64 v[36:37], v[20:21], 0, v[100:101]
	v_lshl_add_u64 v[20:21], s[2:3], 0, v[132:133]
	v_lshl_add_u64 v[20:21], v[20:21], 0, s[6:7]
	v_lshl_add_u64 v[38:39], v[20:21], 0, v[100:101]
	v_lshl_add_u64 v[20:21], s[2:3], 0, v[134:135]
	v_lshl_add_u64 v[20:21], v[20:21], 0, s[6:7]
	v_bfe_u32 v22, v14, 16, 1
	s_waitcnt lgkmcnt(0)
	v_add_f32_e32 v174, v18, v19
	v_lshl_add_u64 v[18:19], s[2:3], 0, v[122:123]
	v_lshl_add_u64 v[58:59], v[20:21], 0, v[100:101]
	v_lshl_add_u64 v[20:21], s[2:3], 0, v[136:137]
	v_add3_u32 v14, v14, v22, s15
	v_lshl_add_u64 v[18:19], v[18:19], 0, s[6:7]
	v_lshl_add_u64 v[20:21], v[20:21], 0, s[6:7]
	v_lshrrev_b32_e32 v14, 16, v14
	v_lshl_add_u64 v[18:19], v[18:19], 0, v[100:101]
	v_lshl_add_u64 v[62:63], v[20:21], 0, v[100:101]
	v_and_or_b32 v14, v26, s16, v14
	global_load_dwordx4 v[18:21], v[232:233], off offset:2048
	s_nop 0
	global_load_dwordx4 v[22:25], v[232:233], off offset:2112
	global_load_dwordx4 v[26:29], v[232:233], off offset:2176
	s_nop 0
	global_load_dwordx4 v[30:33], v[232:233], off offset:2240
	s_nop 0
	global_load_dwordx4 v[34:37], v[232:233], off offset:2304
	s_nop 0
	global_load_dwordx4 v[38:41], v[232:233], off offset:2368
	s_nop 0
	global_load_dwordx4 v[58:61], v[232:233], off offset:2432
	s_nop 0
	global_load_dwordx4 v[62:65], v[232:233], off offset:2496
	s_barrier
	s_waitcnt vmcnt(7)
	ds_write_b16 v236, v18 offset:0
	ds_write_b16_d16_hi v236, v18 offset:272
	ds_write_b16 v236, v19 offset:544
	ds_write_b16_d16_hi v236, v19 offset:816
	ds_write_b16 v236, v20 offset:1088
	ds_write_b16_d16_hi v236, v20 offset:1360
	ds_write_b16 v236, v21 offset:1632
	ds_write_b16_d16_hi v236, v21 offset:1904
	s_waitcnt vmcnt(6)
	ds_write_b16 v236, v22 offset:8704
	ds_write_b16_d16_hi v236, v22 offset:8976
	ds_write_b16 v236, v23 offset:9248
	ds_write_b16_d16_hi v236, v23 offset:9520
	ds_write_b16 v236, v24 offset:9792
	ds_write_b16_d16_hi v236, v24 offset:10064
	ds_write_b16 v236, v25 offset:10336
	ds_write_b16_d16_hi v236, v25 offset:10608
	s_waitcnt vmcnt(5)
	ds_write_b16 v236, v26 offset:17408
	ds_write_b16_d16_hi v236, v26 offset:17680
	ds_write_b16 v236, v27 offset:17952
	ds_write_b16_d16_hi v236, v27 offset:18224
	ds_write_b16 v236, v28 offset:18496
	ds_write_b16_d16_hi v236, v28 offset:18768
	ds_write_b16 v236, v29 offset:19040
	ds_write_b16_d16_hi v236, v29 offset:19312
	s_waitcnt vmcnt(4)
	ds_write_b16 v236, v30 offset:26112
	ds_write_b16_d16_hi v236, v30 offset:26384
	ds_write_b16 v236, v31 offset:26656
	ds_write_b16_d16_hi v236, v31 offset:26928
	ds_write_b16 v236, v32 offset:27200
	ds_write_b16_d16_hi v236, v32 offset:27472
	ds_write_b16 v236, v33 offset:27744
	ds_write_b16_d16_hi v236, v33 offset:28016
	s_waitcnt vmcnt(3)
	ds_write_b16 v236, v34 offset:34816
	ds_write_b16_d16_hi v236, v34 offset:35088
	ds_write_b16 v236, v35 offset:35360
	ds_write_b16_d16_hi v236, v35 offset:35632
	ds_write_b16 v236, v36 offset:35904
	ds_write_b16_d16_hi v236, v36 offset:36176
	ds_write_b16 v236, v37 offset:36448
	ds_write_b16_d16_hi v236, v37 offset:36720
	s_waitcnt vmcnt(2)
	ds_write_b16 v236, v38 offset:43520
	ds_write_b16_d16_hi v236, v38 offset:43792
	ds_write_b16 v236, v39 offset:44064
	ds_write_b16_d16_hi v236, v39 offset:44336
	ds_write_b16 v236, v40 offset:44608
	ds_write_b16_d16_hi v236, v40 offset:44880
	ds_write_b16 v236, v41 offset:45152
	ds_write_b16_d16_hi v236, v41 offset:45424
	s_waitcnt vmcnt(1)
	ds_write_b16 v236, v58 offset:52224
	ds_write_b16_d16_hi v236, v58 offset:52496
	ds_write_b16 v236, v59 offset:52768
	ds_write_b16_d16_hi v236, v59 offset:53040
	ds_write_b16 v236, v60 offset:53312
	ds_write_b16_d16_hi v236, v60 offset:53584
	ds_write_b16 v236, v61 offset:53856
	ds_write_b16_d16_hi v236, v61 offset:54128
	s_waitcnt vmcnt(0)
	ds_write_b16 v236, v62 offset:60928
	ds_write_b16_d16_hi v236, v62 offset:61200
	ds_write_b16 v236, v63 offset:61472
	ds_write_b16_d16_hi v236, v63 offset:61744
	ds_write_b16 v236, v64 offset:62016
	ds_write_b16_d16_hi v236, v64 offset:62288
	ds_write_b16 v236, v65 offset:62560
	ds_write_b16_d16_hi v236, v65 offset:62832
	s_waitcnt lgkmcnt(0)
	s_barrier
; #define LAS __attribute__((address_space(3)))
; __device__ __forceinline__ void xattn_lds(const Ctx& C, const bf16* P, int cqoff, const bf16* MEMKV, const bf16* MEMVT, bf16* CAT, int ldc, int catoff, int u0, int ustride) {
;     ...
; #pragma unroll
;             for (int dt = 0; dt < 16; ++dt) {
; #pragma unroll
;                 for (int kk = 0; kk < 4; ++kk) { const LAS unsigned char* vp = Ls + (16 * dt + c) * VP + (32 * kk + 4 * g) * 2;
;                     const v2u lo = *(const LAS v2u*)vp, hi = *(const LAS v2u*)(vp + 32);
;                     v4u vw; vw.x = lo.x; vw.y = lo.y; vw.z = hi.x; vw.w = hi.y;
;                     o[dt] = __builtin_amdgcn_mfma_f32_16x16x32_bf16(__builtin_bit_cast(bf16x8v, vw), pf[4 * half + kk], o[dt], 0, 0, 0); }
;                 if (dt & 1) asm volatile("" ::: "memory"); }
	ds_read2_b64 v[18:21], v146 offset1:4
	ds_read2_b64 v[22:25], v146 offset0:8 offset1:12
	s_waitcnt lgkmcnt(1)
	v_mfma_f32_16x16x32_bf16 v[18:21], v[18:21], v[50:53], 0
	v_add_u32_e32 v122, 0x5000, v165
	v_add_u32_e32 v123, 0x6000, v165
	v_add_u32_e32 v124, 0x8800, v146
	s_waitcnt lgkmcnt(0)
	v_mfma_f32_16x16x32_bf16 v[18:21], v[22:25], v[54:57], v[18:21]
	ds_read2_b64 v[22:25], v146 offset0:16 offset1:20
	v_add_u32_e32 v125, 0x9800, v146
	v_add_u32_e32 v131, 0xa800, v146
	s_waitcnt lgkmcnt(0)
	v_mfma_f32_16x16x32_bf16 v[18:21], v[22:25], v[42:45], v[18:21]
	ds_read2_b64 v[22:25], v146 offset0:24 offset1:28
	v_add_u32_e32 v130, 0xb800, v146
	v_add_u32_e32 v129, 0xc800, v146
	s_waitcnt lgkmcnt(0)
	v_mfma_f32_16x16x32_bf16 v[38:41], v[22:25], v[46:49], v[18:21]
	s_nop 2
	ds_read2_b64 v[18:21], v165 offset1:4
	ds_read2_b64 v[22:25], v165 offset0:8 offset1:12
	v_add_u32_e32 v128, 0xd800, v146
	s_waitcnt lgkmcnt(1)
	v_mfma_f32_16x16x32_bf16 v[18:21], v[18:21], v[50:53], 0
	v_add_u32_e32 v127, 0xe800, v146
	v_add_u32_e32 v126, 0xf800, v146
	s_waitcnt lgkmcnt(0)
	v_mfma_f32_16x16x32_bf16 v[18:21], v[22:25], v[54:57], v[18:21]
	ds_read2_b64 v[22:25], v165 offset0:16 offset1:20
	s_waitcnt lgkmcnt(0)
	v_mfma_f32_16x16x32_bf16 v[18:21], v[22:25], v[42:45], v[18:21]
	ds_read2_b64 v[22:25], v165 offset0:24 offset1:28
	s_waitcnt lgkmcnt(0)
	v_mfma_f32_16x16x32_bf16 v[34:37], v[22:25], v[46:49], v[18:21]
	s_nop 4
	ds_read2_b64 v[18:21], v169 offset0:32 offset1:36
	ds_read2_b64 v[22:25], v169 offset0:40 offset1:44
	s_waitcnt lgkmcnt(1)
	v_mfma_f32_16x16x32_bf16 v[18:21], v[18:21], v[50:53], 0
	s_waitcnt lgkmcnt(0)
	v_mfma_f32_16x16x32_bf16 v[18:21], v[22:25], v[54:57], v[18:21]
	ds_read2_b64 v[22:25], v169 offset0:48 offset1:52
	s_waitcnt lgkmcnt(0)
	v_mfma_f32_16x16x32_bf16 v[18:21], v[22:25], v[42:45], v[18:21]
	ds_read2_b64 v[22:25], v169 offset0:56 offset1:60
	s_waitcnt lgkmcnt(0)
	v_mfma_f32_16x16x32_bf16 v[30:33], v[22:25], v[46:49], v[18:21]
	s_nop 4
	ds_read2_b64 v[18:21], v170 offset0:64 offset1:68
	ds_read2_b64 v[22:25], v170 offset0:72 offset1:76
	s_waitcnt lgkmcnt(1)
	v_mfma_f32_16x16x32_bf16 v[18:21], v[18:21], v[50:53], 0
	s_waitcnt lgkmcnt(0)
	v_mfma_f32_16x16x32_bf16 v[18:21], v[22:25], v[54:57], v[18:21]
	ds_read2_b64 v[22:25], v170 offset0:80 offset1:84
	s_waitcnt lgkmcnt(0)
	v_mfma_f32_16x16x32_bf16 v[18:21], v[22:25], v[42:45], v[18:21]
	ds_read2_b64 v[22:25], v170 offset0:88 offset1:92
	ds_read2_b64 v[58:61], v172 offset0:136 offset1:140
	s_waitcnt lgkmcnt(1)
	v_mfma_f32_16x16x32_bf16 v[26:29], v[22:25], v[46:49], v[18:21]
	s_nop 3
	ds_read2_b64 v[18:21], v171 offset0:96 offset1:100
	ds_read2_b64 v[22:25], v171 offset0:104 offset1:108
	s_waitcnt lgkmcnt(1)
	v_mfma_f32_16x16x32_bf16 v[18:21], v[18:21], v[50:53], 0
	s_waitcnt lgkmcnt(0)
	v_mfma_f32_16x16x32_bf16 v[18:21], v[22:25], v[54:57], v[18:21]
	ds_read2_b64 v[22:25], v171 offset0:112 offset1:116
	s_waitcnt lgkmcnt(0)
	v_mfma_f32_16x16x32_bf16 v[18:21], v[22:25], v[42:45], v[18:21]
	ds_read2_b64 v[22:25], v171 offset0:120 offset1:124
	s_waitcnt lgkmcnt(0)
	v_mfma_f32_16x16x32_bf16 v[22:25], v[22:25], v[46:49], v[18:21]
	s_nop 4
	ds_read2_b64 v[18:21], v172 offset0:128 offset1:132
	s_waitcnt lgkmcnt(0)
	v_mfma_f32_16x16x32_bf16 v[18:21], v[18:21], v[50:53], 0
	v_mfma_f32_16x16x32_bf16 v[18:21], v[58:61], v[54:57], v[18:21]
	ds_read2_b64 v[58:61], v172 offset0:144 offset1:148
	s_waitcnt lgkmcnt(0)
	v_mfma_f32_16x16x32_bf16 v[18:21], v[58:61], v[42:45], v[18:21]
	ds_read2_b64 v[58:61], v172 offset0:152 offset1:156
	ds_read2_b64 v[62:65], v122 offset0:168 offset1:172
	s_waitcnt lgkmcnt(1)
	v_mfma_f32_16x16x32_bf16 v[18:21], v[58:61], v[46:49], v[18:21]
	ds_read2_b64 v[58:61], v122 offset0:160 offset1:164
	ds_read2_b64 v[66:69], v123 offset0:200 offset1:204
	s_waitcnt lgkmcnt(1)
	v_mfma_f32_16x16x32_bf16 v[58:61], v[58:61], v[50:53], 0
	v_mfma_f32_16x16x32_bf16 v[58:61], v[62:65], v[54:57], v[58:61]
	ds_read2_b64 v[62:65], v122 offset0:176 offset1:180
	s_waitcnt lgkmcnt(0)
	v_mfma_f32_16x16x32_bf16 v[58:61], v[62:65], v[42:45], v[58:61]
	ds_read2_b64 v[62:65], v122 offset0:184 offset1:188
	s_waitcnt lgkmcnt(0)
	v_mfma_f32_16x16x32_bf16 v[58:61], v[62:65], v[46:49], v[58:61]
	ds_read2_b64 v[62:65], v123 offset0:192 offset1:196
	s_waitcnt lgkmcnt(0)
	v_mfma_f32_16x16x32_bf16 v[62:65], v[62:65], v[50:53], 0
	v_mfma_f32_16x16x32_bf16 v[62:65], v[66:69], v[54:57], v[62:65]
	ds_read2_b64 v[66:69], v123 offset0:208 offset1:212
	s_waitcnt lgkmcnt(0)
	v_mfma_f32_16x16x32_bf16 v[62:65], v[66:69], v[42:45], v[62:65]
	ds_read2_b64 v[66:69], v123 offset0:216 offset1:220
	ds_read2_b64 v[70:73], v124 offset0:8 offset1:12
	s_waitcnt lgkmcnt(1)
	v_mfma_f32_16x16x32_bf16 v[62:65], v[66:69], v[46:49], v[62:65]
	ds_read2_b64 v[66:69], v124 offset1:4
	ds_read2_b64 v[74:77], v125 offset0:40 offset1:44
	s_waitcnt lgkmcnt(1)
	v_mfma_f32_16x16x32_bf16 v[66:69], v[66:69], v[50:53], 0
	v_mfma_f32_16x16x32_bf16 v[66:69], v[70:73], v[54:57], v[66:69]
	ds_read2_b64 v[70:73], v124 offset0:16 offset1:20
	s_waitcnt lgkmcnt(0)
	v_mfma_f32_16x16x32_bf16 v[66:69], v[70:73], v[42:45], v[66:69]
	ds_read2_b64 v[70:73], v124 offset0:24 offset1:28
	s_waitcnt lgkmcnt(0)
	v_mfma_f32_16x16x32_bf16 v[66:69], v[70:73], v[46:49], v[66:69]
	ds_read2_b64 v[70:73], v125 offset0:32 offset1:36
	s_waitcnt lgkmcnt(0)
	v_mfma_f32_16x16x32_bf16 v[70:73], v[70:73], v[50:53], 0
	v_mfma_f32_16x16x32_bf16 v[70:73], v[74:77], v[54:57], v[70:73]
	ds_read2_b64 v[74:77], v125 offset0:48 offset1:52
	s_waitcnt lgkmcnt(0)
	v_mfma_f32_16x16x32_bf16 v[70:73], v[74:77], v[42:45], v[70:73]
	ds_read2_b64 v[74:77], v125 offset0:56 offset1:60
	s_waitcnt lgkmcnt(0)
; #define LAS __attribute__((address_space(3)))
; __device__ __forceinline__ void xattn_lds(const Ctx& C, const bf16* P, int cqoff, const bf16* MEMKV, const bf16* MEMVT, bf16* CAT, int ldc, int catoff, int u0, int ustride) {
;     ...
;             v4u stg[8];
; #pragma unroll
;             for (int it = 0; it < 8; ++it) { const int idx = it * 512 + tid, key = idx >> 5, d8 = idx & 31;
;                 stg[it] = *(const v4u*)(MEMKV + (size_t)(b * 256 + half * 128 + key) * 2048 + 1024 + xh * 256 + d8 * 8); }
;     ...
; #pragma unroll
;             for (int dt = 0; dt < 16; ++dt) {
; #pragma unroll
;                 for (int kk = 0; kk < 4; ++kk) { const LAS unsigned char* vp = Ls + (16 * dt + c) * VP + (32 * kk + 4 * g) * 2;
;                     const v2u lo = *(const LAS v2u*)vp, hi = *(const LAS v2u*)(vp + 32);
;                     v4u vw; vw.x = lo.x; vw.y = lo.y; vw.z = hi.x; vw.w = hi.y;
;                     o[dt] = __builtin_amdgcn_mfma_f32_16x16x32_bf16(__builtin_bit_cast(bf16x8v, vw), pf[4 * half + kk], o[dt], 0, 0, 0); }
;                 if (dt & 1) asm volatile("" ::: "memory"); }
	v_mfma_f32_16x16x32_bf16 v[90:93], v[74:77], v[46:49], v[70:73]
	s_nop 4
	ds_read2_b64 v[70:73], v131 offset0:64 offset1:68
	ds_read2_b64 v[74:77], v131 offset0:72 offset1:76
	s_waitcnt lgkmcnt(1)
	v_mfma_f32_16x16x32_bf16 v[70:73], v[70:73], v[50:53], 0
	s_waitcnt lgkmcnt(0)
	v_mfma_f32_16x16x32_bf16 v[70:73], v[74:77], v[54:57], v[70:73]
	ds_read2_b64 v[74:77], v131 offset0:80 offset1:84
	s_waitcnt lgkmcnt(0)
	v_mfma_f32_16x16x32_bf16 v[70:73], v[74:77], v[42:45], v[70:73]
	ds_read2_b64 v[74:77], v131 offset0:88 offset1:92
	s_waitcnt lgkmcnt(0)
	v_mfma_f32_16x16x32_bf16 v[78:81], v[74:77], v[46:49], v[70:73]
	s_nop 4
	ds_read2_b64 v[70:73], v130 offset0:96 offset1:100
	ds_read2_b64 v[74:77], v130 offset0:104 offset1:108
	s_waitcnt lgkmcnt(1)
	v_mfma_f32_16x16x32_bf16 v[70:73], v[70:73], v[50:53], 0
	s_waitcnt lgkmcnt(0)
	v_mfma_f32_16x16x32_bf16 v[70:73], v[74:77], v[54:57], v[70:73]
	ds_read2_b64 v[74:77], v130 offset0:112 offset1:116
	s_waitcnt lgkmcnt(0)
	v_mfma_f32_16x16x32_bf16 v[70:73], v[74:77], v[42:45], v[70:73]
	ds_read2_b64 v[74:77], v130 offset0:120 offset1:124
	ds_read2_b64 v[82:85], v128 offset0:168 offset1:172
	s_waitcnt lgkmcnt(1)
	v_mfma_f32_16x16x32_bf16 v[86:89], v[74:77], v[46:49], v[70:73]
	s_nop 3
	ds_read2_b64 v[70:73], v129 offset0:128 offset1:132
	ds_read2_b64 v[74:77], v129 offset0:136 offset1:140
	s_waitcnt lgkmcnt(1)
	v_mfma_f32_16x16x32_bf16 v[70:73], v[70:73], v[50:53], 0
	s_waitcnt lgkmcnt(0)
	v_mfma_f32_16x16x32_bf16 v[70:73], v[74:77], v[54:57], v[70:73]
	ds_read2_b64 v[74:77], v129 offset0:144 offset1:148
	s_waitcnt lgkmcnt(0)
	v_mfma_f32_16x16x32_bf16 v[70:73], v[74:77], v[42:45], v[70:73]
	ds_read2_b64 v[74:77], v129 offset0:152 offset1:156
	s_waitcnt lgkmcnt(0)
	v_mfma_f32_16x16x32_bf16 v[74:77], v[74:77], v[46:49], v[70:73]
	s_nop 4
	ds_read2_b64 v[70:73], v128 offset0:160 offset1:164
	s_waitcnt lgkmcnt(0)
	v_mfma_f32_16x16x32_bf16 v[70:73], v[70:73], v[50:53], 0
	v_mfma_f32_16x16x32_bf16 v[70:73], v[82:85], v[54:57], v[70:73]
	ds_read2_b64 v[82:85], v128 offset0:176 offset1:180
	s_waitcnt lgkmcnt(0)
	v_mfma_f32_16x16x32_bf16 v[70:73], v[82:85], v[42:45], v[70:73]
	ds_read2_b64 v[82:85], v128 offset0:184 offset1:188
	ds_read2_b64 v[132:135], v127 offset0:200 offset1:204
	s_waitcnt lgkmcnt(1)
	v_mfma_f32_16x16x32_bf16 v[82:85], v[82:85], v[46:49], v[70:73]
	s_nop 3
	ds_read2_b64 v[70:73], v127 offset0:192 offset1:196
	s_waitcnt lgkmcnt(0)
	v_mfma_f32_16x16x32_bf16 v[70:73], v[70:73], v[50:53], 0
	v_mfma_f32_16x16x32_bf16 v[70:73], v[132:135], v[54:57], v[70:73]
	ds_read2_b64 v[132:135], v127 offset0:208 offset1:212
	s_waitcnt lgkmcnt(0)
	v_mfma_f32_16x16x32_bf16 v[70:73], v[132:135], v[42:45], v[70:73]
	ds_read2_b64 v[132:135], v127 offset0:216 offset1:220
	s_waitcnt lgkmcnt(0)
	v_mfma_f32_16x16x32_bf16 v[70:73], v[132:135], v[46:49], v[70:73]
	ds_read2_b64 v[132:135], v126 offset0:224 offset1:228
	s_waitcnt lgkmcnt(0)
	v_mfma_f32_16x16x32_bf16 v[50:53], v[132:135], v[50:53], 0
	ds_read2_b64 v[132:135], v126 offset0:232 offset1:236
	s_waitcnt lgkmcnt(0)
	v_mfma_f32_16x16x32_bf16 v[50:53], v[132:135], v[54:57], v[50:53]
	ds_read2_b64 v[54:57], v126 offset0:240 offset1:244
	s_waitcnt lgkmcnt(0)
	v_mfma_f32_16x16x32_bf16 v[42:45], v[54:57], v[42:45], v[50:53]
	s_nop 4
	ds_read2_b64 v[50:53], v126 offset0:248 offset1:252
	s_waitcnt lgkmcnt(0)
	v_mfma_f32_16x16x32_bf16 v[42:45], v[50:53], v[46:49], v[42:45]
	v_and_b32_e32 v230, 0x7f, v0
	v_lshrrev_b32_e32 v231, 5, v0
	v_sub_u32_e32 v230, v230, v231
	v_lshlrev_b32_e32 v230, 12, v230
	v_lshrrev_b32_e32 v234, 7, v0
	v_lshl_add_u32 v230, v234, 4, v230
	v_ashrrev_i32_e32 v231, 31, v230
	v_lshl_add_u64 v[232:233], s[2:3], 0, v[106:107]
	v_lshl_add_u64 v[232:233], v[232:233], 0, s[6:7]
	v_lshl_add_u64 v[232:233], v[232:233], 0, v[230:231]
	v_and_b32_e32 v235, 0x7f, v0
	v_mul_u32_u24_e32 v236, 0x880, v234
	v_lshl_add_u32 v236, v235, 1, v236
	v_lshl_add_u64 v[48:49], s[2:3], 0, v[108:109]
	v_lshl_add_u64 v[48:49], v[48:49], 0, s[6:7]
	v_lshl_add_u64 v[50:51], v[48:49], 0, v[100:101]
	v_lshl_add_u64 v[48:49], s[2:3], 0, v[110:111]
	v_lshl_add_u64 v[48:49], v[48:49], 0, s[6:7]
	v_lshl_add_u64 v[54:55], v[48:49], 0, v[100:101]
	v_lshl_add_u64 v[48:49], s[2:3], 0, v[112:113]
	v_lshl_add_u64 v[48:49], v[48:49], 0, s[6:7]
	v_lshl_add_u64 v[46:47], s[2:3], 0, v[106:107]
	v_lshl_add_u64 v[106:107], v[48:49], 0, v[100:101]
	v_lshl_add_u64 v[48:49], s[2:3], 0, v[114:115]
	v_lshl_add_u64 v[48:49], v[48:49], 0, s[6:7]
	v_lshl_add_u64 v[110:111], v[48:49], 0, v[100:101]
	v_lshl_add_u64 v[48:49], s[2:3], 0, v[116:117]
	v_lshl_add_u64 v[48:49], v[48:49], 0, s[6:7]
	v_lshl_add_u64 v[114:115], v[48:49], 0, v[100:101]
	v_lshl_add_u64 v[48:49], s[2:3], 0, v[118:119]
	v_lshl_add_u64 v[48:49], v[48:49], 0, s[6:7]
	v_lshl_add_u64 v[118:119], v[48:49], 0, v[100:101]
	v_lshl_add_u64 v[48:49], s[2:3], 0, v[120:121]
	v_lshl_add_u64 v[46:47], v[46:47], 0, s[6:7]
	v_lshl_add_u64 v[48:49], v[48:49], 0, s[6:7]
	v_lshl_add_u64 v[46:47], v[46:47], 0, v[100:101]
	v_lshl_add_u64 v[132:133], v[48:49], 0, v[100:101]
	global_load_dwordx4 v[46:49], v[232:233], off offset:2048
	s_nop 0
	global_load_dwordx4 v[50:53], v[232:233], off offset:2112
	s_nop 0
	global_load_dwordx4 v[54:57], v[232:233], off offset:2176
	s_nop 0
	global_load_dwordx4 v[106:109], v[232:233], off offset:2240
	s_nop 0
	global_load_dwordx4 v[110:113], v[232:233], off offset:2304
	s_nop 0
	global_load_dwordx4 v[114:117], v[232:233], off offset:2368
	s_nop 0
	global_load_dwordx4 v[118:121], v[232:233], off offset:2432
	s_nop 0
	global_load_dwordx4 v[132:135], v[232:233], off offset:2496
	s_barrier
; #define LAS __attribute__((address_space(3)))
; __device__ __forceinline__ void xattn_lds(const Ctx& C, const bf16* P, int cqoff, const bf16* MEMKV, const bf16* MEMVT, bf16* CAT, int ldc, int catoff, int u0, int ustride) {
;     ...
;             __syncthreads();
; #pragma unroll
;             for (int it = 0; it < 8; ++it) { const int idx = it * 512 + tid, key = idx >> 5, d8 = idx & 31;
; #pragma unroll
;                 for (int e = 0; e < 8; ++e) { const unsigned wv = stg[it][e >> 1]; *(LAS unsigned short*)(Ls + (8 * d8 + e) * VP + key * 2) = (unsigned short)((e & 1) ? (wv >> 16) : (wv & 0xffffu)); } }
;             __syncthreads();
; #pragma unroll
;             for (int dt = 0; dt < 16; ++dt) {
; #pragma unroll
;                 for (int kk = 0; kk < 4; ++kk) { const LAS unsigned char* vp = Ls + (16 * dt + c) * VP + (32 * kk + 4 * g) * 2;
;                     const v2u lo = *(const LAS v2u*)vp, hi = *(const LAS v2u*)(vp + 32);
;                     v4u vw; vw.x = lo.x; vw.y = lo.y; vw.z = hi.x; vw.w = hi.y;
;                     o[dt] = __builtin_amdgcn_mfma_f32_16x16x32_bf16(__builtin_bit_cast(bf16x8v, vw), pf[4 * half + kk], o[dt], 0, 0, 0); }
;                 if (dt & 1) asm volatile("" ::: "memory"); }
	s_waitcnt vmcnt(7)
	ds_write_b16 v236, v46 offset:0
	ds_write_b16_d16_hi v236, v46 offset:272
	ds_write_b16 v236, v47 offset:544
	ds_write_b16_d16_hi v236, v47 offset:816
	ds_write_b16 v236, v48 offset:1088
	ds_write_b16_d16_hi v236, v48 offset:1360
	ds_write_b16 v236, v49 offset:1632
	ds_write_b16_d16_hi v236, v49 offset:1904
	s_waitcnt vmcnt(6)
	ds_write_b16 v236, v50 offset:8704
	ds_write_b16_d16_hi v236, v50 offset:8976
	ds_write_b16 v236, v51 offset:9248
	ds_write_b16_d16_hi v236, v51 offset:9520
	ds_write_b16 v236, v52 offset:9792
	ds_write_b16_d16_hi v236, v52 offset:10064
	ds_write_b16 v236, v53 offset:10336
	ds_write_b16_d16_hi v236, v53 offset:10608
	s_waitcnt vmcnt(5)
	ds_write_b16 v236, v54 offset:17408
	ds_write_b16_d16_hi v236, v54 offset:17680
	ds_write_b16 v236, v55 offset:17952
	ds_write_b16_d16_hi v236, v55 offset:18224
	ds_write_b16 v236, v56 offset:18496
	ds_write_b16_d16_hi v236, v56 offset:18768
	ds_write_b16 v236, v57 offset:19040
	ds_write_b16_d16_hi v236, v57 offset:19312
	s_waitcnt vmcnt(4)
	ds_write_b16 v236, v106 offset:26112
	ds_write_b16_d16_hi v236, v106 offset:26384
	ds_write_b16 v236, v107 offset:26656
	ds_write_b16_d16_hi v236, v107 offset:26928
	ds_write_b16 v236, v108 offset:27200
	ds_write_b16_d16_hi v236, v108 offset:27472
	ds_write_b16 v236, v109 offset:27744
	ds_write_b16_d16_hi v236, v109 offset:28016
	s_waitcnt vmcnt(3)
	ds_write_b16 v236, v110 offset:34816
	ds_write_b16_d16_hi v236, v110 offset:35088
	ds_write_b16 v236, v111 offset:35360
	ds_write_b16_d16_hi v236, v111 offset:35632
	ds_write_b16 v236, v112 offset:35904
	ds_write_b16_d16_hi v236, v112 offset:36176
	ds_write_b16 v236, v113 offset:36448
	ds_write_b16_d16_hi v236, v113 offset:36720
	s_waitcnt vmcnt(2)
	ds_write_b16 v236, v114 offset:43520
	ds_write_b16_d16_hi v236, v114 offset:43792
	ds_write_b16 v236, v115 offset:44064
	ds_write_b16_d16_hi v236, v115 offset:44336
	ds_write_b16 v236, v116 offset:44608
	ds_write_b16_d16_hi v236, v116 offset:44880
	ds_write_b16 v236, v117 offset:45152
	ds_write_b16_d16_hi v236, v117 offset:45424
	s_waitcnt vmcnt(1)
	ds_write_b16 v236, v118 offset:52224
	ds_write_b16_d16_hi v236, v118 offset:52496
	ds_write_b16 v236, v119 offset:52768
	ds_write_b16_d16_hi v236, v119 offset:53040
	ds_write_b16 v236, v120 offset:53312
	ds_write_b16_d16_hi v236, v120 offset:53584
	ds_write_b16 v236, v121 offset:53856
	ds_write_b16_d16_hi v236, v121 offset:54128
	s_waitcnt vmcnt(0)
	ds_write_b16 v236, v132 offset:60928
	ds_write_b16_d16_hi v236, v132 offset:61200
	ds_write_b16 v236, v133 offset:61472
	ds_write_b16_d16_hi v236, v133 offset:61744
	ds_write_b16 v236, v134 offset:62016
	ds_write_b16_d16_hi v236, v134 offset:62288
	ds_write_b16 v236, v135 offset:62560
	ds_write_b16_d16_hi v236, v135 offset:62832
	s_waitcnt lgkmcnt(0)
	s_barrier
	ds_read2_b64 v[46:49], v146 offset1:4
	s_waitcnt lgkmcnt(0)
	v_mfma_f32_16x16x32_bf16 v[38:41], v[46:49], v[2:5], v[38:41]
	ds_read2_b64 v[46:49], v146 offset0:8 offset1:12
	s_waitcnt lgkmcnt(0)
	v_mfma_f32_16x16x32_bf16 v[38:41], v[46:49], v[6:9], v[38:41]
	ds_read2_b64 v[46:49], v146 offset0:16 offset1:20
	s_waitcnt lgkmcnt(0)
	v_mfma_f32_16x16x32_bf16 v[38:41], v[46:49], v[10:13], v[38:41]
	ds_read2_b64 v[46:49], v146 offset0:24 offset1:28
	s_waitcnt lgkmcnt(0)
	v_mfma_f32_16x16x32_bf16 v[38:41], v[46:49], v[14:17], v[38:41]
	ds_read2_b64 v[46:49], v165 offset0:24 offset1:28
	ds_read2_b64 v[50:53], v165 offset0:16 offset1:20
	ds_read2_b64 v[54:57], v165 offset0:8 offset1:12
	ds_read2_b64 v[106:109], v165 offset1:4
	s_waitcnt lgkmcnt(0)
	v_mfma_f32_16x16x32_bf16 v[34:37], v[106:109], v[2:5], v[34:37]
	v_mfma_f32_16x16x32_bf16 v[34:37], v[54:57], v[6:9], v[34:37]
	v_mfma_f32_16x16x32_bf16 v[34:37], v[50:53], v[10:13], v[34:37]
	v_mfma_f32_16x16x32_bf16 v[34:37], v[46:49], v[14:17], v[34:37]
	ds_read2_b64 v[46:49], v169 offset0:32 offset1:36
	s_waitcnt lgkmcnt(0)
	v_mfma_f32_16x16x32_bf16 v[30:33], v[46:49], v[2:5], v[30:33]
	ds_read2_b64 v[46:49], v169 offset0:40 offset1:44
	s_waitcnt lgkmcnt(0)
	v_mfma_f32_16x16x32_bf16 v[30:33], v[46:49], v[6:9], v[30:33]
	ds_read2_b64 v[46:49], v169 offset0:48 offset1:52
	s_waitcnt lgkmcnt(0)
	v_mfma_f32_16x16x32_bf16 v[30:33], v[46:49], v[10:13], v[30:33]
	ds_read2_b64 v[46:49], v169 offset0:56 offset1:60
	s_waitcnt lgkmcnt(0)
	v_mfma_f32_16x16x32_bf16 v[30:33], v[46:49], v[14:17], v[30:33]
	ds_read2_b64 v[46:49], v170 offset0:88 offset1:92
	ds_read2_b64 v[50:53], v170 offset0:80 offset1:84
	ds_read2_b64 v[54:57], v170 offset0:72 offset1:76
	ds_read2_b64 v[106:109], v170 offset0:64 offset1:68
	s_waitcnt lgkmcnt(0)
	v_mfma_f32_16x16x32_bf16 v[26:29], v[106:109], v[2:5], v[26:29]
	v_mfma_f32_16x16x32_bf16 v[26:29], v[54:57], v[6:9], v[26:29]
	v_mfma_f32_16x16x32_bf16 v[26:29], v[50:53], v[10:13], v[26:29]
	v_mfma_f32_16x16x32_bf16 v[26:29], v[46:49], v[14:17], v[26:29]
	ds_read2_b64 v[46:49], v171 offset0:96 offset1:100
	s_waitcnt lgkmcnt(0)
	v_mfma_f32_16x16x32_bf16 v[22:25], v[46:49], v[2:5], v[22:25]
	ds_read2_b64 v[46:49], v171 offset0:104 offset1:108
	s_waitcnt lgkmcnt(0)
	v_mfma_f32_16x16x32_bf16 v[22:25], v[46:49], v[6:9], v[22:25]
	ds_read2_b64 v[46:49], v171 offset0:112 offset1:116
	s_waitcnt lgkmcnt(0)
	v_mfma_f32_16x16x32_bf16 v[22:25], v[46:49], v[10:13], v[22:25]
	ds_read2_b64 v[46:49], v171 offset0:120 offset1:124
	s_waitcnt lgkmcnt(0)
	v_mfma_f32_16x16x32_bf16 v[22:25], v[46:49], v[14:17], v[22:25]
	ds_read2_b64 v[46:49], v172 offset0:152 offset1:156
	ds_read2_b64 v[50:53], v172 offset0:144 offset1:148
	ds_read2_b64 v[54:57], v172 offset0:136 offset1:140
	ds_read2_b64 v[106:109], v172 offset0:128 offset1:132
	s_waitcnt lgkmcnt(0)
; #define LAS __attribute__((address_space(3)))
; __device__ __forceinline__ void xattn_lds(const Ctx& C, const bf16* P, int cqoff, const bf16* MEMKV, const bf16* MEMVT, bf16* CAT, int ldc, int catoff, int u0, int ustride) {
;     ...
; #pragma unroll
;             for (int dt = 0; dt < 16; ++dt) {
; #pragma unroll
;                 for (int kk = 0; kk < 4; ++kk) { const LAS unsigned char* vp = Ls + (16 * dt + c) * VP + (32 * kk + 4 * g) * 2;
;                     const v2u lo = *(const LAS v2u*)vp, hi = *(const LAS v2u*)(vp + 32);
;                     v4u vw; vw.x = lo.x; vw.y = lo.y; vw.z = hi.x; vw.w = hi.y;
;                     o[dt] = __builtin_amdgcn_mfma_f32_16x16x32_bf16(__builtin_bit_cast(bf16x8v, vw), pf[4 * half + kk], o[dt], 0, 0, 0); }
;                 if (dt & 1) asm volatile("" ::: "memory"); }
	v_mfma_f32_16x16x32_bf16 v[18:21], v[106:109], v[2:5], v[18:21]
	v_mfma_f32_16x16x32_bf16 v[18:21], v[54:57], v[6:9], v[18:21]
	v_mfma_f32_16x16x32_bf16 v[18:21], v[50:53], v[10:13], v[18:21]
	ds_read2_b64 v[50:53], v122 offset0:168 offset1:172
	v_mfma_f32_16x16x32_bf16 v[18:21], v[46:49], v[14:17], v[18:21]
	ds_read2_b64 v[46:49], v122 offset0:160 offset1:164
	s_waitcnt lgkmcnt(0)
	v_mfma_f32_16x16x32_bf16 v[46:49], v[46:49], v[2:5], v[58:61]
	v_mfma_f32_16x16x32_bf16 v[46:49], v[50:53], v[6:9], v[46:49]
	ds_read2_b64 v[50:53], v122 offset0:176 offset1:180
	s_waitcnt lgkmcnt(0)
	v_mfma_f32_16x16x32_bf16 v[46:49], v[50:53], v[10:13], v[46:49]
	ds_read2_b64 v[50:53], v122 offset0:184 offset1:188
	s_waitcnt lgkmcnt(0)
	v_mfma_f32_16x16x32_bf16 v[46:49], v[50:53], v[14:17], v[46:49]
	ds_read2_b64 v[50:53], v123 offset0:216 offset1:220
	ds_read2_b64 v[54:57], v123 offset0:208 offset1:212
	ds_read2_b64 v[58:61], v123 offset0:200 offset1:204
	ds_read2_b64 v[106:109], v123 offset0:192 offset1:196
	s_waitcnt lgkmcnt(0)
	v_mfma_f32_16x16x32_bf16 v[62:65], v[106:109], v[2:5], v[62:65]
	v_mfma_f32_16x16x32_bf16 v[58:61], v[58:61], v[6:9], v[62:65]
	v_mfma_f32_16x16x32_bf16 v[54:57], v[54:57], v[10:13], v[58:61]
	v_mfma_f32_16x16x32_bf16 v[50:53], v[50:53], v[14:17], v[54:57]
	s_nop 5
	ds_read2_b64 v[58:61], v124 offset0:8 offset1:12
	ds_read2_b64 v[54:57], v124 offset1:4
	s_waitcnt lgkmcnt(0)
	v_mfma_f32_16x16x32_bf16 v[54:57], v[54:57], v[2:5], v[66:69]
	v_mfma_f32_16x16x32_bf16 v[54:57], v[58:61], v[6:9], v[54:57]
	ds_read2_b64 v[58:61], v124 offset0:16 offset1:20
	s_waitcnt lgkmcnt(0)
	v_mfma_f32_16x16x32_bf16 v[54:57], v[58:61], v[10:13], v[54:57]
	ds_read2_b64 v[58:61], v124 offset0:24 offset1:28
	s_waitcnt lgkmcnt(0)
	v_mfma_f32_16x16x32_bf16 v[54:57], v[58:61], v[14:17], v[54:57]
	ds_read2_b64 v[58:61], v125 offset0:56 offset1:60
	ds_read2_b64 v[62:65], v125 offset0:48 offset1:52
	ds_read2_b64 v[66:69], v125 offset0:40 offset1:44
	ds_read2_b64 v[106:109], v125 offset0:32 offset1:36
	s_waitcnt lgkmcnt(0)
	v_mfma_f32_16x16x32_bf16 v[90:93], v[106:109], v[2:5], v[90:93]
	v_mfma_f32_16x16x32_bf16 v[66:69], v[66:69], v[6:9], v[90:93]
	v_mfma_f32_16x16x32_bf16 v[62:65], v[62:65], v[10:13], v[66:69]
	v_mfma_f32_16x16x32_bf16 v[58:61], v[58:61], v[14:17], v[62:65]
	s_nop 5
	ds_read2_b64 v[66:69], v131 offset0:72 offset1:76
	ds_read2_b64 v[62:65], v131 offset0:64 offset1:68
	s_waitcnt lgkmcnt(0)
	v_mfma_f32_16x16x32_bf16 v[62:65], v[62:65], v[2:5], v[78:81]
	v_mfma_f32_16x16x32_bf16 v[62:65], v[66:69], v[6:9], v[62:65]
	ds_read2_b64 v[66:69], v131 offset0:80 offset1:84
	s_waitcnt lgkmcnt(0)
	v_mfma_f32_16x16x32_bf16 v[62:65], v[66:69], v[10:13], v[62:65]
	ds_read2_b64 v[66:69], v131 offset0:88 offset1:92
	s_waitcnt lgkmcnt(0)
	v_mfma_f32_16x16x32_bf16 v[62:65], v[66:69], v[14:17], v[62:65]
	ds_read2_b64 v[66:69], v130 offset0:120 offset1:124
	ds_read2_b64 v[78:81], v130 offset0:112 offset1:116
	ds_read2_b64 v[90:93], v130 offset0:104 offset1:108
	ds_read2_b64 v[106:109], v130 offset0:96 offset1:100
	s_waitcnt lgkmcnt(0)
	v_mfma_f32_16x16x32_bf16 v[86:89], v[106:109], v[2:5], v[86:89]
	v_mfma_f32_16x16x32_bf16 v[86:89], v[90:93], v[6:9], v[86:89]
	v_mfma_f32_16x16x32_bf16 v[78:81], v[78:81], v[10:13], v[86:89]
	v_mfma_f32_16x16x32_bf16 v[66:69], v[66:69], v[14:17], v[78:81]
	s_nop 6
	ds_read2_b64 v[78:81], v129 offset0:128 offset1:132
	s_waitcnt lgkmcnt(0)
	v_mfma_f32_16x16x32_bf16 v[74:77], v[78:81], v[2:5], v[74:77]
	ds_read2_b64 v[78:81], v129 offset0:136 offset1:140
	s_waitcnt lgkmcnt(0)
	v_mfma_f32_16x16x32_bf16 v[74:77], v[78:81], v[6:9], v[74:77]
	ds_read2_b64 v[78:81], v129 offset0:144 offset1:148
	s_waitcnt lgkmcnt(0)
	v_mfma_f32_16x16x32_bf16 v[74:77], v[78:81], v[10:13], v[74:77]
	ds_read2_b64 v[78:81], v129 offset0:152 offset1:156
	s_waitcnt lgkmcnt(0)
	v_mfma_f32_16x16x32_bf16 v[74:77], v[78:81], v[14:17], v[74:77]
	ds_read2_b64 v[78:81], v128 offset0:184 offset1:188
	ds_read2_b64 v[86:89], v128 offset0:176 offset1:180
	ds_read2_b64 v[90:93], v128 offset0:168 offset1:172
	ds_read2_b64 v[106:109], v128 offset0:160 offset1:164
	s_waitcnt lgkmcnt(0)
	v_mfma_f32_16x16x32_bf16 v[82:85], v[106:109], v[2:5], v[82:85]
	v_mfma_f32_16x16x32_bf16 v[82:85], v[90:93], v[6:9], v[82:85]
	v_mfma_f32_16x16x32_bf16 v[82:85], v[86:89], v[10:13], v[82:85]
	v_mfma_f32_16x16x32_bf16 v[78:81], v[78:81], v[14:17], v[82:85]
	s_nop 6
	ds_read2_b64 v[82:85], v127 offset0:192 offset1:196
	s_waitcnt lgkmcnt(0)
	v_mfma_f32_16x16x32_bf16 v[70:73], v[82:85], v[2:5], v[70:73]
	ds_read2_b64 v[82:85], v127 offset0:200 offset1:204
	s_waitcnt lgkmcnt(0)
	v_mfma_f32_16x16x32_bf16 v[70:73], v[82:85], v[6:9], v[70:73]
	ds_read2_b64 v[82:85], v127 offset0:208 offset1:212
	s_waitcnt lgkmcnt(0)
	v_mfma_f32_16x16x32_bf16 v[70:73], v[82:85], v[10:13], v[70:73]
	ds_read2_b64 v[82:85], v127 offset0:216 offset1:220
	s_waitcnt lgkmcnt(0)
	v_mfma_f32_16x16x32_bf16 v[70:73], v[82:85], v[14:17], v[70:73]
	ds_read2_b64 v[82:85], v126 offset0:248 offset1:252
	ds_read2_b64 v[86:89], v126 offset0:240 offset1:244
	ds_read2_b64 v[90:93], v126 offset0:232 offset1:236
	ds_read2_b64 v[106:109], v126 offset0:224 offset1:228
	s_waitcnt lgkmcnt(0)
; __device__ __forceinline__ unsigned pk2(float lo, float hi) { return f2bf(lo) | (f2bf(hi) << 16); }
; __device__ __forceinline__ void xattn_lds(const Ctx& C, const bf16* P, int cqoff, const bf16* MEMKV, const bf16* MEMVT, bf16* CAT, int ldc, int catoff, int u0, int ustride) {
;     ...
;                     o[dt] = __builtin_amdgcn_mfma_f32_16x16x32_bf16(__builtin_bit_cast(bf16x8v, vw), pf[4 * half + kk], o[dt], 0, 0, 0); }
;                 if (dt & 1) asm volatile("" ::: "memory"); }
;         }
;         bf16* op = CAT + (size_t)qrow * ldc + catoff + xh * 256 + 4 * g;
; #pragma unroll
;         for (int dt = 0; dt < 16; ++dt) { v2u ow; ow.x = pk2(o[dt][0] * inv, o[dt][1] * inv); ow.y = pk2(o[dt][2] * inv, o[dt][3] * inv); *(v2u*)(op + dt * 16) = ow; }
	v_mfma_f32_16x16x32_bf16 v[2:5], v[106:109], v[2:5], v[42:45]
	v_mfma_f32_16x16x32_bf16 v[2:5], v[90:93], v[6:9], v[2:5]
	v_div_scale_f32 v6, s[0:1], v174, v174, 1.0
	v_rcp_f32_e32 v7, v6
	v_mfma_f32_16x16x32_bf16 v[2:5], v[86:89], v[10:13], v[2:5]
	v_mov_b32_e32 v11, v40
	v_mov_b32_e32 v40, v39
	v_fma_f32 v8, -v6, v7, 1.0
	v_fmac_f32_e32 v7, v8, v7
	v_div_scale_f32 v8, vcc, 1.0, v174, 1.0
	v_mul_f32_e32 v9, v8, v7
	v_fma_f32 v10, -v6, v9, v8
	v_fmac_f32_e32 v9, v10, v7
	v_fma_f32 v6, -v6, v9, v8
	v_div_fmas_f32 v6, v6, v7, v9
	v_div_fixup_f32 v8, v6, v174, 1.0
	v_mov_b32_e32 v10, v38
	v_pk_mul_f32 v[10:11], v[8:9], v[10:11] op_sel_hi:[0,1]
	v_mfma_f32_16x16x32_bf16 v[2:5], v[82:85], v[14:17], v[2:5]
	v_mul_f32_e64 v12, v8, v40
	v_mul_f32_e64 v13, v8, v41
	v_and_b32_sdwa v9, v11, v173 dst_sel:DWORD dst_unused:UNUSED_PAD src0_sel:WORD_1 src1_sel:DWORD
	v_and_b32_sdwa v14, v10, v173 dst_sel:DWORD dst_unused:UNUSED_PAD src0_sel:WORD_1 src1_sel:DWORD
	v_lshlrev_b64 v[6:7], 12, v[104:105]
	v_add3_u32 v10, v10, v14, s15
	v_add3_u32 v9, v11, v9, s15
	v_and_b32_sdwa v11, v13, v173 dst_sel:DWORD dst_unused:UNUSED_PAD src0_sel:WORD_1 src1_sel:DWORD
	v_and_b32_sdwa v14, v12, v173 dst_sel:DWORD dst_unused:UNUSED_PAD src0_sel:WORD_1 src1_sel:DWORD
	v_lshl_add_u64 v[6:7], s[4:5], 0, v[6:7]
	v_add3_u32 v11, v13, v11, s15
	v_add3_u32 v12, v12, v14, s15
	v_lshl_add_u64 v[6:7], v[6:7], 0, s[6:7]
	v_and_b32_e32 v11, 0xffff0000, v11
	v_and_b32_e32 v12, 0xffff0000, v12
	v_lshl_add_u64 v[6:7], v[6:7], 0, v[102:103]
	v_or_b32_sdwa v11, v11, v9 dst_sel:DWORD dst_unused:UNUSED_PAD src0_sel:DWORD src1_sel:WORD_1
	v_or_b32_sdwa v10, v12, v10 dst_sel:DWORD dst_unused:UNUSED_PAD src0_sel:DWORD src1_sel:WORD_1
	global_store_dwordx2 v[6:7], v[10:11], off
	v_mov_b32_e32 v10, v34
	v_mov_b32_e32 v11, v36
	v_pk_mul_f32 v[10:11], v[8:9], v[10:11] op_sel_hi:[0,1]
	v_mov_b32_e32 v36, v35
	v_pk_mul_f32 v[12:13], v[8:9], v[36:37] op_sel_hi:[0,1]
	v_and_b32_sdwa v9, v11, v173 dst_sel:DWORD dst_unused:UNUSED_PAD src0_sel:WORD_1 src1_sel:DWORD
	v_and_b32_sdwa v14, v10, v173 dst_sel:DWORD dst_unused:UNUSED_PAD src0_sel:WORD_1 src1_sel:DWORD
	v_add3_u32 v10, v10, v14, s15
	v_add3_u32 v9, v11, v9, s15
	v_and_b32_sdwa v11, v13, v173 dst_sel:DWORD dst_unused:UNUSED_PAD src0_sel:WORD_1 src1_sel:DWORD
	v_and_b32_sdwa v14, v12, v173 dst_sel:DWORD dst_unused:UNUSED_PAD src0_sel:WORD_1 src1_sel:DWORD
	v_add3_u32 v11, v13, v11, s15
	v_add3_u32 v12, v12, v14, s15
	v_and_b32_e32 v11, 0xffff0000, v11
	v_and_b32_e32 v12, 0xffff0000, v12
	v_or_b32_sdwa v11, v11, v9 dst_sel:DWORD dst_unused:UNUSED_PAD src0_sel:DWORD src1_sel:WORD_1
	v_or_b32_sdwa v10, v12, v10 dst_sel:DWORD dst_unused:UNUSED_PAD src0_sel:DWORD src1_sel:WORD_1
	global_store_dwordx2 v[6:7], v[10:11], off offset:32
	v_mov_b32_e32 v10, v30
	v_mov_b32_e32 v11, v32
	v_pk_mul_f32 v[10:11], v[8:9], v[10:11] op_sel_hi:[0,1]
	v_mov_b32_e32 v32, v31
	v_pk_mul_f32 v[12:13], v[8:9], v[32:33] op_sel_hi:[0,1]
	v_and_b32_sdwa v9, v11, v173 dst_sel:DWORD dst_unused:UNUSED_PAD src0_sel:WORD_1 src1_sel:DWORD
	v_and_b32_sdwa v14, v10, v173 dst_sel:DWORD dst_unused:UNUSED_PAD src0_sel:WORD_1 src1_sel:DWORD
	v_add3_u32 v10, v10, v14, s15
	v_add3_u32 v9, v11, v9, s15
	v_and_b32_sdwa v11, v13, v173 dst_sel:DWORD dst_unused:UNUSED_PAD src0_sel:WORD_1 src1_sel:DWORD
	v_and_b32_sdwa v14, v12, v173 dst_sel:DWORD dst_unused:UNUSED_PAD src0_sel:WORD_1 src1_sel:DWORD
	v_add3_u32 v11, v13, v11, s15
	v_add3_u32 v12, v12, v14, s15
	v_and_b32_e32 v11, 0xffff0000, v11
	v_and_b32_e32 v12, 0xffff0000, v12
	v_or_b32_sdwa v11, v11, v9 dst_sel:DWORD dst_unused:UNUSED_PAD src0_sel:DWORD src1_sel:WORD_1
	v_or_b32_sdwa v10, v12, v10 dst_sel:DWORD dst_unused:UNUSED_PAD src0_sel:DWORD src1_sel:WORD_1
	global_store_dwordx2 v[6:7], v[10:11], off offset:64
	v_mov_b32_e32 v10, v26
	v_mov_b32_e32 v11, v28
	v_pk_mul_f32 v[10:11], v[8:9], v[10:11] op_sel_hi:[0,1]
	v_mov_b32_e32 v28, v27
	v_pk_mul_f32 v[12:13], v[8:9], v[28:29] op_sel_hi:[0,1]
	v_and_b32_sdwa v9, v11, v173 dst_sel:DWORD dst_unused:UNUSED_PAD src0_sel:WORD_1 src1_sel:DWORD
	v_and_b32_sdwa v14, v10, v173 dst_sel:DWORD dst_unused:UNUSED_PAD src0_sel:WORD_1 src1_sel:DWORD
	v_add3_u32 v10, v10, v14, s15
	v_add3_u32 v9, v11, v9, s15
	v_and_b32_sdwa v11, v13, v173 dst_sel:DWORD dst_unused:UNUSED_PAD src0_sel:WORD_1 src1_sel:DWORD
	v_and_b32_sdwa v14, v12, v173 dst_sel:DWORD dst_unused:UNUSED_PAD src0_sel:WORD_1 src1_sel:DWORD
	v_add3_u32 v11, v13, v11, s15
	v_add3_u32 v12, v12, v14, s15
	v_and_b32_e32 v11, 0xffff0000, v11
	v_and_b32_e32 v12, 0xffff0000, v12
	v_or_b32_sdwa v11, v11, v9 dst_sel:DWORD dst_unused:UNUSED_PAD src0_sel:DWORD src1_sel:WORD_1
	v_or_b32_sdwa v10, v12, v10 dst_sel:DWORD dst_unused:UNUSED_PAD src0_sel:DWORD src1_sel:WORD_1
	global_store_dwordx2 v[6:7], v[10:11], off offset:96
	v_mov_b32_e32 v10, v22
	v_mov_b32_e32 v11, v24
	v_pk_mul_f32 v[10:11], v[8:9], v[10:11] op_sel_hi:[0,1]
	v_mov_b32_e32 v24, v23
	v_pk_mul_f32 v[12:13], v[8:9], v[24:25] op_sel_hi:[0,1]
	v_and_b32_sdwa v9, v11, v173 dst_sel:DWORD dst_unused:UNUSED_PAD src0_sel:WORD_1 src1_sel:DWORD
	v_and_b32_sdwa v14, v10, v173 dst_sel:DWORD dst_unused:UNUSED_PAD src0_sel:WORD_1 src1_sel:DWORD
	v_add3_u32 v10, v10, v14, s15
	v_add3_u32 v9, v11, v9, s15
	v_and_b32_sdwa v11, v13, v173 dst_sel:DWORD dst_unused:UNUSED_PAD src0_sel:WORD_1 src1_sel:DWORD
	v_and_b32_sdwa v14, v12, v173 dst_sel:DWORD dst_unused:UNUSED_PAD src0_sel:WORD_1 src1_sel:DWORD
	v_add3_u32 v11, v13, v11, s15
	v_add3_u32 v12, v12, v14, s15
	v_and_b32_e32 v11, 0xffff0000, v11
	v_and_b32_e32 v12, 0xffff0000, v12
	v_or_b32_sdwa v11, v11, v9 dst_sel:DWORD dst_unused:UNUSED_PAD src0_sel:DWORD src1_sel:WORD_1
; __device__ __forceinline__ unsigned pk2(float lo, float hi) { return f2bf(lo) | (f2bf(hi) << 16); }
; __device__ __forceinline__ void xattn_lds(const Ctx& C, const bf16* P, int cqoff, const bf16* MEMKV, const bf16* MEMVT, bf16* CAT, int ldc, int catoff, int u0, int ustride) {
;     ...
;         bf16* op = CAT + (size_t)qrow * ldc + catoff + xh * 256 + 4 * g;
; #pragma unroll
;         for (int dt = 0; dt < 16; ++dt) { v2u ow; ow.x = pk2(o[dt][0] * inv, o[dt][1] * inv); ow.y = pk2(o[dt][2] * inv, o[dt][3] * inv); *(v2u*)(op + dt * 16) = ow; }
	v_or_b32_sdwa v10, v12, v10 dst_sel:DWORD dst_unused:UNUSED_PAD src0_sel:DWORD src1_sel:WORD_1
	global_store_dwordx2 v[6:7], v[10:11], off offset:128
	v_mov_b32_e32 v10, v18
	v_mov_b32_e32 v11, v20
	v_pk_mul_f32 v[10:11], v[8:9], v[10:11] op_sel_hi:[0,1]
	v_mov_b32_e32 v20, v19
	v_pk_mul_f32 v[12:13], v[8:9], v[20:21] op_sel_hi:[0,1]
	v_and_b32_sdwa v9, v11, v173 dst_sel:DWORD dst_unused:UNUSED_PAD src0_sel:WORD_1 src1_sel:DWORD
	v_and_b32_sdwa v14, v10, v173 dst_sel:DWORD dst_unused:UNUSED_PAD src0_sel:WORD_1 src1_sel:DWORD
	v_add3_u32 v10, v10, v14, s15
	v_add3_u32 v9, v11, v9, s15
	v_and_b32_sdwa v11, v13, v173 dst_sel:DWORD dst_unused:UNUSED_PAD src0_sel:WORD_1 src1_sel:DWORD
	v_and_b32_sdwa v14, v12, v173 dst_sel:DWORD dst_unused:UNUSED_PAD src0_sel:WORD_1 src1_sel:DWORD
	v_add3_u32 v11, v13, v11, s15
	v_add3_u32 v12, v12, v14, s15
	v_and_b32_e32 v11, 0xffff0000, v11
	v_and_b32_e32 v12, 0xffff0000, v12
	v_or_b32_sdwa v11, v11, v9 dst_sel:DWORD dst_unused:UNUSED_PAD src0_sel:DWORD src1_sel:WORD_1
	v_or_b32_sdwa v10, v12, v10 dst_sel:DWORD dst_unused:UNUSED_PAD src0_sel:DWORD src1_sel:WORD_1
	global_store_dwordx2 v[6:7], v[10:11], off offset:160
	v_mov_b32_e32 v10, v46
	v_mov_b32_e32 v11, v48
	v_pk_mul_f32 v[10:11], v[8:9], v[10:11] op_sel_hi:[0,1]
	v_mov_b32_e32 v48, v47
	v_pk_mul_f32 v[12:13], v[8:9], v[48:49] op_sel_hi:[0,1]
	v_and_b32_sdwa v9, v11, v173 dst_sel:DWORD dst_unused:UNUSED_PAD src0_sel:WORD_1 src1_sel:DWORD
	v_and_b32_sdwa v14, v10, v173 dst_sel:DWORD dst_unused:UNUSED_PAD src0_sel:WORD_1 src1_sel:DWORD
	v_add3_u32 v10, v10, v14, s15
	v_add3_u32 v9, v11, v9, s15
	v_and_b32_sdwa v11, v13, v173 dst_sel:DWORD dst_unused:UNUSED_PAD src0_sel:WORD_1 src1_sel:DWORD
	v_and_b32_sdwa v14, v12, v173 dst_sel:DWORD dst_unused:UNUSED_PAD src0_sel:WORD_1 src1_sel:DWORD
	v_add3_u32 v11, v13, v11, s15
	v_add3_u32 v12, v12, v14, s15
	v_and_b32_e32 v11, 0xffff0000, v11
	v_and_b32_e32 v12, 0xffff0000, v12
	v_or_b32_sdwa v11, v11, v9 dst_sel:DWORD dst_unused:UNUSED_PAD src0_sel:DWORD src1_sel:WORD_1
	v_or_b32_sdwa v10, v12, v10 dst_sel:DWORD dst_unused:UNUSED_PAD src0_sel:DWORD src1_sel:WORD_1
	global_store_dwordx2 v[6:7], v[10:11], off offset:192
	v_mov_b32_e32 v10, v50
	v_mov_b32_e32 v11, v52
	v_pk_mul_f32 v[10:11], v[8:9], v[10:11] op_sel_hi:[0,1]
	v_mov_b32_e32 v52, v51
	v_pk_mul_f32 v[12:13], v[8:9], v[52:53] op_sel_hi:[0,1]
	v_and_b32_sdwa v9, v11, v173 dst_sel:DWORD dst_unused:UNUSED_PAD src0_sel:WORD_1 src1_sel:DWORD
	v_and_b32_sdwa v14, v10, v173 dst_sel:DWORD dst_unused:UNUSED_PAD src0_sel:WORD_1 src1_sel:DWORD
	v_add3_u32 v10, v10, v14, s15
	v_add3_u32 v9, v11, v9, s15
	v_and_b32_sdwa v11, v13, v173 dst_sel:DWORD dst_unused:UNUSED_PAD src0_sel:WORD_1 src1_sel:DWORD
	v_and_b32_sdwa v14, v12, v173 dst_sel:DWORD dst_unused:UNUSED_PAD src0_sel:WORD_1 src1_sel:DWORD
	v_add3_u32 v11, v13, v11, s15
	v_add3_u32 v12, v12, v14, s15
	v_and_b32_e32 v11, 0xffff0000, v11
	v_and_b32_e32 v12, 0xffff0000, v12
	v_or_b32_sdwa v11, v11, v9 dst_sel:DWORD dst_unused:UNUSED_PAD src0_sel:DWORD src1_sel:WORD_1
	v_or_b32_sdwa v10, v12, v10 dst_sel:DWORD dst_unused:UNUSED_PAD src0_sel:DWORD src1_sel:WORD_1
	global_store_dwordx2 v[6:7], v[10:11], off offset:224
	v_mov_b32_e32 v10, v54
	v_mov_b32_e32 v11, v56
	v_pk_mul_f32 v[10:11], v[8:9], v[10:11] op_sel_hi:[0,1]
	v_mov_b32_e32 v56, v55
	v_pk_mul_f32 v[12:13], v[8:9], v[56:57] op_sel_hi:[0,1]
	v_and_b32_sdwa v9, v11, v173 dst_sel:DWORD dst_unused:UNUSED_PAD src0_sel:WORD_1 src1_sel:DWORD
	v_and_b32_sdwa v14, v10, v173 dst_sel:DWORD dst_unused:UNUSED_PAD src0_sel:WORD_1 src1_sel:DWORD
	v_add3_u32 v10, v10, v14, s15
	v_add3_u32 v9, v11, v9, s15
	v_and_b32_sdwa v11, v13, v173 dst_sel:DWORD dst_unused:UNUSED_PAD src0_sel:WORD_1 src1_sel:DWORD
	v_and_b32_sdwa v14, v12, v173 dst_sel:DWORD dst_unused:UNUSED_PAD src0_sel:WORD_1 src1_sel:DWORD
	v_add3_u32 v11, v13, v11, s15
	v_add3_u32 v12, v12, v14, s15
	v_and_b32_e32 v11, 0xffff0000, v11
	v_and_b32_e32 v12, 0xffff0000, v12
	v_or_b32_sdwa v11, v11, v9 dst_sel:DWORD dst_unused:UNUSED_PAD src0_sel:DWORD src1_sel:WORD_1
	v_or_b32_sdwa v10, v12, v10 dst_sel:DWORD dst_unused:UNUSED_PAD src0_sel:DWORD src1_sel:WORD_1
	global_store_dwordx2 v[6:7], v[10:11], off offset:256
	v_mov_b32_e32 v10, v58
	v_mov_b32_e32 v11, v60
	v_pk_mul_f32 v[10:11], v[8:9], v[10:11] op_sel_hi:[0,1]
	v_mov_b32_e32 v60, v59
	v_pk_mul_f32 v[12:13], v[8:9], v[60:61] op_sel_hi:[0,1]
	v_and_b32_sdwa v9, v11, v173 dst_sel:DWORD dst_unused:UNUSED_PAD src0_sel:WORD_1 src1_sel:DWORD
	v_and_b32_sdwa v14, v10, v173 dst_sel:DWORD dst_unused:UNUSED_PAD src0_sel:WORD_1 src1_sel:DWORD
	v_add3_u32 v10, v10, v14, s15
	v_add3_u32 v9, v11, v9, s15
	v_and_b32_sdwa v11, v13, v173 dst_sel:DWORD dst_unused:UNUSED_PAD src0_sel:WORD_1 src1_sel:DWORD
	v_and_b32_sdwa v14, v12, v173 dst_sel:DWORD dst_unused:UNUSED_PAD src0_sel:WORD_1 src1_sel:DWORD
	v_add3_u32 v11, v13, v11, s15
	v_add3_u32 v12, v12, v14, s15
	v_and_b32_e32 v11, 0xffff0000, v11
	v_and_b32_e32 v12, 0xffff0000, v12
	v_or_b32_sdwa v11, v11, v9 dst_sel:DWORD dst_unused:UNUSED_PAD src0_sel:DWORD src1_sel:WORD_1
	v_or_b32_sdwa v10, v12, v10 dst_sel:DWORD dst_unused:UNUSED_PAD src0_sel:DWORD src1_sel:WORD_1
	global_store_dwordx2 v[6:7], v[10:11], off offset:288
	v_mov_b32_e32 v10, v62
	v_mov_b32_e32 v11, v64
	v_pk_mul_f32 v[10:11], v[8:9], v[10:11] op_sel_hi:[0,1]
	v_mov_b32_e32 v64, v63
	v_pk_mul_f32 v[12:13], v[8:9], v[64:65] op_sel_hi:[0,1]
	v_and_b32_sdwa v9, v11, v173 dst_sel:DWORD dst_unused:UNUSED_PAD src0_sel:WORD_1 src1_sel:DWORD
	v_and_b32_sdwa v14, v10, v173 dst_sel:DWORD dst_unused:UNUSED_PAD src0_sel:WORD_1 src1_sel:DWORD
	v_add3_u32 v10, v10, v14, s15
; __device__ __forceinline__ unsigned pk2(float lo, float hi) { return f2bf(lo) | (f2bf(hi) << 16); }
; __device__ __forceinline__ void xattn_lds(const Ctx& C, const bf16* P, int cqoff, const bf16* MEMKV, const bf16* MEMVT, bf16* CAT, int ldc, int catoff, int u0, int ustride) {
;     ...
;         bf16* op = CAT + (size_t)qrow * ldc + catoff + xh * 256 + 4 * g;
; #pragma unroll
;         for (int dt = 0; dt < 16; ++dt) { v2u ow; ow.x = pk2(o[dt][0] * inv, o[dt][1] * inv); ow.y = pk2(o[dt][2] * inv, o[dt][3] * inv); *(v2u*)(op + dt * 16) = ow; }
;     }
	v_add3_u32 v9, v11, v9, s15
	v_and_b32_sdwa v11, v13, v173 dst_sel:DWORD dst_unused:UNUSED_PAD src0_sel:WORD_1 src1_sel:DWORD
	v_and_b32_sdwa v14, v12, v173 dst_sel:DWORD dst_unused:UNUSED_PAD src0_sel:WORD_1 src1_sel:DWORD
	v_add3_u32 v11, v13, v11, s15
	v_add3_u32 v12, v12, v14, s15
	v_and_b32_e32 v11, 0xffff0000, v11
	v_and_b32_e32 v12, 0xffff0000, v12
	v_or_b32_sdwa v11, v11, v9 dst_sel:DWORD dst_unused:UNUSED_PAD src0_sel:DWORD src1_sel:WORD_1
	v_or_b32_sdwa v10, v12, v10 dst_sel:DWORD dst_unused:UNUSED_PAD src0_sel:DWORD src1_sel:WORD_1
	global_store_dwordx2 v[6:7], v[10:11], off offset:320
	v_mov_b32_e32 v10, v66
	v_mov_b32_e32 v11, v68
	v_pk_mul_f32 v[10:11], v[8:9], v[10:11] op_sel_hi:[0,1]
	v_mov_b32_e32 v68, v67
	v_pk_mul_f32 v[12:13], v[8:9], v[68:69] op_sel_hi:[0,1]
	v_and_b32_sdwa v9, v11, v173 dst_sel:DWORD dst_unused:UNUSED_PAD src0_sel:WORD_1 src1_sel:DWORD
	v_and_b32_sdwa v14, v10, v173 dst_sel:DWORD dst_unused:UNUSED_PAD src0_sel:WORD_1 src1_sel:DWORD
	v_add3_u32 v10, v10, v14, s15
	v_add3_u32 v9, v11, v9, s15
	v_and_b32_sdwa v11, v13, v173 dst_sel:DWORD dst_unused:UNUSED_PAD src0_sel:WORD_1 src1_sel:DWORD
	v_and_b32_sdwa v14, v12, v173 dst_sel:DWORD dst_unused:UNUSED_PAD src0_sel:WORD_1 src1_sel:DWORD
	v_add3_u32 v11, v13, v11, s15
	v_add3_u32 v12, v12, v14, s15
	v_and_b32_e32 v11, 0xffff0000, v11
	v_and_b32_e32 v12, 0xffff0000, v12
	v_or_b32_sdwa v11, v11, v9 dst_sel:DWORD dst_unused:UNUSED_PAD src0_sel:DWORD src1_sel:WORD_1
	v_or_b32_sdwa v10, v12, v10 dst_sel:DWORD dst_unused:UNUSED_PAD src0_sel:DWORD src1_sel:WORD_1
	global_store_dwordx2 v[6:7], v[10:11], off offset:352
	v_mov_b32_e32 v10, v74
	v_mov_b32_e32 v11, v76
	v_pk_mul_f32 v[10:11], v[8:9], v[10:11] op_sel_hi:[0,1]
	v_mov_b32_e32 v76, v75
	v_pk_mul_f32 v[12:13], v[8:9], v[76:77] op_sel_hi:[0,1]
	v_and_b32_sdwa v9, v11, v173 dst_sel:DWORD dst_unused:UNUSED_PAD src0_sel:WORD_1 src1_sel:DWORD
	v_and_b32_sdwa v14, v10, v173 dst_sel:DWORD dst_unused:UNUSED_PAD src0_sel:WORD_1 src1_sel:DWORD
	v_add3_u32 v10, v10, v14, s15
	v_add3_u32 v9, v11, v9, s15
	v_and_b32_sdwa v11, v13, v173 dst_sel:DWORD dst_unused:UNUSED_PAD src0_sel:WORD_1 src1_sel:DWORD
	v_and_b32_sdwa v14, v12, v173 dst_sel:DWORD dst_unused:UNUSED_PAD src0_sel:WORD_1 src1_sel:DWORD
	v_add3_u32 v11, v13, v11, s15
	v_add3_u32 v12, v12, v14, s15
	v_and_b32_e32 v11, 0xffff0000, v11
	v_and_b32_e32 v12, 0xffff0000, v12
	v_or_b32_sdwa v11, v11, v9 dst_sel:DWORD dst_unused:UNUSED_PAD src0_sel:DWORD src1_sel:WORD_1
	v_or_b32_sdwa v10, v12, v10 dst_sel:DWORD dst_unused:UNUSED_PAD src0_sel:DWORD src1_sel:WORD_1
	global_store_dwordx2 v[6:7], v[10:11], off offset:384
	v_mov_b32_e32 v10, v78
	v_mov_b32_e32 v11, v80
	v_pk_mul_f32 v[10:11], v[8:9], v[10:11] op_sel_hi:[0,1]
	v_mov_b32_e32 v80, v79
	v_pk_mul_f32 v[12:13], v[8:9], v[80:81] op_sel_hi:[0,1]
	v_and_b32_sdwa v9, v11, v173 dst_sel:DWORD dst_unused:UNUSED_PAD src0_sel:WORD_1 src1_sel:DWORD
	v_and_b32_sdwa v14, v10, v173 dst_sel:DWORD dst_unused:UNUSED_PAD src0_sel:WORD_1 src1_sel:DWORD
	v_add3_u32 v10, v10, v14, s15
	v_add3_u32 v9, v11, v9, s15
	v_and_b32_sdwa v11, v13, v173 dst_sel:DWORD dst_unused:UNUSED_PAD src0_sel:WORD_1 src1_sel:DWORD
	v_and_b32_sdwa v14, v12, v173 dst_sel:DWORD dst_unused:UNUSED_PAD src0_sel:WORD_1 src1_sel:DWORD
	v_add3_u32 v11, v13, v11, s15
	v_add3_u32 v12, v12, v14, s15
	v_and_b32_e32 v11, 0xffff0000, v11
	v_and_b32_e32 v12, 0xffff0000, v12
	v_or_b32_sdwa v11, v11, v9 dst_sel:DWORD dst_unused:UNUSED_PAD src0_sel:DWORD src1_sel:WORD_1
	v_or_b32_sdwa v10, v12, v10 dst_sel:DWORD dst_unused:UNUSED_PAD src0_sel:DWORD src1_sel:WORD_1
	global_store_dwordx2 v[6:7], v[10:11], off offset:416
	v_mov_b32_e32 v10, v70
	v_mov_b32_e32 v11, v72
	v_pk_mul_f32 v[10:11], v[8:9], v[10:11] op_sel_hi:[0,1]
	v_mov_b32_e32 v72, v71
	v_pk_mul_f32 v[12:13], v[8:9], v[72:73] op_sel_hi:[0,1]
	v_and_b32_sdwa v9, v11, v173 dst_sel:DWORD dst_unused:UNUSED_PAD src0_sel:WORD_1 src1_sel:DWORD
	v_and_b32_sdwa v14, v10, v173 dst_sel:DWORD dst_unused:UNUSED_PAD src0_sel:WORD_1 src1_sel:DWORD
	v_add3_u32 v10, v10, v14, s15
	v_add3_u32 v9, v11, v9, s15
	v_and_b32_sdwa v11, v13, v173 dst_sel:DWORD dst_unused:UNUSED_PAD src0_sel:WORD_1 src1_sel:DWORD
	v_and_b32_sdwa v14, v12, v173 dst_sel:DWORD dst_unused:UNUSED_PAD src0_sel:WORD_1 src1_sel:DWORD
	v_add3_u32 v11, v13, v11, s15
	v_add3_u32 v12, v12, v14, s15
	v_and_b32_e32 v11, 0xffff0000, v11
	v_and_b32_e32 v12, 0xffff0000, v12
	v_or_b32_sdwa v11, v11, v9 dst_sel:DWORD dst_unused:UNUSED_PAD src0_sel:DWORD src1_sel:WORD_1
	v_or_b32_sdwa v10, v12, v10 dst_sel:DWORD dst_unused:UNUSED_PAD src0_sel:DWORD src1_sel:WORD_1
	global_store_dwordx2 v[6:7], v[10:11], off offset:448
	v_mov_b32_e32 v11, v4
	v_mov_b32_e32 v4, v3
	v_mov_b32_e32 v10, v2
	v_pk_mul_f32 v[2:3], v[8:9], v[4:5] op_sel_hi:[0,1]
	v_pk_mul_f32 v[10:11], v[8:9], v[10:11] op_sel_hi:[0,1]
	v_and_b32_sdwa v8, v3, v173 dst_sel:DWORD dst_unused:UNUSED_PAD src0_sel:WORD_1 src1_sel:DWORD
	v_and_b32_sdwa v9, v2, v173 dst_sel:DWORD dst_unused:UNUSED_PAD src0_sel:WORD_1 src1_sel:DWORD
	v_and_b32_sdwa v4, v11, v173 dst_sel:DWORD dst_unused:UNUSED_PAD src0_sel:WORD_1 src1_sel:DWORD
	v_and_b32_sdwa v5, v10, v173 dst_sel:DWORD dst_unused:UNUSED_PAD src0_sel:WORD_1 src1_sel:DWORD
	v_add3_u32 v3, v3, v8, s15
	v_add3_u32 v2, v2, v9, s15
	v_add3_u32 v5, v10, v5, s15
	v_add3_u32 v4, v11, v4, s15
	v_and_b32_e32 v3, 0xffff0000, v3
	v_and_b32_e32 v2, 0xffff0000, v2
	v_or_b32_sdwa v3, v3, v4 dst_sel:DWORD dst_unused:UNUSED_PAD src0_sel:DWORD src1_sel:WORD_1
	v_or_b32_sdwa v2, v2, v5 dst_sel:DWORD dst_unused:UNUSED_PAD src0_sel:DWORD src1_sel:WORD_1
	global_store_dwordx2 v[6:7], v[2:3], off offset:480
	s_cbranch_scc1 .LBB0_466

; #define LAS __attribute__((address_space(3)))
; __device__ __forceinline__ void xattn_lds(const Ctx& C, const bf16* P, int cqoff, const bf16* MEMKV, const bf16* MEMVT, bf16* CAT, int ldc, int catoff, int u0, int ustride) {
;     ...
;     for (int u = u0; u < 256; u += ustride) {
;         const int b = u >> 7, xh = (u >> 5) & 3, qb = u & 31;
;         const int qrow = b * SEQ + qb * 128 + w * 16 + c;
;         bf16x8v qf[8];
;         { const bf16* qp = P + (size_t)qrow * LDP + cqoff + xh * 256 + 8 * g;
; #pragma unroll
;           for (int ks = 0; ks < 8; ++ks) qf[ks] = *(const bf16x8v*)(qp + 32 * ks); }
;         f32x4 s[16];
; #pragma unroll
;         for (int kt = 0; kt < 16; ++kt) s[kt] = (f32x4){0.f, 0.f, 0.f, 0.f};
; #pragma unroll
;         for (int half = 0; half < 2; ++half) {
;             v4u stg[8];
; #pragma unroll
;             for (int it = 0; it < 8; ++it) { const int idx = it * 512 + tid, row = idx >> 5, c16 = idx & 31;
;                 stg[it] = *(const v4u*)(MEMKV + (size_t)(b * 256 + half * 128 + row) * 2048 + xh * 256 + c16 * 8); }
;             __syncthreads();
; #pragma unroll
;             for (int it = 0; it < 8; ++it) { const int idx = it * 512 + tid, row = idx >> 5, c16 = idx & 31; *(LAS v4u*)(Ls + row * KP + c16 * 16) = stg[it]; }
;             __syncthreads();
; #pragma unroll
;             for (int kt = 0; kt < 8; ++kt) {
; #pragma unroll
;                 for (int ks = 0; ks < 8; ++ks) { const bf16x8v kf = *(const LAS bf16x8v*)(Ls + (16 * kt + c) * KP + (32 * ks + 8 * g) * 2);
;                     s[8 * half + kt] = __builtin_amdgcn_mfma_f32_16x16x32_bf16(kf, qf[ks], s[8 * half + kt], 0, 0, 0); }
;                 asm volatile("" ::: "memory"); }
.LBB0_1331:
	s_ashr_i32 s25, s16, 7
	s_lshl_b32 s0, s25, 12
	s_and_b32 s1, s18, 0xf80
	s_or_b32 s0, s0, s1
	v_add_u32_e32 v104, s0, v140
	v_mad_i64_i32 v[2:3], s[0:1], v104, s20, v[98:99]
	s_and_b32 s0, s24, 0x300
	s_lshl_b32 s10, s0, 1
	v_lshl_add_u64 v[2:3], v[2:3], 0, s[10:11]
	v_lshl_add_u64 v[2:3], v[2:3], 0, v[94:95]
	s_lshl_b32 s0, s25, 8
	global_load_dwordx4 v[70:73], v[2:3], off
	global_load_dwordx4 v[62:65], v[2:3], off offset:64
	global_load_dwordx4 v[54:57], v[2:3], off offset:128
	global_load_dwordx4 v[50:53], v[2:3], off offset:192
	global_load_dwordx4 v[46:49], v[2:3], off offset:256
	global_load_dwordx4 v[42:45], v[2:3], off offset:320
	global_load_dwordx4 v[38:41], v[2:3], off offset:384
	global_load_dwordx4 v[34:37], v[2:3], off offset:448
	v_add_u32_e32 v2, s0, v141
	v_ashrrev_i32_e32 v3, 31, v2
	v_add_u32_e32 v6, s0, v142
	s_waitcnt vmcnt(0)
	v_lshl_add_u64 v[58:59], v[96:97], 0, s[10:11]
	v_lshlrev_b64 v[122:123], 12, v[2:3]
	v_ashrrev_i32_e32 v7, 31, v6
	v_add_u32_e32 v10, s0, v143
	v_lshl_add_u64 v[2:3], v[58:59], 0, v[122:123]
	v_lshlrev_b64 v[124:125], 12, v[6:7]
	v_ashrrev_i32_e32 v11, 31, v10
	v_add_u32_e32 v14, s0, v144
	global_load_dwordx4 v[2:5], v[2:3], off
	v_lshl_add_u64 v[6:7], v[58:59], 0, v[124:125]
	v_lshlrev_b64 v[126:127], 12, v[10:11]
	v_ashrrev_i32_e32 v15, 31, v14
	v_add_u32_e32 v18, s0, v145
	global_load_dwordx4 v[6:9], v[6:7], off
	v_lshl_add_u64 v[10:11], v[58:59], 0, v[126:127]
	v_lshlrev_b64 v[128:129], 12, v[14:15]
	v_ashrrev_i32_e32 v19, 31, v18
	v_add_u32_e32 v22, s0, v146
	global_load_dwordx4 v[10:13], v[10:11], off
	v_lshl_add_u64 v[14:15], v[58:59], 0, v[128:129]
	v_lshlrev_b64 v[130:131], 12, v[18:19]
	v_ashrrev_i32_e32 v23, 31, v22
	v_add_u32_e32 v26, s0, v147
	global_load_dwordx4 v[14:17], v[14:15], off
	v_lshl_add_u64 v[18:19], v[58:59], 0, v[130:131]
	v_lshlrev_b64 v[132:133], 12, v[22:23]
	v_ashrrev_i32_e32 v27, 31, v26
	v_add_u32_e32 v30, s0, v148
	global_load_dwordx4 v[18:21], v[18:19], off
	v_lshl_add_u64 v[22:23], v[58:59], 0, v[132:133]
	v_lshlrev_b64 v[134:135], 12, v[26:27]
	v_ashrrev_i32_e32 v31, 31, v30
	global_load_dwordx4 v[22:25], v[22:23], off
	v_lshl_add_u64 v[26:27], v[58:59], 0, v[134:135]
	v_lshlrev_b64 v[136:137], 12, v[30:31]
	global_load_dwordx4 v[26:29], v[26:27], off
	v_lshl_add_u64 v[30:31], v[58:59], 0, v[136:137]
	global_load_dwordx4 v[30:33], v[30:31], off
	s_barrier
	s_bitset1_b32 s0, 7
	v_add_u32_e32 v60, s0, v141
	v_ashrrev_i32_e32 v61, 31, v60
	v_lshlrev_b64 v[106:107], 12, v[60:61]
	v_lshl_add_u64 v[60:61], v[58:59], 0, v[106:107]
	v_cmp_lt_i32_e32 vcc, v169, v170
	v_ashrrev_i32_e32 v105, 31, v104
	s_add_i32 s16, s16, s13
	s_add_i32 s24, s24, s17
	s_add_i32 s18, s18, s19
	s_cmpk_lt_i32 s16, 0x100
	s_waitcnt vmcnt(7)
	ds_write_b128 v150, v[2:5]
	s_waitcnt vmcnt(6)
	ds_write_b128 v151, v[6:9]
	s_waitcnt vmcnt(5)
	ds_write_b128 v152, v[10:13]
	s_waitcnt vmcnt(4)
	ds_write_b128 v153, v[14:17]
	s_waitcnt vmcnt(3)
	ds_write_b128 v154, v[18:21]
	s_waitcnt vmcnt(2)
	ds_write_b128 v155, v[22:25]
	s_waitcnt vmcnt(1)
	ds_write_b128 v156, v[26:29]
	s_waitcnt vmcnt(0)
	ds_write_b128 v157, v[30:33]
	s_waitcnt lgkmcnt(0)
	s_barrier
	ds_read_b128 v[2:5], v158
	ds_read_b128 v[6:9], v158 offset:64
	s_waitcnt lgkmcnt(1)
	v_mfma_f32_16x16x32_bf16 v[2:5], v[2:5], v[70:73], 0
	s_waitcnt lgkmcnt(0)
	v_mfma_f32_16x16x32_bf16 v[2:5], v[6:9], v[62:65], v[2:5]
	ds_read_b128 v[6:9], v158 offset:128
	s_waitcnt lgkmcnt(0)
	v_mfma_f32_16x16x32_bf16 v[2:5], v[6:9], v[54:57], v[2:5]
	ds_read_b128 v[6:9], v158 offset:192
	s_waitcnt lgkmcnt(0)
	v_mfma_f32_16x16x32_bf16 v[2:5], v[6:9], v[50:53], v[2:5]
	ds_read_b128 v[6:9], v158 offset:256
	s_waitcnt lgkmcnt(0)
	v_mfma_f32_16x16x32_bf16 v[2:5], v[6:9], v[46:49], v[2:5]
	ds_read_b128 v[6:9], v158 offset:320
	s_waitcnt lgkmcnt(0)
	v_mfma_f32_16x16x32_bf16 v[2:5], v[6:9], v[42:45], v[2:5]
	ds_read_b128 v[6:9], v158 offset:384
	s_waitcnt lgkmcnt(0)
	v_mfma_f32_16x16x32_bf16 v[2:5], v[6:9], v[38:41], v[2:5]
	ds_read_b128 v[6:9], v158 offset:448
	ds_read_b128 v[10:13], v158 offset:8512
	s_waitcnt lgkmcnt(1)
	v_mfma_f32_16x16x32_bf16 v[2:5], v[6:9], v[34:37], v[2:5]
	ds_read_b128 v[6:9], v158 offset:8448
	s_waitcnt lgkmcnt(0)
	v_mfma_f32_16x16x32_bf16 v[6:9], v[6:9], v[70:73], 0
	v_mfma_f32_16x16x32_bf16 v[6:9], v[10:13], v[62:65], v[6:9]
	ds_read_b128 v[10:13], v158 offset:8576
	s_waitcnt lgkmcnt(0)
	v_mfma_f32_16x16x32_bf16 v[6:9], v[10:13], v[54:57], v[6:9]
	ds_read_b128 v[10:13], v158 offset:8640
	s_waitcnt lgkmcnt(0)
	v_mfma_f32_16x16x32_bf16 v[6:9], v[10:13], v[50:53], v[6:9]
	ds_read_b128 v[10:13], v158 offset:8704
	s_waitcnt lgkmcnt(0)
	v_mfma_f32_16x16x32_bf16 v[6:9], v[10:13], v[46:49], v[6:9]
	ds_read_b128 v[10:13], v158 offset:8768
	s_waitcnt lgkmcnt(0)
	v_mfma_f32_16x16x32_bf16 v[6:9], v[10:13], v[42:45], v[6:9]
	ds_read_b128 v[10:13], v158 offset:8832
	s_waitcnt lgkmcnt(0)
	v_mfma_f32_16x16x32_bf16 v[6:9], v[10:13], v[38:41], v[6:9]
	ds_read_b128 v[10:13], v158 offset:8896
	ds_read_b128 v[14:17], v158 offset:16960
	s_waitcnt lgkmcnt(1)
	v_mfma_f32_16x16x32_bf16 v[10:13], v[10:13], v[34:37], v[6:9]
	s_nop 3
	ds_read_b128 v[6:9], v158 offset:16896
	s_waitcnt lgkmcnt(0)
	v_mfma_f32_16x16x32_bf16 v[6:9], v[6:9], v[70:73], 0
	v_mfma_f32_16x16x32_bf16 v[6:9], v[14:17], v[62:65], v[6:9]
	ds_read_b128 v[14:17], v158 offset:17024
	s_waitcnt lgkmcnt(0)
	v_mfma_f32_16x16x32_bf16 v[6:9], v[14:17], v[54:57], v[6:9]
	ds_read_b128 v[14:17], v158 offset:17088
	s_waitcnt lgkmcnt(0)
	v_mfma_f32_16x16x32_bf16 v[6:9], v[14:17], v[50:53], v[6:9]
	ds_read_b128 v[14:17], v158 offset:17152
	s_waitcnt lgkmcnt(0)
; #define LAS __attribute__((address_space(3)))
; __device__ __forceinline__ void xattn_lds(const Ctx& C, const bf16* P, int cqoff, const bf16* MEMKV, const bf16* MEMVT, bf16* CAT, int ldc, int catoff, int u0, int ustride) {
;     ...
;         for (int half = 0; half < 2; ++half) {
;             v4u stg[8];
; #pragma unroll
;             for (int it = 0; it < 8; ++it) { const int idx = it * 512 + tid, row = idx >> 5, c16 = idx & 31;
;                 stg[it] = *(const v4u*)(MEMKV + (size_t)(b * 256 + half * 128 + row) * 2048 + xh * 256 + c16 * 8); }
;             __syncthreads();
; #pragma unroll
;             for (int it = 0; it < 8; ++it) { const int idx = it * 512 + tid, row = idx >> 5, c16 = idx & 31; *(LAS v4u*)(Ls + row * KP + c16 * 16) = stg[it]; }
;             __syncthreads();
; #pragma unroll
;             for (int kt = 0; kt < 8; ++kt) {
; #pragma unroll
;                 for (int ks = 0; ks < 8; ++ks) { const bf16x8v kf = *(const LAS bf16x8v*)(Ls + (16 * kt + c) * KP + (32 * ks + 8 * g) * 2);
;                     s[8 * half + kt] = __builtin_amdgcn_mfma_f32_16x16x32_bf16(kf, qf[ks], s[8 * half + kt], 0, 0, 0); }
;                 asm volatile("" ::: "memory"); }
	v_mfma_f32_16x16x32_bf16 v[6:9], v[14:17], v[46:49], v[6:9]
	ds_read_b128 v[14:17], v158 offset:17216
	s_waitcnt lgkmcnt(0)
	v_mfma_f32_16x16x32_bf16 v[6:9], v[14:17], v[42:45], v[6:9]
	ds_read_b128 v[14:17], v158 offset:17280
	s_waitcnt lgkmcnt(0)
	v_mfma_f32_16x16x32_bf16 v[6:9], v[14:17], v[38:41], v[6:9]
	ds_read_b128 v[14:17], v158 offset:17344
	ds_read_b128 v[18:21], v158 offset:25408
	s_waitcnt lgkmcnt(1)
	v_mfma_f32_16x16x32_bf16 v[6:9], v[14:17], v[34:37], v[6:9]
	ds_read_b128 v[14:17], v158 offset:25344
	s_waitcnt lgkmcnt(0)
	v_mfma_f32_16x16x32_bf16 v[14:17], v[14:17], v[70:73], 0
	v_mfma_f32_16x16x32_bf16 v[14:17], v[18:21], v[62:65], v[14:17]
	ds_read_b128 v[18:21], v158 offset:25472
	s_waitcnt lgkmcnt(0)
	v_mfma_f32_16x16x32_bf16 v[14:17], v[18:21], v[54:57], v[14:17]
	ds_read_b128 v[18:21], v158 offset:25536
	s_waitcnt lgkmcnt(0)
	v_mfma_f32_16x16x32_bf16 v[14:17], v[18:21], v[50:53], v[14:17]
	ds_read_b128 v[18:21], v158 offset:25600
	s_waitcnt lgkmcnt(0)
	v_mfma_f32_16x16x32_bf16 v[14:17], v[18:21], v[46:49], v[14:17]
	ds_read_b128 v[18:21], v158 offset:25664
	s_waitcnt lgkmcnt(0)
	v_mfma_f32_16x16x32_bf16 v[14:17], v[18:21], v[42:45], v[14:17]
	ds_read_b128 v[18:21], v158 offset:25728
	s_waitcnt lgkmcnt(0)
	v_mfma_f32_16x16x32_bf16 v[14:17], v[18:21], v[38:41], v[14:17]
	ds_read_b128 v[18:21], v158 offset:25792
	ds_read_b128 v[22:25], v158 offset:33856
	s_waitcnt lgkmcnt(1)
	v_mfma_f32_16x16x32_bf16 v[18:21], v[18:21], v[34:37], v[14:17]
	s_nop 3
	ds_read_b128 v[14:17], v158 offset:33792
	s_waitcnt lgkmcnt(0)
	v_mfma_f32_16x16x32_bf16 v[14:17], v[14:17], v[70:73], 0
	v_mfma_f32_16x16x32_bf16 v[14:17], v[22:25], v[62:65], v[14:17]
	ds_read_b128 v[22:25], v158 offset:33920
	s_waitcnt lgkmcnt(0)
	v_mfma_f32_16x16x32_bf16 v[14:17], v[22:25], v[54:57], v[14:17]
	ds_read_b128 v[22:25], v158 offset:33984
	s_waitcnt lgkmcnt(0)
	v_mfma_f32_16x16x32_bf16 v[14:17], v[22:25], v[50:53], v[14:17]
	ds_read_b128 v[22:25], v158 offset:34048
	s_waitcnt lgkmcnt(0)
	v_mfma_f32_16x16x32_bf16 v[14:17], v[22:25], v[46:49], v[14:17]
	ds_read_b128 v[22:25], v158 offset:34112
	s_waitcnt lgkmcnt(0)
	v_mfma_f32_16x16x32_bf16 v[14:17], v[22:25], v[42:45], v[14:17]
	ds_read_b128 v[22:25], v158 offset:34176
	s_waitcnt lgkmcnt(0)
	v_mfma_f32_16x16x32_bf16 v[14:17], v[22:25], v[38:41], v[14:17]
	ds_read_b128 v[22:25], v158 offset:34240
	ds_read_b128 v[26:29], v158 offset:42304
	s_waitcnt lgkmcnt(1)
	v_mfma_f32_16x16x32_bf16 v[14:17], v[22:25], v[34:37], v[14:17]
	ds_read_b128 v[22:25], v158 offset:42240
	s_waitcnt lgkmcnt(0)
	v_mfma_f32_16x16x32_bf16 v[22:25], v[22:25], v[70:73], 0
	v_mfma_f32_16x16x32_bf16 v[22:25], v[26:29], v[62:65], v[22:25]
	ds_read_b128 v[26:29], v158 offset:42368
	s_waitcnt lgkmcnt(0)
	v_mfma_f32_16x16x32_bf16 v[22:25], v[26:29], v[54:57], v[22:25]
	ds_read_b128 v[26:29], v158 offset:42432
	s_waitcnt lgkmcnt(0)
	v_mfma_f32_16x16x32_bf16 v[22:25], v[26:29], v[50:53], v[22:25]
	ds_read_b128 v[26:29], v158 offset:42496
	s_waitcnt lgkmcnt(0)
	v_mfma_f32_16x16x32_bf16 v[22:25], v[26:29], v[46:49], v[22:25]
	ds_read_b128 v[26:29], v158 offset:42560
	s_waitcnt lgkmcnt(0)
	v_mfma_f32_16x16x32_bf16 v[22:25], v[26:29], v[42:45], v[22:25]
	ds_read_b128 v[26:29], v158 offset:42624
	s_waitcnt lgkmcnt(0)
	v_mfma_f32_16x16x32_bf16 v[22:25], v[26:29], v[38:41], v[22:25]
	ds_read_b128 v[26:29], v158 offset:42688
	ds_read_b128 v[30:33], v158 offset:50752
	s_waitcnt lgkmcnt(1)
	v_mfma_f32_16x16x32_bf16 v[26:29], v[26:29], v[34:37], v[22:25]
	s_nop 3
	ds_read_b128 v[22:25], v158 offset:50688
	s_waitcnt lgkmcnt(0)
	v_mfma_f32_16x16x32_bf16 v[22:25], v[22:25], v[70:73], 0
	v_mfma_f32_16x16x32_bf16 v[22:25], v[30:33], v[62:65], v[22:25]
	ds_read_b128 v[30:33], v158 offset:50816
	s_waitcnt lgkmcnt(0)
	v_mfma_f32_16x16x32_bf16 v[22:25], v[30:33], v[54:57], v[22:25]
	ds_read_b128 v[30:33], v158 offset:50880
	s_waitcnt lgkmcnt(0)
	v_mfma_f32_16x16x32_bf16 v[22:25], v[30:33], v[50:53], v[22:25]
	ds_read_b128 v[30:33], v158 offset:50944
	s_waitcnt lgkmcnt(0)
	v_mfma_f32_16x16x32_bf16 v[22:25], v[30:33], v[46:49], v[22:25]
	ds_read_b128 v[30:33], v158 offset:51008
	s_waitcnt lgkmcnt(0)
	v_mfma_f32_16x16x32_bf16 v[22:25], v[30:33], v[42:45], v[22:25]
	ds_read_b128 v[30:33], v158 offset:51072
	s_waitcnt lgkmcnt(0)
	v_mfma_f32_16x16x32_bf16 v[22:25], v[30:33], v[38:41], v[22:25]
	ds_read_b128 v[30:33], v158 offset:51136
	ds_read_b128 v[66:69], v158 offset:59200
	s_waitcnt lgkmcnt(1)
	v_mfma_f32_16x16x32_bf16 v[22:25], v[30:33], v[34:37], v[22:25]
	ds_read_b128 v[30:33], v158 offset:59136
	s_waitcnt lgkmcnt(0)
	v_mfma_f32_16x16x32_bf16 v[30:33], v[30:33], v[70:73], 0
	v_mfma_f32_16x16x32_bf16 v[30:33], v[66:69], v[62:65], v[30:33]
	ds_read_b128 v[66:69], v158 offset:59264
	s_waitcnt lgkmcnt(0)
	v_mfma_f32_16x16x32_bf16 v[30:33], v[66:69], v[54:57], v[30:33]
	ds_read_b128 v[66:69], v158 offset:59328
	s_waitcnt lgkmcnt(0)
	v_mfma_f32_16x16x32_bf16 v[30:33], v[66:69], v[50:53], v[30:33]
	ds_read_b128 v[66:69], v158 offset:59392
	s_waitcnt lgkmcnt(0)
	v_mfma_f32_16x16x32_bf16 v[30:33], v[66:69], v[46:49], v[30:33]
	ds_read_b128 v[66:69], v158 offset:59456
	s_waitcnt lgkmcnt(0)
	v_mfma_f32_16x16x32_bf16 v[30:33], v[66:69], v[42:45], v[30:33]
	ds_read_b128 v[66:69], v158 offset:59520
	s_waitcnt lgkmcnt(0)
	v_mfma_f32_16x16x32_bf16 v[30:33], v[66:69], v[38:41], v[30:33]
	ds_read_b128 v[66:69], v158 offset:59584
	s_waitcnt lgkmcnt(0)
	v_mfma_f32_16x16x32_bf16 v[30:33], v[66:69], v[34:37], v[30:33]
	global_load_dwordx4 v[66:69], v[60:61], off
	v_add_u32_e32 v60, s0, v142
	v_ashrrev_i32_e32 v61, 31, v60
	v_lshlrev_b64 v[108:109], 12, v[60:61]
	v_lshl_add_u64 v[60:61], v[58:59], 0, v[108:109]
	global_load_dwordx4 v[74:77], v[60:61], off
	v_add_u32_e32 v60, s0, v143
	v_ashrrev_i32_e32 v61, 31, v60
	v_lshlrev_b64 v[110:111], 12, v[60:61]
	v_lshl_add_u64 v[60:61], v[58:59], 0, v[110:111]
	global_load_dwordx4 v[78:81], v[60:61], off
	v_add_u32_e32 v60, s0, v144
	v_ashrrev_i32_e32 v61, 31, v60
	v_lshlrev_b64 v[112:113], 12, v[60:61]
	v_lshl_add_u64 v[60:61], v[58:59], 0, v[112:113]
	global_load_dwordx4 v[82:85], v[60:61], off
	v_add_u32_e32 v60, s0, v145
	v_ashrrev_i32_e32 v61, 31, v60
	v_lshlrev_b64 v[114:115], 12, v[60:61]
	v_lshl_add_u64 v[60:61], v[58:59], 0, v[114:115]
	global_load_dwordx4 v[86:89], v[60:61], off
	v_add_u32_e32 v60, s0, v146
	v_ashrrev_i32_e32 v61, 31, v60
	v_lshlrev_b64 v[116:117], 12, v[60:61]
	v_lshl_add_u64 v[60:61], v[58:59], 0, v[116:117]
	global_load_dwordx4 v[90:93], v[60:61], off
	v_add_u32_e32 v60, s0, v147
	v_ashrrev_i32_e32 v61, 31, v60
	v_lshlrev_b64 v[118:119], 12, v[60:61]
	v_lshl_add_u64 v[60:61], v[58:59], 0, v[118:119]
	global_load_dwordx4 v[178:181], v[60:61], off
	v_add_u32_e32 v60, s0, v148
	v_ashrrev_i32_e32 v61, 31, v60
	v_lshlrev_b64 v[120:121], 12, v[60:61]
	v_lshl_add_u64 v[58:59], v[58:59], 0, v[120:121]
	global_load_dwordx4 v[58:61], v[58:59], off
	s_barrier
; #define LAS __attribute__((address_space(3)))
; __device__ __forceinline__ void xattn_lds(const Ctx& C, const bf16* P, int cqoff, const bf16* MEMKV, const bf16* MEMVT, bf16* CAT, int ldc, int catoff, int u0, int ustride) {
;     ...
;             __syncthreads();
; #pragma unroll
;             for (int it = 0; it < 8; ++it) { const int idx = it * 512 + tid, row = idx >> 5, c16 = idx & 31; *(LAS v4u*)(Ls + row * KP + c16 * 16) = stg[it]; }
;             __syncthreads();
; #pragma unroll
;             for (int kt = 0; kt < 8; ++kt) {
; #pragma unroll
;                 for (int ks = 0; ks < 8; ++ks) { const bf16x8v kf = *(const LAS bf16x8v*)(Ls + (16 * kt + c) * KP + (32 * ks + 8 * g) * 2);
;                     s[8 * half + kt] = __builtin_amdgcn_mfma_f32_16x16x32_bf16(kf, qf[ks], s[8 * half + kt], 0, 0, 0); }
;                 asm volatile("" ::: "memory"); }
	s_waitcnt vmcnt(7)
	ds_write_b128 v150, v[66:69]
	s_waitcnt vmcnt(6)
	ds_write_b128 v151, v[74:77]
	s_waitcnt vmcnt(5)
	ds_write_b128 v152, v[78:81]
	s_waitcnt vmcnt(4)
	ds_write_b128 v153, v[82:85]
	s_waitcnt vmcnt(3)
	ds_write_b128 v154, v[86:89]
	s_waitcnt vmcnt(2)
	ds_write_b128 v155, v[90:93]
	s_waitcnt vmcnt(1)
	ds_write_b128 v156, v[178:181]
	s_waitcnt vmcnt(0)
	ds_write_b128 v157, v[58:61]
	s_waitcnt lgkmcnt(0)
	s_barrier
	ds_read_b128 v[58:61], v158
	ds_read_b128 v[66:69], v158 offset:64
	s_waitcnt lgkmcnt(1)
	v_mfma_f32_16x16x32_bf16 v[58:61], v[58:61], v[70:73], 0
	s_waitcnt lgkmcnt(0)
	v_mfma_f32_16x16x32_bf16 v[58:61], v[66:69], v[62:65], v[58:61]
	ds_read_b128 v[66:69], v158 offset:128
	s_waitcnt lgkmcnt(0)
	v_mfma_f32_16x16x32_bf16 v[58:61], v[66:69], v[54:57], v[58:61]
	ds_read_b128 v[66:69], v158 offset:192
	s_waitcnt lgkmcnt(0)
	v_mfma_f32_16x16x32_bf16 v[58:61], v[66:69], v[50:53], v[58:61]
	ds_read_b128 v[66:69], v158 offset:256
	s_waitcnt lgkmcnt(0)
	v_mfma_f32_16x16x32_bf16 v[58:61], v[66:69], v[46:49], v[58:61]
	ds_read_b128 v[66:69], v158 offset:320
	s_waitcnt lgkmcnt(0)
	v_mfma_f32_16x16x32_bf16 v[58:61], v[66:69], v[42:45], v[58:61]
	ds_read_b128 v[66:69], v158 offset:384
	s_waitcnt lgkmcnt(0)
	v_mfma_f32_16x16x32_bf16 v[58:61], v[66:69], v[38:41], v[58:61]
	ds_read_b128 v[66:69], v158 offset:448
	ds_read_b128 v[74:77], v158 offset:8512
	s_waitcnt lgkmcnt(1)
	v_mfma_f32_16x16x32_bf16 v[58:61], v[66:69], v[34:37], v[58:61]
	ds_read_b128 v[66:69], v158 offset:8448
	s_waitcnt lgkmcnt(0)
	v_mfma_f32_16x16x32_bf16 v[66:69], v[66:69], v[70:73], 0
	v_mfma_f32_16x16x32_bf16 v[66:69], v[74:77], v[62:65], v[66:69]
	ds_read_b128 v[74:77], v158 offset:8576
	s_waitcnt lgkmcnt(0)
	v_mfma_f32_16x16x32_bf16 v[66:69], v[74:77], v[54:57], v[66:69]
	ds_read_b128 v[74:77], v158 offset:8640
	s_waitcnt lgkmcnt(0)
	v_mfma_f32_16x16x32_bf16 v[66:69], v[74:77], v[50:53], v[66:69]
	ds_read_b128 v[74:77], v158 offset:8704
	s_waitcnt lgkmcnt(0)
	v_mfma_f32_16x16x32_bf16 v[66:69], v[74:77], v[46:49], v[66:69]
	ds_read_b128 v[74:77], v158 offset:8768
	s_waitcnt lgkmcnt(0)
	v_mfma_f32_16x16x32_bf16 v[66:69], v[74:77], v[42:45], v[66:69]
	ds_read_b128 v[74:77], v158 offset:8832
	s_waitcnt lgkmcnt(0)
	v_mfma_f32_16x16x32_bf16 v[66:69], v[74:77], v[38:41], v[66:69]
	ds_read_b128 v[74:77], v158 offset:8896
	ds_read_b128 v[78:81], v158 offset:16960
	s_waitcnt lgkmcnt(1)
	v_mfma_f32_16x16x32_bf16 v[74:77], v[74:77], v[34:37], v[66:69]
	s_nop 3
	ds_read_b128 v[66:69], v158 offset:16896
	s_waitcnt lgkmcnt(0)
	v_mfma_f32_16x16x32_bf16 v[66:69], v[66:69], v[70:73], 0
	v_mfma_f32_16x16x32_bf16 v[66:69], v[78:81], v[62:65], v[66:69]
	ds_read_b128 v[78:81], v158 offset:17024
	s_waitcnt lgkmcnt(0)
	v_mfma_f32_16x16x32_bf16 v[66:69], v[78:81], v[54:57], v[66:69]
	ds_read_b128 v[78:81], v158 offset:17088
	s_waitcnt lgkmcnt(0)
	v_mfma_f32_16x16x32_bf16 v[66:69], v[78:81], v[50:53], v[66:69]
	ds_read_b128 v[78:81], v158 offset:17152
	s_waitcnt lgkmcnt(0)
	v_mfma_f32_16x16x32_bf16 v[66:69], v[78:81], v[46:49], v[66:69]
	ds_read_b128 v[78:81], v158 offset:17216
	s_waitcnt lgkmcnt(0)
	v_mfma_f32_16x16x32_bf16 v[66:69], v[78:81], v[42:45], v[66:69]
	ds_read_b128 v[78:81], v158 offset:17280
	s_waitcnt lgkmcnt(0)
	v_mfma_f32_16x16x32_bf16 v[66:69], v[78:81], v[38:41], v[66:69]
	ds_read_b128 v[78:81], v158 offset:17344
	ds_read_b128 v[82:85], v158 offset:25408
	s_waitcnt lgkmcnt(1)
	v_mfma_f32_16x16x32_bf16 v[66:69], v[78:81], v[34:37], v[66:69]
	ds_read_b128 v[78:81], v158 offset:25344
	s_waitcnt lgkmcnt(0)
	v_mfma_f32_16x16x32_bf16 v[78:81], v[78:81], v[70:73], 0
	v_mfma_f32_16x16x32_bf16 v[78:81], v[82:85], v[62:65], v[78:81]
	ds_read_b128 v[82:85], v158 offset:25472
	s_waitcnt lgkmcnt(0)
	v_mfma_f32_16x16x32_bf16 v[78:81], v[82:85], v[54:57], v[78:81]
	ds_read_b128 v[82:85], v158 offset:25536
	s_waitcnt lgkmcnt(0)
	v_mfma_f32_16x16x32_bf16 v[78:81], v[82:85], v[50:53], v[78:81]
	ds_read_b128 v[82:85], v158 offset:25600
	s_waitcnt lgkmcnt(0)
	v_mfma_f32_16x16x32_bf16 v[78:81], v[82:85], v[46:49], v[78:81]
	ds_read_b128 v[82:85], v158 offset:25664
	s_waitcnt lgkmcnt(0)
	v_mfma_f32_16x16x32_bf16 v[78:81], v[82:85], v[42:45], v[78:81]
	ds_read_b128 v[82:85], v158 offset:25728
	s_waitcnt lgkmcnt(0)
	v_mfma_f32_16x16x32_bf16 v[78:81], v[82:85], v[38:41], v[78:81]
	ds_read_b128 v[82:85], v158 offset:25792
	ds_read_b128 v[86:89], v158 offset:33856
	s_waitcnt lgkmcnt(1)
	v_mfma_f32_16x16x32_bf16 v[82:85], v[82:85], v[34:37], v[78:81]
	s_nop 3
	ds_read_b128 v[78:81], v158 offset:33792
	s_waitcnt lgkmcnt(0)
	v_mfma_f32_16x16x32_bf16 v[78:81], v[78:81], v[70:73], 0
	v_mfma_f32_16x16x32_bf16 v[78:81], v[86:89], v[62:65], v[78:81]
	ds_read_b128 v[86:89], v158 offset:33920
	s_waitcnt lgkmcnt(0)
	v_mfma_f32_16x16x32_bf16 v[78:81], v[86:89], v[54:57], v[78:81]
	ds_read_b128 v[86:89], v158 offset:33984
	s_waitcnt lgkmcnt(0)
	v_mfma_f32_16x16x32_bf16 v[78:81], v[86:89], v[50:53], v[78:81]
	ds_read_b128 v[86:89], v158 offset:34048
	s_waitcnt lgkmcnt(0)
	v_mfma_f32_16x16x32_bf16 v[78:81], v[86:89], v[46:49], v[78:81]
	ds_read_b128 v[86:89], v158 offset:34112
	s_waitcnt lgkmcnt(0)
	v_mfma_f32_16x16x32_bf16 v[78:81], v[86:89], v[42:45], v[78:81]
	ds_read_b128 v[86:89], v158 offset:34176
	s_waitcnt lgkmcnt(0)
	v_mfma_f32_16x16x32_bf16 v[78:81], v[86:89], v[38:41], v[78:81]
	ds_read_b128 v[86:89], v158 offset:34240
	ds_read_b128 v[90:93], v158 offset:42304
	s_waitcnt lgkmcnt(1)
	v_mfma_f32_16x16x32_bf16 v[78:81], v[86:89], v[34:37], v[78:81]
	ds_read_b128 v[86:89], v158 offset:42240
	s_waitcnt lgkmcnt(0)
; #define LAS __attribute__((address_space(3)))
; __device__ __forceinline__ void xattn_lds(const Ctx& C, const bf16* P, int cqoff, const bf16* MEMKV, const bf16* MEMVT, bf16* CAT, int ldc, int catoff, int u0, int ustride) {
;     ...
;             for (int kt = 0; kt < 8; ++kt) {
; #pragma unroll
;                 for (int ks = 0; ks < 8; ++ks) { const bf16x8v kf = *(const LAS bf16x8v*)(Ls + (16 * kt + c) * KP + (32 * ks + 8 * g) * 2);
;                     s[8 * half + kt] = __builtin_amdgcn_mfma_f32_16x16x32_bf16(kf, qf[ks], s[8 * half + kt], 0, 0, 0); }
;                 asm volatile("" ::: "memory"); }
;         }
;         float m = -1e30f;
; #pragma unroll
;         for (int kt = 0; kt < 16; ++kt) m = fmaxf(fmaxf(m, fmaxf(s[kt][0], s[kt][1])), fmaxf(s[kt][2], s[kt][3]));
;         m = fmaxf(m, __shfl_xor(m, 16)); m = fmaxf(m, __shfl_xor(m, 32));
	v_mfma_f32_16x16x32_bf16 v[86:89], v[86:89], v[70:73], 0
	v_mfma_f32_16x16x32_bf16 v[86:89], v[90:93], v[62:65], v[86:89]
	ds_read_b128 v[90:93], v158 offset:42368
	s_waitcnt lgkmcnt(0)
	v_mfma_f32_16x16x32_bf16 v[86:89], v[90:93], v[54:57], v[86:89]
	ds_read_b128 v[90:93], v158 offset:42432
	s_waitcnt lgkmcnt(0)
	v_mfma_f32_16x16x32_bf16 v[86:89], v[90:93], v[50:53], v[86:89]
	ds_read_b128 v[90:93], v158 offset:42496
	s_waitcnt lgkmcnt(0)
	v_mfma_f32_16x16x32_bf16 v[86:89], v[90:93], v[46:49], v[86:89]
	ds_read_b128 v[90:93], v158 offset:42560
	s_waitcnt lgkmcnt(0)
	v_mfma_f32_16x16x32_bf16 v[86:89], v[90:93], v[42:45], v[86:89]
	ds_read_b128 v[90:93], v158 offset:42624
	s_waitcnt lgkmcnt(0)
	v_mfma_f32_16x16x32_bf16 v[86:89], v[90:93], v[38:41], v[86:89]
	ds_read_b128 v[90:93], v158 offset:42688
	ds_read_b128 v[178:181], v158 offset:50752
	s_waitcnt lgkmcnt(1)
	v_mfma_f32_16x16x32_bf16 v[90:93], v[90:93], v[34:37], v[86:89]
	s_nop 3
	ds_read_b128 v[86:89], v158 offset:50688
	s_waitcnt lgkmcnt(0)
	v_mfma_f32_16x16x32_bf16 v[86:89], v[86:89], v[70:73], 0
	v_mfma_f32_16x16x32_bf16 v[86:89], v[178:181], v[62:65], v[86:89]
	ds_read_b128 v[178:181], v158 offset:50816
	s_waitcnt lgkmcnt(0)
	v_mfma_f32_16x16x32_bf16 v[86:89], v[178:181], v[54:57], v[86:89]
	ds_read_b128 v[178:181], v158 offset:50880
	s_waitcnt lgkmcnt(0)
	v_mfma_f32_16x16x32_bf16 v[86:89], v[178:181], v[50:53], v[86:89]
	ds_read_b128 v[178:181], v158 offset:50944
	s_waitcnt lgkmcnt(0)
	v_mfma_f32_16x16x32_bf16 v[86:89], v[178:181], v[46:49], v[86:89]
	ds_read_b128 v[178:181], v158 offset:51008
	s_waitcnt lgkmcnt(0)
	v_mfma_f32_16x16x32_bf16 v[86:89], v[178:181], v[42:45], v[86:89]
	ds_read_b128 v[178:181], v158 offset:51072
	s_waitcnt lgkmcnt(0)
	v_mfma_f32_16x16x32_bf16 v[86:89], v[178:181], v[38:41], v[86:89]
	ds_read_b128 v[178:181], v158 offset:51136
	s_waitcnt lgkmcnt(0)
	v_mfma_f32_16x16x32_bf16 v[86:89], v[178:181], v[34:37], v[86:89]
	ds_read_b128 v[178:181], v158 offset:59136
	s_waitcnt lgkmcnt(0)
	v_mfma_f32_16x16x32_bf16 v[70:73], v[178:181], v[70:73], 0
	ds_read_b128 v[178:181], v158 offset:59200
	s_waitcnt lgkmcnt(0)
	v_mfma_f32_16x16x32_bf16 v[62:65], v[178:181], v[62:65], v[70:73]
	s_nop 4
	ds_read_b128 v[70:73], v158 offset:59264
	s_waitcnt lgkmcnt(0)
	v_mfma_f32_16x16x32_bf16 v[54:57], v[70:73], v[54:57], v[62:65]
	s_nop 2
	ds_read_b128 v[62:65], v158 offset:59328
	s_waitcnt lgkmcnt(0)
	v_mfma_f32_16x16x32_bf16 v[50:53], v[62:65], v[50:53], v[54:57]
	s_nop 2
	ds_read_b128 v[54:57], v158 offset:59392
	s_waitcnt lgkmcnt(0)
	v_mfma_f32_16x16x32_bf16 v[46:49], v[54:57], v[46:49], v[50:53]
	s_nop 2
	ds_read_b128 v[50:53], v158 offset:59456
	s_waitcnt lgkmcnt(0)
	v_mfma_f32_16x16x32_bf16 v[42:45], v[50:53], v[42:45], v[46:49]
	s_nop 2
	ds_read_b128 v[46:49], v158 offset:59520
	s_waitcnt lgkmcnt(0)
	v_mfma_f32_16x16x32_bf16 v[38:41], v[46:49], v[38:41], v[42:45]
	s_nop 2
	ds_read_b128 v[42:45], v158 offset:59584
	s_waitcnt lgkmcnt(0)
	v_mfma_f32_16x16x32_bf16 v[34:37], v[42:45], v[34:37], v[38:41]
	s_nop 2
	v_max_f32_e32 v38, v3, v3
	v_max_f32_e32 v39, v2, v2
	v_max_f32_e32 v38, v39, v38
	v_max_f32_e32 v39, v5, v5
	v_max_f32_e32 v40, v4, v4
	v_max_f32_e32 v39, v40, v39
	v_max3_f32 v38, v38, s21, v39
	v_max_f32_e32 v39, v11, v11
	v_max_f32_e32 v40, v10, v10
	v_max_f32_e32 v39, v40, v39
	v_max_f32_e32 v40, v13, v13
	v_max_f32_e32 v41, v12, v12
	v_max_f32_e32 v40, v41, v40
	v_max3_f32 v38, v38, v39, v40
	v_max_f32_e32 v39, v7, v7
	v_max_f32_e32 v40, v6, v6
	v_max_f32_e32 v39, v40, v39
	v_max_f32_e32 v40, v9, v9
	v_max_f32_e32 v41, v8, v8
	v_max_f32_e32 v40, v41, v40
	v_max3_f32 v38, v38, v39, v40
	v_max_f32_e32 v39, v19, v19
	v_max_f32_e32 v40, v18, v18
	v_max_f32_e32 v39, v40, v39
	v_max_f32_e32 v40, v21, v21
	v_max_f32_e32 v41, v20, v20
	v_max_f32_e32 v40, v41, v40
	v_max3_f32 v38, v38, v39, v40
	v_max_f32_e32 v39, v15, v15
	v_max_f32_e32 v40, v14, v14
	v_max_f32_e32 v39, v40, v39
	v_max_f32_e32 v40, v17, v17
	v_max_f32_e32 v41, v16, v16
	v_max_f32_e32 v40, v41, v40
	v_max3_f32 v38, v38, v39, v40
	v_max_f32_e32 v39, v27, v27
	v_max_f32_e32 v40, v26, v26
	v_max_f32_e32 v39, v40, v39
	v_max_f32_e32 v40, v29, v29
	v_max_f32_e32 v41, v28, v28
	v_max_f32_e32 v40, v41, v40
	v_max3_f32 v38, v38, v39, v40
	v_max_f32_e32 v39, v23, v23
	v_max_f32_e32 v40, v22, v22
	v_max_f32_e32 v39, v40, v39
	v_max_f32_e32 v40, v25, v25
	v_max_f32_e32 v41, v24, v24
	v_max_f32_e32 v40, v41, v40
	v_max3_f32 v38, v38, v39, v40
	v_max_f32_e32 v39, v31, v31
	v_max_f32_e32 v40, v30, v30
	v_max_f32_e32 v39, v40, v39
	v_max_f32_e32 v40, v33, v33
	v_max_f32_e32 v41, v32, v32
	v_max_f32_e32 v40, v41, v40
	v_max3_f32 v38, v38, v39, v40
	v_max_f32_e32 v39, v59, v59
	v_max_f32_e32 v40, v58, v58
	v_max_f32_e32 v39, v40, v39
	v_max_f32_e32 v40, v61, v61
	v_max_f32_e32 v41, v60, v60
	v_max_f32_e32 v40, v41, v40
	v_max3_f32 v38, v38, v39, v40
	v_max_f32_e32 v39, v75, v75
	v_max_f32_e32 v40, v74, v74
	v_max_f32_e32 v39, v40, v39
	v_max_f32_e32 v40, v77, v77
	v_max_f32_e32 v41, v76, v76
	v_max_f32_e32 v40, v41, v40
	v_max3_f32 v38, v38, v39, v40
	v_max_f32_e32 v39, v67, v67
	v_max_f32_e32 v40, v66, v66
	v_max_f32_e32 v39, v40, v39
	v_max_f32_e32 v40, v69, v69
	v_max_f32_e32 v41, v68, v68
	v_max_f32_e32 v40, v41, v40
	v_max3_f32 v38, v38, v39, v40
	v_max_f32_e32 v39, v83, v83
	v_max_f32_e32 v40, v82, v82
	v_max_f32_e32 v39, v40, v39
	v_max_f32_e32 v40, v85, v85
	v_max_f32_e32 v41, v84, v84
	v_max_f32_e32 v40, v41, v40
	v_max3_f32 v38, v38, v39, v40
	v_max_f32_e32 v39, v79, v79
	v_max_f32_e32 v40, v78, v78
	v_max_f32_e32 v39, v40, v39
	v_max_f32_e32 v40, v81, v81
	v_max_f32_e32 v41, v80, v80
	v_max_f32_e32 v40, v41, v40
	v_max3_f32 v38, v38, v39, v40
	v_max_f32_e32 v39, v91, v91
	v_max_f32_e32 v40, v90, v90
	v_max_f32_e32 v39, v40, v39
	v_max_f32_e32 v40, v93, v93
	v_max_f32_e32 v41, v92, v92
	v_max_f32_e32 v40, v41, v40
	v_max3_f32 v38, v38, v39, v40
	v_max_f32_e32 v39, v87, v87
	v_max_f32_e32 v40, v86, v86
	v_max_f32_e32 v39, v40, v39
	v_max_f32_e32 v40, v89, v89
	v_max_f32_e32 v41, v88, v88
	v_max_f32_e32 v40, v41, v40
	v_max3_f32 v38, v38, v39, v40
	v_max_f32_e32 v39, v35, v35
	v_max_f32_e32 v40, v34, v34
	v_max_f32_e32 v39, v40, v39
	v_max_f32_e32 v40, v37, v37
	v_max_f32_e32 v41, v36, v36
	v_max_f32_e32 v40, v41, v40
	v_max3_f32 v38, v38, v39, v40
	v_cndmask_b32_e32 v39, v159, v169, vcc
	v_lshlrev_b32_e32 v39, 2, v39
	ds_bpermute_b32 v40, v39, v38
	v_cmp_lt_i32_e32 vcc, v171, v170
	s_waitcnt lgkmcnt(0)
; __device__ __forceinline__ unsigned pk2(float lo, float hi) { return f2bf(lo) | (f2bf(hi) << 16); }
; __device__ __forceinline__ void xattn_lds(const Ctx& C, const bf16* P, int cqoff, const bf16* MEMKV, const bf16* MEMVT, bf16* CAT, int ldc, int catoff, int u0, int ustride) {
;     ...
;         m = fmaxf(m, __shfl_xor(m, 16)); m = fmaxf(m, __shfl_xor(m, 32));
;         float l = 0.f; const float sc = 0.0625f * 1.4426950408889634f;
;         bf16x8v pf[8];
; #pragma unroll
;         for (int kk = 0; kk < 8; ++kk) { float p[8];
; #pragma unroll
;             for (int r = 0; r < 4; ++r) { p[r] = __builtin_amdgcn_exp2f((s[2 * kk][r] - m) * sc); p[4 + r] = __builtin_amdgcn_exp2f((s[2 * kk + 1][r] - m) * sc); }
; #pragma unroll
;             for (int r = 0; r < 8; ++r) l += p[r];
;             v4u pw; pw.x = pk2(p[0], p[1]); pw.y = pk2(p[2], p[3]); pw.z = pk2(p[4], p[5]); pw.w = pk2(p[6], p[7]);
;             pf[kk] = __builtin_bit_cast(bf16x8v, pw); }
	v_max_f32_e32 v40, v40, v40
	v_max_f32_e32 v38, v38, v40
	v_cndmask_b32_e32 v40, v159, v171, vcc
	v_lshlrev_b32_e32 v40, 2, v40
	ds_bpermute_b32 v41, v40, v38
	s_waitcnt lgkmcnt(0)
	v_max_f32_e32 v41, v41, v41
	v_max_f32_e32 v38, v38, v41
	v_sub_f32_e32 v2, v2, v38
	v_mul_f32_e32 v2, 0x3db8aa3b, v2
	v_sub_f32_e32 v3, v3, v38
	v_exp_f32_e32 v2, v2
	v_mul_f32_e32 v3, 0x3db8aa3b, v3
	v_sub_f32_e32 v4, v4, v38
	v_exp_f32_e32 v3, v3
	v_mul_f32_e32 v4, 0x3db8aa3b, v4
	v_sub_f32_e32 v5, v5, v38
	v_sub_f32_e32 v10, v10, v38
	v_exp_f32_e32 v4, v4
	v_mul_f32_e32 v5, 0x3db8aa3b, v5
	v_mul_f32_e32 v10, 0x3db8aa3b, v10
	v_sub_f32_e32 v11, v11, v38
	v_exp_f32_e32 v5, v5
	v_exp_f32_e32 v10, v10
	v_mul_f32_e32 v11, 0x3db8aa3b, v11
	v_sub_f32_e32 v12, v12, v38
	v_sub_f32_e32 v13, v13, v38
	v_add_f32_e32 v41, 0, v2
	v_exp_f32_e32 v11, v11
	v_mul_f32_e32 v12, 0x3db8aa3b, v12
	v_mul_f32_e32 v13, 0x3db8aa3b, v13
	v_add_f32_e32 v41, v3, v41
	v_exp_f32_e32 v12, v12
	v_exp_f32_e32 v13, v13
	v_add_f32_e32 v41, v4, v41
	v_add_f32_e32 v41, v5, v41
	v_add_f32_e32 v41, v10, v41
	v_add_f32_e32 v41, v11, v41
	v_add_f32_e32 v41, v12, v41
	v_bfe_u32 v42, v13, 16, 1
	v_add_f32_e32 v41, v13, v41
	v_bfe_u32 v43, v11, 16, 1
	v_add3_u32 v13, v13, v42, s22
	v_bfe_u32 v42, v2, 16, 1
	v_bfe_u32 v45, v3, 16, 1
	v_add3_u32 v11, v11, v43, s22
	v_bfe_u32 v43, v4, 16, 1
	v_add3_u32 v2, v2, v42, s22
	v_bfe_u32 v44, v5, 16, 1
	v_add3_u32 v3, v3, v45, s22
	v_add3_u32 v4, v4, v43, s22
	v_lshrrev_b32_e32 v2, 16, v2
	v_add3_u32 v5, v5, v44, s22
	v_lshrrev_b32_e32 v4, 16, v4
	v_and_or_b32 v50, v3, s23, v2
	v_sub_f32_e32 v2, v6, v38
	v_and_or_b32 v51, v5, s23, v4
	v_mul_f32_e32 v2, 0x3db8aa3b, v2
	v_sub_f32_e32 v4, v7, v38
	v_exp_f32_e32 v2, v2
	v_mul_f32_e32 v4, 0x3db8aa3b, v4
	v_sub_f32_e32 v6, v8, v38
	v_bfe_u32 v44, v10, 16, 1
	v_exp_f32_e32 v4, v4
	v_mul_f32_e32 v6, 0x3db8aa3b, v6
	v_sub_f32_e32 v8, v9, v38
	v_add3_u32 v10, v10, v44, s22
	v_sub_f32_e32 v3, v18, v38
	v_exp_f32_e32 v6, v6
	v_mul_f32_e32 v8, 0x3db8aa3b, v8
	v_lshrrev_b32_e32 v10, 16, v10
	v_mul_f32_e32 v3, 0x3db8aa3b, v3
	v_sub_f32_e32 v5, v19, v38
	v_exp_f32_e32 v8, v8
	v_and_or_b32 v52, v11, s23, v10
	v_exp_f32_e32 v3, v3
	v_mul_f32_e32 v5, 0x3db8aa3b, v5
	v_sub_f32_e32 v7, v20, v38
	v_sub_f32_e32 v9, v21, v38
	v_add_f32_e32 v10, v2, v41
	v_exp_f32_e32 v5, v5
	v_mul_f32_e32 v7, 0x3db8aa3b, v7
	v_mul_f32_e32 v9, 0x3db8aa3b, v9
	v_add_f32_e32 v10, v4, v10
	v_exp_f32_e32 v7, v7
	v_exp_f32_e32 v9, v9
	v_add_f32_e32 v10, v6, v10
	v_add_f32_e32 v10, v8, v10
	v_add_f32_e32 v10, v3, v10
	v_bfe_u32 v45, v12, 16, 1
	v_add_f32_e32 v10, v5, v10
	v_add3_u32 v12, v12, v45, s22
	v_add_f32_e32 v10, v7, v10
	v_bfe_u32 v11, v9, 16, 1
	v_lshrrev_b32_e32 v12, 16, v12
	v_add_f32_e32 v10, v9, v10
	v_add3_u32 v9, v9, v11, s22
	v_bfe_u32 v11, v2, 16, 1
	v_and_or_b32 v53, v13, s23, v12
	v_bfe_u32 v12, v5, 16, 1
	v_bfe_u32 v18, v4, 16, 1
	v_add3_u32 v2, v2, v11, s22
	v_add3_u32 v4, v4, v18, s22
	v_add3_u32 v5, v5, v12, s22
	v_bfe_u32 v12, v6, 16, 1
	v_lshrrev_b32_e32 v2, 16, v2
	v_bfe_u32 v13, v8, 16, 1
	v_add3_u32 v6, v6, v12, s22
	v_and_or_b32 v54, v4, s23, v2
	v_sub_f32_e32 v2, v14, v38
	v_add3_u32 v8, v8, v13, s22
	v_bfe_u32 v13, v3, 16, 1
	v_lshrrev_b32_e32 v6, 16, v6
	v_mul_f32_e32 v2, 0x3db8aa3b, v2
	v_sub_f32_e32 v4, v15, v38
	v_add3_u32 v3, v3, v13, s22
	v_and_or_b32 v55, v8, s23, v6
	v_exp_f32_e32 v2, v2
	v_mul_f32_e32 v4, 0x3db8aa3b, v4
	v_sub_f32_e32 v6, v16, v38
	v_bfe_u32 v18, v7, 16, 1
	v_lshrrev_b32_e32 v3, 16, v3
	v_exp_f32_e32 v4, v4
	v_mul_f32_e32 v6, 0x3db8aa3b, v6
	v_sub_f32_e32 v8, v17, v38
	v_add3_u32 v7, v7, v18, s22
	v_and_or_b32 v56, v5, s23, v3
	v_sub_f32_e32 v3, v26, v38
	v_exp_f32_e32 v6, v6
	v_mul_f32_e32 v8, 0x3db8aa3b, v8
	v_lshrrev_b32_e32 v7, 16, v7
	v_mul_f32_e32 v3, 0x3db8aa3b, v3
	v_sub_f32_e32 v5, v27, v38
	v_exp_f32_e32 v8, v8
	v_and_or_b32 v57, v9, s23, v7
	v_exp_f32_e32 v3, v3
	v_mul_f32_e32 v5, 0x3db8aa3b, v5
	v_sub_f32_e32 v7, v28, v38
	v_sub_f32_e32 v9, v29, v38
	v_add_f32_e32 v10, v2, v10
	v_exp_f32_e32 v5, v5
	v_mul_f32_e32 v7, 0x3db8aa3b, v7
	v_mul_f32_e32 v9, 0x3db8aa3b, v9
	v_add_f32_e32 v10, v4, v10
	v_exp_f32_e32 v7, v7
	v_exp_f32_e32 v9, v9
	v_add_f32_e32 v10, v6, v10
	v_add_f32_e32 v10, v8, v10
	v_add_f32_e32 v10, v3, v10
	v_add_f32_e32 v10, v5, v10
	v_add_f32_e32 v10, v7, v10
	v_bfe_u32 v11, v9, 16, 1
	v_add_f32_e32 v10, v9, v10
	v_add3_u32 v9, v9, v11, s22
	v_bfe_u32 v11, v2, 16, 1
	v_bfe_u32 v12, v5, 16, 1
	v_bfe_u32 v14, v4, 16, 1
	v_add3_u32 v2, v2, v11, s22
	v_add3_u32 v4, v4, v14, s22
	v_add3_u32 v5, v5, v12, s22
	v_bfe_u32 v12, v6, 16, 1
	v_lshrrev_b32_e32 v2, 16, v2
	v_bfe_u32 v13, v8, 16, 1
	v_add3_u32 v6, v6, v12, s22
	v_and_or_b32 v42, v4, s23, v2
	v_sub_f32_e32 v2, v22, v38
	v_add3_u32 v8, v8, v13, s22
	v_bfe_u32 v13, v3, 16, 1
	v_lshrrev_b32_e32 v6, 16, v6
	v_mul_f32_e32 v2, 0x3db8aa3b, v2
	v_sub_f32_e32 v4, v23, v38
	v_add3_u32 v3, v3, v13, s22
	v_and_or_b32 v43, v8, s23, v6
	v_exp_f32_e32 v2, v2
	v_mul_f32_e32 v4, 0x3db8aa3b, v4
	v_sub_f32_e32 v6, v24, v38
	v_bfe_u32 v14, v7, 16, 1
	v_lshrrev_b32_e32 v3, 16, v3
	v_exp_f32_e32 v4, v4
	v_mul_f32_e32 v6, 0x3db8aa3b, v6
	v_sub_f32_e32 v8, v25, v38
	v_add3_u32 v7, v7, v14, s22
	v_and_or_b32 v44, v5, s23, v3
	v_sub_f32_e32 v3, v30, v38
	v_exp_f32_e32 v6, v6
	v_mul_f32_e32 v8, 0x3db8aa3b, v8
	v_lshrrev_b32_e32 v7, 16, v7
	v_mul_f32_e32 v3, 0x3db8aa3b, v3
	v_sub_f32_e32 v5, v31, v38
	v_exp_f32_e32 v8, v8
	v_and_or_b32 v45, v9, s23, v7
	v_exp_f32_e32 v3, v3
	v_mul_f32_e32 v5, 0x3db8aa3b, v5
	v_sub_f32_e32 v7, v32, v38
	v_sub_f32_e32 v9, v33, v38
	v_add_f32_e32 v10, v2, v10
	v_exp_f32_e32 v5, v5
	v_mul_f32_e32 v7, 0x3db8aa3b, v7
; __device__ __forceinline__ unsigned pk2(float lo, float hi) { return f2bf(lo) | (f2bf(hi) << 16); }
; __device__ __forceinline__ void xattn_lds(const Ctx& C, const bf16* P, int cqoff, const bf16* MEMKV, const bf16* MEMVT, bf16* CAT, int ldc, int catoff, int u0, int ustride) {
;     ...
; #pragma unroll
;         for (int kk = 0; kk < 8; ++kk) { float p[8];
; #pragma unroll
;             for (int r = 0; r < 4; ++r) { p[r] = __builtin_amdgcn_exp2f((s[2 * kk][r] - m) * sc); p[4 + r] = __builtin_amdgcn_exp2f((s[2 * kk + 1][r] - m) * sc); }
; #pragma unroll
;             for (int r = 0; r < 8; ++r) l += p[r];
;             v4u pw; pw.x = pk2(p[0], p[1]); pw.y = pk2(p[2], p[3]); pw.z = pk2(p[4], p[5]); pw.w = pk2(p[6], p[7]);
;             pf[kk] = __builtin_bit_cast(bf16x8v, pw); }
	v_mul_f32_e32 v9, 0x3db8aa3b, v9
	v_add_f32_e32 v10, v4, v10
	v_exp_f32_e32 v7, v7
	v_exp_f32_e32 v9, v9
	v_add_f32_e32 v10, v6, v10
	v_add_f32_e32 v10, v8, v10
	v_add_f32_e32 v10, v3, v10
	v_add_f32_e32 v10, v5, v10
	v_add_f32_e32 v10, v7, v10
	v_bfe_u32 v11, v9, 16, 1
	v_add_f32_e32 v10, v9, v10
	v_add3_u32 v9, v9, v11, s22
	v_bfe_u32 v11, v2, 16, 1
	v_bfe_u32 v12, v5, 16, 1
	v_bfe_u32 v14, v4, 16, 1
	v_add3_u32 v2, v2, v11, s22
	v_add3_u32 v4, v4, v14, s22
	v_add3_u32 v5, v5, v12, s22
	v_bfe_u32 v12, v6, 16, 1
	v_lshrrev_b32_e32 v2, 16, v2
	v_bfe_u32 v13, v8, 16, 1
	v_add3_u32 v6, v6, v12, s22
	v_and_or_b32 v46, v4, s23, v2
	v_sub_f32_e32 v2, v58, v38
	v_add3_u32 v8, v8, v13, s22
	v_bfe_u32 v13, v3, 16, 1
	v_bfe_u32 v14, v7, 16, 1
	v_lshrrev_b32_e32 v6, 16, v6
	v_mul_f32_e32 v2, 0x3db8aa3b, v2
	v_sub_f32_e32 v4, v59, v38
	v_add3_u32 v7, v7, v14, s22
	v_add3_u32 v3, v3, v13, s22
	v_and_or_b32 v47, v8, s23, v6
	v_exp_f32_e32 v2, v2
	v_mul_f32_e32 v4, 0x3db8aa3b, v4
	v_sub_f32_e32 v6, v60, v38
	v_lshrrev_b32_e32 v3, 16, v3
	v_lshrrev_b32_e32 v7, 16, v7
	v_exp_f32_e32 v4, v4
	v_mul_f32_e32 v6, 0x3db8aa3b, v6
	v_sub_f32_e32 v8, v61, v38
	v_and_or_b32 v49, v9, s23, v7
	v_and_or_b32 v48, v5, s23, v3
	v_sub_f32_e32 v3, v74, v38
	v_sub_f32_e32 v5, v75, v38
	v_exp_f32_e32 v6, v6
	v_mul_f32_e32 v8, 0x3db8aa3b, v8
	v_sub_f32_e32 v9, v77, v38
	v_mul_f32_e32 v3, 0x3db8aa3b, v3
	v_mul_f32_e32 v5, 0x3db8aa3b, v5
	v_exp_f32_e32 v8, v8
	v_mul_f32_e32 v9, 0x3db8aa3b, v9
	v_exp_f32_e32 v3, v3
	v_exp_f32_e32 v5, v5
	v_exp_f32_e32 v9, v9
	v_add_f32_e32 v10, v2, v10
	v_add_f32_e32 v10, v4, v10
	v_sub_f32_e32 v7, v76, v38
	v_add_f32_e32 v10, v6, v10
	v_mul_f32_e32 v7, 0x3db8aa3b, v7
	v_add_f32_e32 v10, v8, v10
	v_exp_f32_e32 v7, v7
	v_add_f32_e32 v10, v3, v10
	v_bfe_u32 v11, v9, 16, 1
	v_bfe_u32 v12, v5, 16, 1
	v_bfe_u32 v14, v4, 16, 1
	v_add_f32_e32 v10, v5, v10
	v_add3_u32 v14, v4, v14, s22
	v_add3_u32 v4, v5, v12, s22
	v_add3_u32 v5, v9, v11, s22
	v_bfe_u32 v11, v6, 16, 1
	v_bfe_u32 v12, v3, 16, 1
	v_bfe_u32 v13, v8, 16, 1
	v_add3_u32 v3, v3, v12, s22
	v_add3_u32 v6, v6, v11, s22
	v_add3_u32 v8, v8, v13, s22
	v_lshrrev_b32_e32 v6, 16, v6
	v_lshrrev_b32_e32 v3, 16, v3
	v_add_f32_e32 v10, v7, v10
	v_and_or_b32 v4, v4, s23, v3
	v_and_or_b32 v3, v8, s23, v6
	v_sub_f32_e32 v6, v66, v38
	v_add_f32_e32 v10, v9, v10
	v_bfe_u32 v9, v2, 16, 1
	v_bfe_u32 v13, v7, 16, 1
	v_mul_f32_e32 v6, 0x3db8aa3b, v6
	v_sub_f32_e32 v8, v67, v38
	v_add3_u32 v7, v7, v13, s22
	v_add3_u32 v2, v2, v9, s22
	v_exp_f32_e32 v6, v6
	v_mul_f32_e32 v8, 0x3db8aa3b, v8
	v_sub_f32_e32 v11, v68, v38
	v_lshrrev_b32_e32 v2, 16, v2
	v_lshrrev_b32_e32 v7, 16, v7
	v_exp_f32_e32 v8, v8
	v_mul_f32_e32 v11, 0x3db8aa3b, v11
	v_sub_f32_e32 v13, v69, v38
	v_and_or_b32 v5, v5, s23, v7
	v_and_or_b32 v2, v14, s23, v2
	v_sub_f32_e32 v7, v82, v38
	v_sub_f32_e32 v9, v83, v38
	v_exp_f32_e32 v11, v11
	v_mul_f32_e32 v13, 0x3db8aa3b, v13
	v_sub_f32_e32 v14, v85, v38
	v_mul_f32_e32 v7, 0x3db8aa3b, v7
	v_mul_f32_e32 v9, 0x3db8aa3b, v9
	v_exp_f32_e32 v13, v13
	v_mul_f32_e32 v14, 0x3db8aa3b, v14
	v_exp_f32_e32 v7, v7
	v_exp_f32_e32 v9, v9
	v_exp_f32_e32 v14, v14
	v_add_f32_e32 v10, v6, v10
	v_add_f32_e32 v10, v8, v10
	v_add_f32_e32 v10, v11, v10
	v_sub_f32_e32 v12, v84, v38
	v_add_f32_e32 v10, v13, v10
	v_mul_f32_e32 v12, 0x3db8aa3b, v12
	v_add_f32_e32 v10, v7, v10
	v_bfe_u32 v15, v14, 16, 1
	v_bfe_u32 v16, v9, 16, 1
	v_bfe_u32 v18, v8, 16, 1
	v_exp_f32_e32 v12, v12
	v_add_f32_e32 v10, v9, v10
	v_add3_u32 v18, v8, v18, s22
	v_add3_u32 v8, v9, v16, s22
	v_add3_u32 v9, v14, v15, s22
	v_bfe_u32 v15, v11, 16, 1
	v_bfe_u32 v16, v7, 16, 1
	v_bfe_u32 v17, v13, 16, 1
	v_add3_u32 v7, v7, v16, s22
	v_add3_u32 v11, v11, v15, s22
	v_add3_u32 v13, v13, v17, s22
	v_lshrrev_b32_e32 v11, 16, v11
	v_lshrrev_b32_e32 v7, 16, v7
	v_and_or_b32 v8, v8, s23, v7
	v_and_or_b32 v7, v13, s23, v11
	v_sub_f32_e32 v11, v78, v38
	v_bfe_u32 v17, v12, 16, 1
	v_mul_f32_e32 v11, 0x3db8aa3b, v11
	v_sub_f32_e32 v13, v79, v38
	v_add_f32_e32 v10, v12, v10
	v_add3_u32 v12, v12, v17, s22
	v_exp_f32_e32 v11, v11
	v_mul_f32_e32 v13, 0x3db8aa3b, v13
	v_sub_f32_e32 v15, v80, v38
	v_add_f32_e32 v10, v14, v10
	v_bfe_u32 v14, v6, 16, 1
	v_lshrrev_b32_e32 v12, 16, v12
	v_exp_f32_e32 v13, v13
	v_mul_f32_e32 v15, 0x3db8aa3b, v15
	v_sub_f32_e32 v17, v81, v38
	v_add3_u32 v6, v6, v14, s22
	v_and_or_b32 v9, v9, s23, v12
	v_sub_f32_e32 v12, v90, v38
	v_sub_f32_e32 v14, v91, v38
	v_exp_f32_e32 v15, v15
	v_mul_f32_e32 v17, 0x3db8aa3b, v17
	v_mul_f32_e32 v12, 0x3db8aa3b, v12
	v_mul_f32_e32 v14, 0x3db8aa3b, v14
	v_exp_f32_e32 v17, v17
	v_lshrrev_b32_e32 v6, 16, v6
	v_exp_f32_e32 v12, v12
	v_exp_f32_e32 v14, v14
	v_sub_f32_e32 v16, v92, v38
	v_add_f32_e32 v10, v11, v10
	v_and_or_b32 v6, v18, s23, v6
	v_mul_f32_e32 v16, 0x3db8aa3b, v16
	v_sub_f32_e32 v18, v93, v38
	v_add_f32_e32 v10, v13, v10
	v_exp_f32_e32 v16, v16
	v_mul_f32_e32 v18, 0x3db8aa3b, v18
	v_add_f32_e32 v10, v15, v10
	v_exp_f32_e32 v18, v18
	v_add_f32_e32 v10, v17, v10
	v_add_f32_e32 v10, v12, v10
	v_bfe_u32 v20, v14, 16, 1
	v_add_f32_e32 v10, v14, v10
	v_add3_u32 v14, v14, v20, s22
	v_bfe_u32 v20, v12, 16, 1
	v_add_f32_e32 v10, v16, v10
	v_bfe_u32 v21, v17, 16, 1
	v_bfe_u32 v22, v13, 16, 1
	v_add3_u32 v12, v12, v20, s22
	v_add_f32_e32 v19, v18, v10
	v_bfe_u32 v10, v18, 16, 1
	v_add3_u32 v22, v13, v22, s22
	v_add3_u32 v17, v17, v21, s22
	v_bfe_u32 v13, v11, 16, 1
	v_bfe_u32 v21, v16, 16, 1
	v_lshrrev_b32_e32 v12, 16, v12
	v_add3_u32 v10, v18, v10, s22
	v_bfe_u32 v18, v15, 16, 1
	v_add3_u32 v16, v16, v21, s22
	v_add3_u32 v11, v11, v13, s22
	v_and_or_b32 v12, v14, s23, v12
	v_sub_f32_e32 v14, v86, v38
; #define LAS __attribute__((address_space(3)))
; __device__ __forceinline__ unsigned pk2(float lo, float hi) { return f2bf(lo) | (f2bf(hi) << 16); }
; __device__ __forceinline__ void xattn_lds(const Ctx& C, const bf16* P, int cqoff, const bf16* MEMKV, const bf16* MEMVT, bf16* CAT, int ldc, int catoff, int u0, int ustride) {
;     ...
;         for (int kk = 0; kk < 8; ++kk) { float p[8];
; #pragma unroll
;             for (int r = 0; r < 4; ++r) { p[r] = __builtin_amdgcn_exp2f((s[2 * kk][r] - m) * sc); p[4 + r] = __builtin_amdgcn_exp2f((s[2 * kk + 1][r] - m) * sc); }
; #pragma unroll
;             for (int r = 0; r < 8; ++r) l += p[r];
;             v4u pw; pw.x = pk2(p[0], p[1]); pw.y = pk2(p[2], p[3]); pw.z = pk2(p[4], p[5]); pw.w = pk2(p[6], p[7]);
;             pf[kk] = __builtin_bit_cast(bf16x8v, pw); }
;         l += __shfl_xor(l, 16); l += __shfl_xor(l, 32);
;         const float inv = 1.f / l;
;         f32x4 o[16];
; #pragma unroll
;         for (int dt = 0; dt < 16; ++dt) o[dt] = (f32x4){0.f, 0.f, 0.f, 0.f};
; #pragma unroll
;         for (int half = 0; half < 2; ++half) {
;             v4u stg[8];
; #pragma unroll
;             for (int it = 0; it < 8; ++it) { const int idx = it * 512 + tid, key = idx >> 5, d8 = idx & 31;
;                 stg[it] = *(const v4u*)(MEMKV + (size_t)(b * 256 + half * 128 + key) * 2048 + 1024 + xh * 256 + d8 * 8); }
;             __syncthreads();
; #pragma unroll
;             for (int it = 0; it < 8; ++it) { const int idx = it * 512 + tid, key = idx >> 5, d8 = idx & 31;
; #pragma unroll
;                 for (int e = 0; e < 8; ++e) { const unsigned wv = stg[it][e >> 1]; *(LAS unsigned short*)(Ls + (8 * d8 + e) * VP + key * 2) = (unsigned short)((e & 1) ? (wv >> 16) : (wv & 0xffffu)); } }
;             __syncthreads();
	v_add3_u32 v15, v15, v18, s22
	v_lshrrev_b32_e32 v18, 16, v11
	v_lshrrev_b32_e32 v13, 16, v16
	v_mul_f32_e32 v14, 0x3db8aa3b, v14
	v_sub_f32_e32 v16, v87, v38
	v_and_or_b32 v13, v10, s23, v13
	v_and_or_b32 v10, v22, s23, v18
	v_exp_f32_e32 v14, v14
	v_mul_f32_e32 v16, 0x3db8aa3b, v16
	v_sub_f32_e32 v18, v88, v38
	v_lshrrev_b32_e32 v11, 16, v15
	v_exp_f32_e32 v16, v16
	v_mul_f32_e32 v18, 0x3db8aa3b, v18
	v_sub_f32_e32 v21, v89, v38
	v_and_or_b32 v11, v17, s23, v11
	v_sub_f32_e32 v15, v34, v38
	v_sub_f32_e32 v17, v35, v38
	v_exp_f32_e32 v18, v18
	v_mul_f32_e32 v21, 0x3db8aa3b, v21
	v_sub_f32_e32 v22, v37, v38
	v_mul_f32_e32 v15, 0x3db8aa3b, v15
	v_mul_f32_e32 v17, 0x3db8aa3b, v17
	v_sub_f32_e32 v20, v36, v38
	v_exp_f32_e32 v21, v21
	v_mul_f32_e32 v22, 0x3db8aa3b, v22
	v_exp_f32_e32 v15, v15
	v_exp_f32_e32 v17, v17
	v_mul_f32_e32 v20, 0x3db8aa3b, v20
	v_exp_f32_e32 v22, v22
	v_add_f32_e32 v19, v14, v19
	v_exp_f32_e32 v20, v20
	v_add_f32_e32 v19, v16, v19
	v_add_f32_e32 v19, v18, v19
	v_add_f32_e32 v19, v21, v19
	v_add_f32_e32 v19, v15, v19
	v_bfe_u32 v23, v22, 16, 1
	v_bfe_u32 v24, v17, 16, 1
	v_bfe_u32 v25, v21, 16, 1
	v_bfe_u32 v26, v16, 16, 1
	v_add_f32_e32 v19, v17, v19
	v_add3_u32 v26, v16, v26, s22
	v_add3_u32 v21, v21, v25, s22
	v_add3_u32 v16, v17, v24, s22
	v_add3_u32 v17, v22, v23, s22
	v_bfe_u32 v23, v18, 16, 1
	v_bfe_u32 v24, v15, 16, 1
	v_bfe_u32 v25, v20, 16, 1
	v_add_f32_e32 v19, v20, v19
	v_add3_u32 v20, v20, v25, s22
	v_add3_u32 v15, v15, v24, s22
	v_add3_u32 v18, v18, v23, s22
	v_lshrrev_b32_e32 v18, 16, v18
	v_lshrrev_b32_e32 v15, 16, v15
	v_lshrrev_b32_e32 v20, 16, v20
	v_add_f32_e32 v19, v22, v19
	v_and_or_b32 v17, v17, s23, v20
	v_and_or_b32 v16, v16, s23, v15
	v_and_or_b32 v15, v21, s23, v18
	v_and_b32_e32 v230, 0x7f, v0
	v_lshrrev_b32_e32 v231, 5, v0
	v_sub_u32_e32 v230, v230, v231
	v_lshlrev_b32_e32 v230, 12, v230
	v_lshrrev_b32_e32 v234, 7, v0
	v_lshl_add_u32 v230, v234, 4, v230
	v_ashrrev_i32_e32 v231, 31, v230
	v_lshl_add_u64 v[232:233], s[6:7], 0, v[122:123]
	v_lshl_add_u64 v[232:233], v[232:233], 0, s[10:11]
	v_lshl_add_u64 v[232:233], v[232:233], 0, v[230:231]
	v_and_b32_e32 v235, 0x7f, v0
	v_mul_u32_u24_e32 v236, 0x880, v234
	v_lshl_add_u32 v236, v235, 1, v236
	v_lshl_add_u64 v[20:21], s[6:7], 0, v[124:125]
	ds_bpermute_b32 v18, v39, v19
	v_lshl_add_u64 v[20:21], v[20:21], 0, s[10:11]
	v_lshl_add_u64 v[30:31], v[20:21], 0, v[100:101]
	v_lshl_add_u64 v[20:21], s[6:7], 0, v[126:127]
	v_lshl_add_u64 v[20:21], v[20:21], 0, s[10:11]
	v_lshl_add_u64 v[32:33], v[20:21], 0, v[100:101]
	v_lshl_add_u64 v[20:21], s[6:7], 0, v[128:129]
	v_lshl_add_u64 v[20:21], v[20:21], 0, s[10:11]
	s_waitcnt lgkmcnt(0)
	v_add_f32_e32 v18, v19, v18
	v_lshl_add_u64 v[34:35], v[20:21], 0, v[100:101]
	v_lshl_add_u64 v[20:21], s[6:7], 0, v[130:131]
	ds_bpermute_b32 v19, v40, v18
	v_lshl_add_u64 v[20:21], v[20:21], 0, s[10:11]
	v_lshl_add_u64 v[36:37], v[20:21], 0, v[100:101]
	v_lshl_add_u64 v[20:21], s[6:7], 0, v[132:133]
	v_lshl_add_u64 v[20:21], v[20:21], 0, s[10:11]
	v_lshl_add_u64 v[38:39], v[20:21], 0, v[100:101]
	v_lshl_add_u64 v[20:21], s[6:7], 0, v[134:135]
	v_lshl_add_u64 v[20:21], v[20:21], 0, s[10:11]
	v_bfe_u32 v22, v14, 16, 1
	s_waitcnt lgkmcnt(0)
	v_add_f32_e32 v177, v18, v19
	v_lshl_add_u64 v[18:19], s[6:7], 0, v[122:123]
	v_lshl_add_u64 v[58:59], v[20:21], 0, v[100:101]
	v_lshl_add_u64 v[20:21], s[6:7], 0, v[136:137]
	v_add3_u32 v14, v14, v22, s22
	v_lshl_add_u64 v[18:19], v[18:19], 0, s[10:11]
	v_lshl_add_u64 v[20:21], v[20:21], 0, s[10:11]
	v_lshrrev_b32_e32 v14, 16, v14
	v_lshl_add_u64 v[18:19], v[18:19], 0, v[100:101]
	v_lshl_add_u64 v[62:63], v[20:21], 0, v[100:101]
	v_and_or_b32 v14, v26, s23, v14
	global_load_dwordx4 v[18:21], v[232:233], off offset:2048
	s_nop 0
	global_load_dwordx4 v[22:25], v[232:233], off offset:2112
	global_load_dwordx4 v[26:29], v[232:233], off offset:2176
	s_nop 0
	global_load_dwordx4 v[30:33], v[232:233], off offset:2240
	s_nop 0
	global_load_dwordx4 v[34:37], v[232:233], off offset:2304
	s_nop 0
	global_load_dwordx4 v[38:41], v[232:233], off offset:2368
	s_nop 0
	global_load_dwordx4 v[58:61], v[232:233], off offset:2432
	s_nop 0
	global_load_dwordx4 v[62:65], v[232:233], off offset:2496
	s_barrier
	s_waitcnt vmcnt(7)
	ds_write_b16 v236, v18 offset:0
	ds_write_b16_d16_hi v236, v18 offset:272
	ds_write_b16 v236, v19 offset:544
	ds_write_b16_d16_hi v236, v19 offset:816
	ds_write_b16 v236, v20 offset:1088
	ds_write_b16_d16_hi v236, v20 offset:1360
	ds_write_b16 v236, v21 offset:1632
	ds_write_b16_d16_hi v236, v21 offset:1904
	s_waitcnt vmcnt(6)
	ds_write_b16 v236, v22 offset:8704
	ds_write_b16_d16_hi v236, v22 offset:8976
	ds_write_b16 v236, v23 offset:9248
	ds_write_b16_d16_hi v236, v23 offset:9520
	ds_write_b16 v236, v24 offset:9792
	ds_write_b16_d16_hi v236, v24 offset:10064
	ds_write_b16 v236, v25 offset:10336
	ds_write_b16_d16_hi v236, v25 offset:10608
	s_waitcnt vmcnt(5)
	ds_write_b16 v236, v26 offset:17408
	ds_write_b16_d16_hi v236, v26 offset:17680
	ds_write_b16 v236, v27 offset:17952
	ds_write_b16_d16_hi v236, v27 offset:18224
	ds_write_b16 v236, v28 offset:18496
	ds_write_b16_d16_hi v236, v28 offset:18768
	ds_write_b16 v236, v29 offset:19040
	ds_write_b16_d16_hi v236, v29 offset:19312
	s_waitcnt vmcnt(4)
	ds_write_b16 v236, v30 offset:26112
	ds_write_b16_d16_hi v236, v30 offset:26384
	ds_write_b16 v236, v31 offset:26656
	ds_write_b16_d16_hi v236, v31 offset:26928
	ds_write_b16 v236, v32 offset:27200
	ds_write_b16_d16_hi v236, v32 offset:27472
	ds_write_b16 v236, v33 offset:27744
	ds_write_b16_d16_hi v236, v33 offset:28016
	s_waitcnt vmcnt(3)
	ds_write_b16 v236, v34 offset:34816
	ds_write_b16_d16_hi v236, v34 offset:35088
	ds_write_b16 v236, v35 offset:35360
	ds_write_b16_d16_hi v236, v35 offset:35632
	ds_write_b16 v236, v36 offset:35904
	ds_write_b16_d16_hi v236, v36 offset:36176
	ds_write_b16 v236, v37 offset:36448
	ds_write_b16_d16_hi v236, v37 offset:36720
	s_waitcnt vmcnt(2)
	ds_write_b16 v236, v38 offset:43520
	ds_write_b16_d16_hi v236, v38 offset:43792
	ds_write_b16 v236, v39 offset:44064
	ds_write_b16_d16_hi v236, v39 offset:44336
	ds_write_b16 v236, v40 offset:44608
	ds_write_b16_d16_hi v236, v40 offset:44880
	ds_write_b16 v236, v41 offset:45152
	ds_write_b16_d16_hi v236, v41 offset:45424
	s_waitcnt vmcnt(1)
	ds_write_b16 v236, v58 offset:52224
	ds_write_b16_d16_hi v236, v58 offset:52496
	ds_write_b16 v236, v59 offset:52768
	ds_write_b16_d16_hi v236, v59 offset:53040
	ds_write_b16 v236, v60 offset:53312
	ds_write_b16_d16_hi v236, v60 offset:53584
	ds_write_b16 v236, v61 offset:53856
	ds_write_b16_d16_hi v236, v61 offset:54128
	s_waitcnt vmcnt(0)
	ds_write_b16 v236, v62 offset:60928
	ds_write_b16_d16_hi v236, v62 offset:61200
	ds_write_b16 v236, v63 offset:61472
	ds_write_b16_d16_hi v236, v63 offset:61744
	ds_write_b16 v236, v64 offset:62016
	ds_write_b16_d16_hi v236, v64 offset:62288
	ds_write_b16 v236, v65 offset:62560
	ds_write_b16_d16_hi v236, v65 offset:62832
	s_waitcnt lgkmcnt(0)
	s_barrier
; #define LAS __attribute__((address_space(3)))
; __device__ __forceinline__ void xattn_lds(const Ctx& C, const bf16* P, int cqoff, const bf16* MEMKV, const bf16* MEMVT, bf16* CAT, int ldc, int catoff, int u0, int ustride) {
;     ...
; #pragma unroll
;             for (int dt = 0; dt < 16; ++dt) {
; #pragma unroll
;                 for (int kk = 0; kk < 4; ++kk) { const LAS unsigned char* vp = Ls + (16 * dt + c) * VP + (32 * kk + 4 * g) * 2;
;                     const v2u lo = *(const LAS v2u*)vp, hi = *(const LAS v2u*)(vp + 32);
;                     v4u vw; vw.x = lo.x; vw.y = lo.y; vw.z = hi.x; vw.w = hi.y;
;                     o[dt] = __builtin_amdgcn_mfma_f32_16x16x32_bf16(__builtin_bit_cast(bf16x8v, vw), pf[4 * half + kk], o[dt], 0, 0, 0); }
;                 if (dt & 1) asm volatile("" ::: "memory"); }
	ds_read2_b64 v[18:21], v149 offset1:4
	ds_read2_b64 v[22:25], v149 offset0:8 offset1:12
	s_waitcnt lgkmcnt(1)
	v_mfma_f32_16x16x32_bf16 v[18:21], v[18:21], v[50:53], 0
	v_add_u32_e32 v122, 0x5000, v168
	v_add_u32_e32 v123, 0x6000, v168
	v_add_u32_e32 v124, 0x8800, v149
	s_waitcnt lgkmcnt(0)
	v_mfma_f32_16x16x32_bf16 v[18:21], v[22:25], v[54:57], v[18:21]
	ds_read2_b64 v[22:25], v149 offset0:16 offset1:20
	v_add_u32_e32 v125, 0x9800, v149
	v_add_u32_e32 v131, 0xa800, v149
	s_waitcnt lgkmcnt(0)
	v_mfma_f32_16x16x32_bf16 v[18:21], v[22:25], v[42:45], v[18:21]
	ds_read2_b64 v[22:25], v149 offset0:24 offset1:28
	v_add_u32_e32 v130, 0xb800, v149
	v_add_u32_e32 v129, 0xc800, v149
	s_waitcnt lgkmcnt(0)
	v_mfma_f32_16x16x32_bf16 v[38:41], v[22:25], v[46:49], v[18:21]
	s_nop 2
	ds_read2_b64 v[18:21], v168 offset1:4
	ds_read2_b64 v[22:25], v168 offset0:8 offset1:12
	v_add_u32_e32 v128, 0xd800, v149
	s_waitcnt lgkmcnt(1)
	v_mfma_f32_16x16x32_bf16 v[18:21], v[18:21], v[50:53], 0
	v_add_u32_e32 v127, 0xe800, v149
	v_add_u32_e32 v126, 0xf800, v149
	s_waitcnt lgkmcnt(0)
	v_mfma_f32_16x16x32_bf16 v[18:21], v[22:25], v[54:57], v[18:21]
	ds_read2_b64 v[22:25], v168 offset0:16 offset1:20
	s_waitcnt lgkmcnt(0)
	v_mfma_f32_16x16x32_bf16 v[18:21], v[22:25], v[42:45], v[18:21]
	ds_read2_b64 v[22:25], v168 offset0:24 offset1:28
	s_waitcnt lgkmcnt(0)
	v_mfma_f32_16x16x32_bf16 v[34:37], v[22:25], v[46:49], v[18:21]
	s_nop 4
	ds_read2_b64 v[18:21], v172 offset0:32 offset1:36
	ds_read2_b64 v[22:25], v172 offset0:40 offset1:44
	s_waitcnt lgkmcnt(1)
	v_mfma_f32_16x16x32_bf16 v[18:21], v[18:21], v[50:53], 0
	s_waitcnt lgkmcnt(0)
	v_mfma_f32_16x16x32_bf16 v[18:21], v[22:25], v[54:57], v[18:21]
	ds_read2_b64 v[22:25], v172 offset0:48 offset1:52
	s_waitcnt lgkmcnt(0)
	v_mfma_f32_16x16x32_bf16 v[18:21], v[22:25], v[42:45], v[18:21]
	ds_read2_b64 v[22:25], v172 offset0:56 offset1:60
	s_waitcnt lgkmcnt(0)
	v_mfma_f32_16x16x32_bf16 v[30:33], v[22:25], v[46:49], v[18:21]
	s_nop 4
	ds_read2_b64 v[18:21], v173 offset0:64 offset1:68
	ds_read2_b64 v[22:25], v173 offset0:72 offset1:76
	s_waitcnt lgkmcnt(1)
	v_mfma_f32_16x16x32_bf16 v[18:21], v[18:21], v[50:53], 0
	s_waitcnt lgkmcnt(0)
	v_mfma_f32_16x16x32_bf16 v[18:21], v[22:25], v[54:57], v[18:21]
	ds_read2_b64 v[22:25], v173 offset0:80 offset1:84
	s_waitcnt lgkmcnt(0)
	v_mfma_f32_16x16x32_bf16 v[18:21], v[22:25], v[42:45], v[18:21]
	ds_read2_b64 v[22:25], v173 offset0:88 offset1:92
	ds_read2_b64 v[58:61], v175 offset0:136 offset1:140
	s_waitcnt lgkmcnt(1)
	v_mfma_f32_16x16x32_bf16 v[26:29], v[22:25], v[46:49], v[18:21]
	s_nop 3
	ds_read2_b64 v[18:21], v174 offset0:96 offset1:100
	ds_read2_b64 v[22:25], v174 offset0:104 offset1:108
	s_waitcnt lgkmcnt(1)
	v_mfma_f32_16x16x32_bf16 v[18:21], v[18:21], v[50:53], 0
	s_waitcnt lgkmcnt(0)
	v_mfma_f32_16x16x32_bf16 v[18:21], v[22:25], v[54:57], v[18:21]
	ds_read2_b64 v[22:25], v174 offset0:112 offset1:116
	s_waitcnt lgkmcnt(0)
	v_mfma_f32_16x16x32_bf16 v[18:21], v[22:25], v[42:45], v[18:21]
	ds_read2_b64 v[22:25], v174 offset0:120 offset1:124
	s_waitcnt lgkmcnt(0)
	v_mfma_f32_16x16x32_bf16 v[22:25], v[22:25], v[46:49], v[18:21]
	s_nop 4
	ds_read2_b64 v[18:21], v175 offset0:128 offset1:132
	s_waitcnt lgkmcnt(0)
	v_mfma_f32_16x16x32_bf16 v[18:21], v[18:21], v[50:53], 0
	v_mfma_f32_16x16x32_bf16 v[18:21], v[58:61], v[54:57], v[18:21]
	ds_read2_b64 v[58:61], v175 offset0:144 offset1:148
	s_waitcnt lgkmcnt(0)
	v_mfma_f32_16x16x32_bf16 v[18:21], v[58:61], v[42:45], v[18:21]
	ds_read2_b64 v[58:61], v175 offset0:152 offset1:156
	ds_read2_b64 v[62:65], v122 offset0:168 offset1:172
	s_waitcnt lgkmcnt(1)
	v_mfma_f32_16x16x32_bf16 v[18:21], v[58:61], v[46:49], v[18:21]
	ds_read2_b64 v[58:61], v122 offset0:160 offset1:164
	ds_read2_b64 v[66:69], v123 offset0:200 offset1:204
	s_waitcnt lgkmcnt(1)
	v_mfma_f32_16x16x32_bf16 v[58:61], v[58:61], v[50:53], 0
	v_mfma_f32_16x16x32_bf16 v[58:61], v[62:65], v[54:57], v[58:61]
	ds_read2_b64 v[62:65], v122 offset0:176 offset1:180
	s_waitcnt lgkmcnt(0)
	v_mfma_f32_16x16x32_bf16 v[58:61], v[62:65], v[42:45], v[58:61]
	ds_read2_b64 v[62:65], v122 offset0:184 offset1:188
	s_waitcnt lgkmcnt(0)
	v_mfma_f32_16x16x32_bf16 v[58:61], v[62:65], v[46:49], v[58:61]
	ds_read2_b64 v[62:65], v123 offset0:192 offset1:196
	s_waitcnt lgkmcnt(0)
	v_mfma_f32_16x16x32_bf16 v[62:65], v[62:65], v[50:53], 0
	v_mfma_f32_16x16x32_bf16 v[62:65], v[66:69], v[54:57], v[62:65]
	ds_read2_b64 v[66:69], v123 offset0:208 offset1:212
	s_waitcnt lgkmcnt(0)
	v_mfma_f32_16x16x32_bf16 v[62:65], v[66:69], v[42:45], v[62:65]
	ds_read2_b64 v[66:69], v123 offset0:216 offset1:220
	ds_read2_b64 v[70:73], v124 offset0:8 offset1:12
	s_waitcnt lgkmcnt(1)
	v_mfma_f32_16x16x32_bf16 v[62:65], v[66:69], v[46:49], v[62:65]
	ds_read2_b64 v[66:69], v124 offset1:4
	ds_read2_b64 v[74:77], v125 offset0:40 offset1:44
	s_waitcnt lgkmcnt(1)
	v_mfma_f32_16x16x32_bf16 v[66:69], v[66:69], v[50:53], 0
	v_mfma_f32_16x16x32_bf16 v[66:69], v[70:73], v[54:57], v[66:69]
	ds_read2_b64 v[70:73], v124 offset0:16 offset1:20
	s_waitcnt lgkmcnt(0)
	v_mfma_f32_16x16x32_bf16 v[66:69], v[70:73], v[42:45], v[66:69]
	ds_read2_b64 v[70:73], v124 offset0:24 offset1:28
	s_waitcnt lgkmcnt(0)
	v_mfma_f32_16x16x32_bf16 v[66:69], v[70:73], v[46:49], v[66:69]
	ds_read2_b64 v[70:73], v125 offset0:32 offset1:36
	s_waitcnt lgkmcnt(0)
	v_mfma_f32_16x16x32_bf16 v[70:73], v[70:73], v[50:53], 0
	v_mfma_f32_16x16x32_bf16 v[70:73], v[74:77], v[54:57], v[70:73]
	ds_read2_b64 v[74:77], v125 offset0:48 offset1:52
	s_waitcnt lgkmcnt(0)
	v_mfma_f32_16x16x32_bf16 v[70:73], v[74:77], v[42:45], v[70:73]
	ds_read2_b64 v[74:77], v125 offset0:56 offset1:60
	s_waitcnt lgkmcnt(0)
; #define LAS __attribute__((address_space(3)))
; __device__ __forceinline__ void xattn_lds(const Ctx& C, const bf16* P, int cqoff, const bf16* MEMKV, const bf16* MEMVT, bf16* CAT, int ldc, int catoff, int u0, int ustride) {
;     ...
;         for (int half = 0; half < 2; ++half) {
;             v4u stg[8];
; #pragma unroll
;             for (int it = 0; it < 8; ++it) { const int idx = it * 512 + tid, key = idx >> 5, d8 = idx & 31;
;                 stg[it] = *(const v4u*)(MEMKV + (size_t)(b * 256 + half * 128 + key) * 2048 + 1024 + xh * 256 + d8 * 8); }
;             __syncthreads();
;     ...
;             for (int dt = 0; dt < 16; ++dt) {
; #pragma unroll
;                 for (int kk = 0; kk < 4; ++kk) { const LAS unsigned char* vp = Ls + (16 * dt + c) * VP + (32 * kk + 4 * g) * 2;
;                     const v2u lo = *(const LAS v2u*)vp, hi = *(const LAS v2u*)(vp + 32);
;                     v4u vw; vw.x = lo.x; vw.y = lo.y; vw.z = hi.x; vw.w = hi.y;
;                     o[dt] = __builtin_amdgcn_mfma_f32_16x16x32_bf16(__builtin_bit_cast(bf16x8v, vw), pf[4 * half + kk], o[dt], 0, 0, 0); }
	v_mfma_f32_16x16x32_bf16 v[90:93], v[74:77], v[46:49], v[70:73]
	s_nop 4
	ds_read2_b64 v[70:73], v131 offset0:64 offset1:68
	ds_read2_b64 v[74:77], v131 offset0:72 offset1:76
	s_waitcnt lgkmcnt(1)
	v_mfma_f32_16x16x32_bf16 v[70:73], v[70:73], v[50:53], 0
	s_waitcnt lgkmcnt(0)
	v_mfma_f32_16x16x32_bf16 v[70:73], v[74:77], v[54:57], v[70:73]
	ds_read2_b64 v[74:77], v131 offset0:80 offset1:84
	s_waitcnt lgkmcnt(0)
	v_mfma_f32_16x16x32_bf16 v[70:73], v[74:77], v[42:45], v[70:73]
	ds_read2_b64 v[74:77], v131 offset0:88 offset1:92
	s_waitcnt lgkmcnt(0)
	v_mfma_f32_16x16x32_bf16 v[78:81], v[74:77], v[46:49], v[70:73]
	s_nop 4
	ds_read2_b64 v[70:73], v130 offset0:96 offset1:100
	ds_read2_b64 v[74:77], v130 offset0:104 offset1:108
	s_waitcnt lgkmcnt(1)
	v_mfma_f32_16x16x32_bf16 v[70:73], v[70:73], v[50:53], 0
	s_waitcnt lgkmcnt(0)
	v_mfma_f32_16x16x32_bf16 v[70:73], v[74:77], v[54:57], v[70:73]
	ds_read2_b64 v[74:77], v130 offset0:112 offset1:116
	s_waitcnt lgkmcnt(0)
	v_mfma_f32_16x16x32_bf16 v[70:73], v[74:77], v[42:45], v[70:73]
	ds_read2_b64 v[74:77], v130 offset0:120 offset1:124
	ds_read2_b64 v[82:85], v128 offset0:168 offset1:172
	s_waitcnt lgkmcnt(1)
	v_mfma_f32_16x16x32_bf16 v[86:89], v[74:77], v[46:49], v[70:73]
	s_nop 3
	ds_read2_b64 v[70:73], v129 offset0:128 offset1:132
	ds_read2_b64 v[74:77], v129 offset0:136 offset1:140
	s_waitcnt lgkmcnt(1)
	v_mfma_f32_16x16x32_bf16 v[70:73], v[70:73], v[50:53], 0
	s_waitcnt lgkmcnt(0)
	v_mfma_f32_16x16x32_bf16 v[70:73], v[74:77], v[54:57], v[70:73]
	ds_read2_b64 v[74:77], v129 offset0:144 offset1:148
	s_waitcnt lgkmcnt(0)
	v_mfma_f32_16x16x32_bf16 v[70:73], v[74:77], v[42:45], v[70:73]
	ds_read2_b64 v[74:77], v129 offset0:152 offset1:156
	s_waitcnt lgkmcnt(0)
	v_mfma_f32_16x16x32_bf16 v[74:77], v[74:77], v[46:49], v[70:73]
	s_nop 4
	ds_read2_b64 v[70:73], v128 offset0:160 offset1:164
	s_waitcnt lgkmcnt(0)
	v_mfma_f32_16x16x32_bf16 v[70:73], v[70:73], v[50:53], 0
	v_mfma_f32_16x16x32_bf16 v[70:73], v[82:85], v[54:57], v[70:73]
	ds_read2_b64 v[82:85], v128 offset0:176 offset1:180
	s_waitcnt lgkmcnt(0)
	v_mfma_f32_16x16x32_bf16 v[70:73], v[82:85], v[42:45], v[70:73]
	ds_read2_b64 v[82:85], v128 offset0:184 offset1:188
	ds_read2_b64 v[132:135], v127 offset0:200 offset1:204
	s_waitcnt lgkmcnt(1)
	v_mfma_f32_16x16x32_bf16 v[82:85], v[82:85], v[46:49], v[70:73]
	s_nop 3
	ds_read2_b64 v[70:73], v127 offset0:192 offset1:196
	s_waitcnt lgkmcnt(0)
	v_mfma_f32_16x16x32_bf16 v[70:73], v[70:73], v[50:53], 0
	v_mfma_f32_16x16x32_bf16 v[70:73], v[132:135], v[54:57], v[70:73]
	ds_read2_b64 v[132:135], v127 offset0:208 offset1:212
	s_waitcnt lgkmcnt(0)
	v_mfma_f32_16x16x32_bf16 v[70:73], v[132:135], v[42:45], v[70:73]
	ds_read2_b64 v[132:135], v127 offset0:216 offset1:220
	s_waitcnt lgkmcnt(0)
	v_mfma_f32_16x16x32_bf16 v[70:73], v[132:135], v[46:49], v[70:73]
	ds_read2_b64 v[132:135], v126 offset0:224 offset1:228
	s_waitcnt lgkmcnt(0)
	v_mfma_f32_16x16x32_bf16 v[50:53], v[132:135], v[50:53], 0
	ds_read2_b64 v[132:135], v126 offset0:232 offset1:236
	s_waitcnt lgkmcnt(0)
	v_mfma_f32_16x16x32_bf16 v[50:53], v[132:135], v[54:57], v[50:53]
	ds_read2_b64 v[54:57], v126 offset0:240 offset1:244
	s_waitcnt lgkmcnt(0)
	v_mfma_f32_16x16x32_bf16 v[42:45], v[54:57], v[42:45], v[50:53]
	s_nop 4
	ds_read2_b64 v[50:53], v126 offset0:248 offset1:252
	s_waitcnt lgkmcnt(0)
	v_mfma_f32_16x16x32_bf16 v[42:45], v[50:53], v[46:49], v[42:45]
	v_and_b32_e32 v230, 0x7f, v0
	v_lshrrev_b32_e32 v231, 5, v0
	v_sub_u32_e32 v230, v230, v231
	v_lshlrev_b32_e32 v230, 12, v230
	v_lshrrev_b32_e32 v234, 7, v0
	v_lshl_add_u32 v230, v234, 4, v230
	v_ashrrev_i32_e32 v231, 31, v230
	v_lshl_add_u64 v[232:233], s[6:7], 0, v[106:107]
	v_lshl_add_u64 v[232:233], v[232:233], 0, s[10:11]
	v_lshl_add_u64 v[232:233], v[232:233], 0, v[230:231]
	v_and_b32_e32 v235, 0x7f, v0
	v_mul_u32_u24_e32 v236, 0x880, v234
	v_lshl_add_u32 v236, v235, 1, v236
	v_lshl_add_u64 v[48:49], s[6:7], 0, v[108:109]
	v_lshl_add_u64 v[48:49], v[48:49], 0, s[10:11]
	v_lshl_add_u64 v[50:51], v[48:49], 0, v[100:101]
	v_lshl_add_u64 v[48:49], s[6:7], 0, v[110:111]
	v_lshl_add_u64 v[48:49], v[48:49], 0, s[10:11]
	v_lshl_add_u64 v[54:55], v[48:49], 0, v[100:101]
	v_lshl_add_u64 v[48:49], s[6:7], 0, v[112:113]
	v_lshl_add_u64 v[48:49], v[48:49], 0, s[10:11]
	v_lshl_add_u64 v[46:47], s[6:7], 0, v[106:107]
	v_lshl_add_u64 v[106:107], v[48:49], 0, v[100:101]
	v_lshl_add_u64 v[48:49], s[6:7], 0, v[114:115]
	v_lshl_add_u64 v[48:49], v[48:49], 0, s[10:11]
	v_lshl_add_u64 v[110:111], v[48:49], 0, v[100:101]
	v_lshl_add_u64 v[48:49], s[6:7], 0, v[116:117]
	v_lshl_add_u64 v[48:49], v[48:49], 0, s[10:11]
	v_lshl_add_u64 v[114:115], v[48:49], 0, v[100:101]
	v_lshl_add_u64 v[48:49], s[6:7], 0, v[118:119]
	v_lshl_add_u64 v[48:49], v[48:49], 0, s[10:11]
	v_lshl_add_u64 v[118:119], v[48:49], 0, v[100:101]
	v_lshl_add_u64 v[48:49], s[6:7], 0, v[120:121]
	v_lshl_add_u64 v[46:47], v[46:47], 0, s[10:11]
	v_lshl_add_u64 v[48:49], v[48:49], 0, s[10:11]
	v_lshl_add_u64 v[46:47], v[46:47], 0, v[100:101]
	v_lshl_add_u64 v[132:133], v[48:49], 0, v[100:101]
	global_load_dwordx4 v[46:49], v[232:233], off offset:2048
	s_nop 0
	global_load_dwordx4 v[50:53], v[232:233], off offset:2112
	s_nop 0
	global_load_dwordx4 v[54:57], v[232:233], off offset:2176
	s_nop 0
	global_load_dwordx4 v[106:109], v[232:233], off offset:2240
	s_nop 0
	global_load_dwordx4 v[110:113], v[232:233], off offset:2304
	s_nop 0
	global_load_dwordx4 v[114:117], v[232:233], off offset:2368
	s_nop 0
	global_load_dwordx4 v[118:121], v[232:233], off offset:2432
	s_nop 0
	global_load_dwordx4 v[132:135], v[232:233], off offset:2496
	s_barrier
; #define LAS __attribute__((address_space(3)))
; __device__ __forceinline__ void xattn_lds(const Ctx& C, const bf16* P, int cqoff, const bf16* MEMKV, const bf16* MEMVT, bf16* CAT, int ldc, int catoff, int u0, int ustride) {
;     ...
;             for (int it = 0; it < 8; ++it) { const int idx = it * 512 + tid, key = idx >> 5, d8 = idx & 31;
; #pragma unroll
;                 for (int e = 0; e < 8; ++e) { const unsigned wv = stg[it][e >> 1]; *(LAS unsigned short*)(Ls + (8 * d8 + e) * VP + key * 2) = (unsigned short)((e & 1) ? (wv >> 16) : (wv & 0xffffu)); } }
;             __syncthreads();
; #pragma unroll
;             for (int dt = 0; dt < 16; ++dt) {
; #pragma unroll
;                 for (int kk = 0; kk < 4; ++kk) { const LAS unsigned char* vp = Ls + (16 * dt + c) * VP + (32 * kk + 4 * g) * 2;
;                     const v2u lo = *(const LAS v2u*)vp, hi = *(const LAS v2u*)(vp + 32);
;                     v4u vw; vw.x = lo.x; vw.y = lo.y; vw.z = hi.x; vw.w = hi.y;
;                     o[dt] = __builtin_amdgcn_mfma_f32_16x16x32_bf16(__builtin_bit_cast(bf16x8v, vw), pf[4 * half + kk], o[dt], 0, 0, 0); }
	s_waitcnt vmcnt(7)
	ds_write_b16 v236, v46 offset:0
	ds_write_b16_d16_hi v236, v46 offset:272
	ds_write_b16 v236, v47 offset:544
	ds_write_b16_d16_hi v236, v47 offset:816
	ds_write_b16 v236, v48 offset:1088
	ds_write_b16_d16_hi v236, v48 offset:1360
	ds_write_b16 v236, v49 offset:1632
	ds_write_b16_d16_hi v236, v49 offset:1904
	s_waitcnt vmcnt(6)
	ds_write_b16 v236, v50 offset:8704
	ds_write_b16_d16_hi v236, v50 offset:8976
	ds_write_b16 v236, v51 offset:9248
	ds_write_b16_d16_hi v236, v51 offset:9520
	ds_write_b16 v236, v52 offset:9792
	ds_write_b16_d16_hi v236, v52 offset:10064
	ds_write_b16 v236, v53 offset:10336
	ds_write_b16_d16_hi v236, v53 offset:10608
	s_waitcnt vmcnt(5)
	ds_write_b16 v236, v54 offset:17408
	ds_write_b16_d16_hi v236, v54 offset:17680
	ds_write_b16 v236, v55 offset:17952
	ds_write_b16_d16_hi v236, v55 offset:18224
	ds_write_b16 v236, v56 offset:18496
	ds_write_b16_d16_hi v236, v56 offset:18768
	ds_write_b16 v236, v57 offset:19040
	ds_write_b16_d16_hi v236, v57 offset:19312
	s_waitcnt vmcnt(4)
	ds_write_b16 v236, v106 offset:26112
	ds_write_b16_d16_hi v236, v106 offset:26384
	ds_write_b16 v236, v107 offset:26656
	ds_write_b16_d16_hi v236, v107 offset:26928
	ds_write_b16 v236, v108 offset:27200
	ds_write_b16_d16_hi v236, v108 offset:27472
	ds_write_b16 v236, v109 offset:27744
	ds_write_b16_d16_hi v236, v109 offset:28016
	s_waitcnt vmcnt(3)
	ds_write_b16 v236, v110 offset:34816
	ds_write_b16_d16_hi v236, v110 offset:35088
	ds_write_b16 v236, v111 offset:35360
	ds_write_b16_d16_hi v236, v111 offset:35632
	ds_write_b16 v236, v112 offset:35904
	ds_write_b16_d16_hi v236, v112 offset:36176
	ds_write_b16 v236, v113 offset:36448
	ds_write_b16_d16_hi v236, v113 offset:36720
	s_waitcnt vmcnt(2)
	ds_write_b16 v236, v114 offset:43520
	ds_write_b16_d16_hi v236, v114 offset:43792
	ds_write_b16 v236, v115 offset:44064
	ds_write_b16_d16_hi v236, v115 offset:44336
	ds_write_b16 v236, v116 offset:44608
	ds_write_b16_d16_hi v236, v116 offset:44880
	ds_write_b16 v236, v117 offset:45152
	ds_write_b16_d16_hi v236, v117 offset:45424
	s_waitcnt vmcnt(1)
	ds_write_b16 v236, v118 offset:52224
	ds_write_b16_d16_hi v236, v118 offset:52496
	ds_write_b16 v236, v119 offset:52768
	ds_write_b16_d16_hi v236, v119 offset:53040
	ds_write_b16 v236, v120 offset:53312
	ds_write_b16_d16_hi v236, v120 offset:53584
	ds_write_b16 v236, v121 offset:53856
	ds_write_b16_d16_hi v236, v121 offset:54128
	s_waitcnt vmcnt(0)
	ds_write_b16 v236, v132 offset:60928
	ds_write_b16_d16_hi v236, v132 offset:61200
	ds_write_b16 v236, v133 offset:61472
	ds_write_b16_d16_hi v236, v133 offset:61744
	ds_write_b16 v236, v134 offset:62016
	ds_write_b16_d16_hi v236, v134 offset:62288
	ds_write_b16 v236, v135 offset:62560
	ds_write_b16_d16_hi v236, v135 offset:62832
	s_waitcnt lgkmcnt(0)
	s_barrier
	ds_read2_b64 v[46:49], v149 offset1:4
	s_waitcnt lgkmcnt(0)
	v_mfma_f32_16x16x32_bf16 v[38:41], v[46:49], v[2:5], v[38:41]
	ds_read2_b64 v[46:49], v149 offset0:8 offset1:12
	s_waitcnt lgkmcnt(0)
	v_mfma_f32_16x16x32_bf16 v[38:41], v[46:49], v[6:9], v[38:41]
	ds_read2_b64 v[46:49], v149 offset0:16 offset1:20
	s_waitcnt lgkmcnt(0)
	v_mfma_f32_16x16x32_bf16 v[38:41], v[46:49], v[10:13], v[38:41]
	ds_read2_b64 v[46:49], v149 offset0:24 offset1:28
	s_waitcnt lgkmcnt(0)
	v_mfma_f32_16x16x32_bf16 v[38:41], v[46:49], v[14:17], v[38:41]
	ds_read2_b64 v[46:49], v168 offset0:24 offset1:28
	ds_read2_b64 v[50:53], v168 offset0:16 offset1:20
	ds_read2_b64 v[54:57], v168 offset0:8 offset1:12
	ds_read2_b64 v[106:109], v168 offset1:4
	s_waitcnt lgkmcnt(0)
	v_mfma_f32_16x16x32_bf16 v[34:37], v[106:109], v[2:5], v[34:37]
	v_mfma_f32_16x16x32_bf16 v[34:37], v[54:57], v[6:9], v[34:37]
	v_mfma_f32_16x16x32_bf16 v[34:37], v[50:53], v[10:13], v[34:37]
	v_mfma_f32_16x16x32_bf16 v[34:37], v[46:49], v[14:17], v[34:37]
	ds_read2_b64 v[46:49], v172 offset0:32 offset1:36
	s_waitcnt lgkmcnt(0)
	v_mfma_f32_16x16x32_bf16 v[30:33], v[46:49], v[2:5], v[30:33]
	ds_read2_b64 v[46:49], v172 offset0:40 offset1:44
	s_waitcnt lgkmcnt(0)
	v_mfma_f32_16x16x32_bf16 v[30:33], v[46:49], v[6:9], v[30:33]
	ds_read2_b64 v[46:49], v172 offset0:48 offset1:52
	s_waitcnt lgkmcnt(0)
	v_mfma_f32_16x16x32_bf16 v[30:33], v[46:49], v[10:13], v[30:33]
	ds_read2_b64 v[46:49], v172 offset0:56 offset1:60
	s_waitcnt lgkmcnt(0)
	v_mfma_f32_16x16x32_bf16 v[30:33], v[46:49], v[14:17], v[30:33]
	ds_read2_b64 v[46:49], v173 offset0:88 offset1:92
	ds_read2_b64 v[50:53], v173 offset0:80 offset1:84
	ds_read2_b64 v[54:57], v173 offset0:72 offset1:76
	ds_read2_b64 v[106:109], v173 offset0:64 offset1:68
	s_waitcnt lgkmcnt(0)
	v_mfma_f32_16x16x32_bf16 v[26:29], v[106:109], v[2:5], v[26:29]
	v_mfma_f32_16x16x32_bf16 v[26:29], v[54:57], v[6:9], v[26:29]
	v_mfma_f32_16x16x32_bf16 v[26:29], v[50:53], v[10:13], v[26:29]
	v_mfma_f32_16x16x32_bf16 v[26:29], v[46:49], v[14:17], v[26:29]
	ds_read2_b64 v[46:49], v174 offset0:96 offset1:100
	s_waitcnt lgkmcnt(0)
	v_mfma_f32_16x16x32_bf16 v[22:25], v[46:49], v[2:5], v[22:25]
	ds_read2_b64 v[46:49], v174 offset0:104 offset1:108
	s_waitcnt lgkmcnt(0)
	v_mfma_f32_16x16x32_bf16 v[22:25], v[46:49], v[6:9], v[22:25]
	ds_read2_b64 v[46:49], v174 offset0:112 offset1:116
	s_waitcnt lgkmcnt(0)
	v_mfma_f32_16x16x32_bf16 v[22:25], v[46:49], v[10:13], v[22:25]
	ds_read2_b64 v[46:49], v174 offset0:120 offset1:124
	s_waitcnt lgkmcnt(0)
	v_mfma_f32_16x16x32_bf16 v[22:25], v[46:49], v[14:17], v[22:25]
	ds_read2_b64 v[46:49], v175 offset0:152 offset1:156
	ds_read2_b64 v[50:53], v175 offset0:144 offset1:148
	ds_read2_b64 v[54:57], v175 offset0:136 offset1:140
	ds_read2_b64 v[106:109], v175 offset0:128 offset1:132
	s_waitcnt lgkmcnt(0)
; #define LAS __attribute__((address_space(3)))
; __device__ __forceinline__ void xattn_lds(const Ctx& C, const bf16* P, int cqoff, const bf16* MEMKV, const bf16* MEMVT, bf16* CAT, int ldc, int catoff, int u0, int ustride) {
;     ...
;             for (int dt = 0; dt < 16; ++dt) {
; #pragma unroll
;                 for (int kk = 0; kk < 4; ++kk) { const LAS unsigned char* vp = Ls + (16 * dt + c) * VP + (32 * kk + 4 * g) * 2;
;                     const v2u lo = *(const LAS v2u*)vp, hi = *(const LAS v2u*)(vp + 32);
;                     v4u vw; vw.x = lo.x; vw.y = lo.y; vw.z = hi.x; vw.w = hi.y;
;                     o[dt] = __builtin_amdgcn_mfma_f32_16x16x32_bf16(__builtin_bit_cast(bf16x8v, vw), pf[4 * half + kk], o[dt], 0, 0, 0); }
;                 if (dt & 1) asm volatile("" ::: "memory"); }
	v_mfma_f32_16x16x32_bf16 v[18:21], v[106:109], v[2:5], v[18:21]
	v_mfma_f32_16x16x32_bf16 v[18:21], v[54:57], v[6:9], v[18:21]
	v_mfma_f32_16x16x32_bf16 v[18:21], v[50:53], v[10:13], v[18:21]
	ds_read2_b64 v[50:53], v122 offset0:168 offset1:172
	v_mfma_f32_16x16x32_bf16 v[18:21], v[46:49], v[14:17], v[18:21]
	ds_read2_b64 v[46:49], v122 offset0:160 offset1:164
	s_waitcnt lgkmcnt(0)
	v_mfma_f32_16x16x32_bf16 v[46:49], v[46:49], v[2:5], v[58:61]
	v_mfma_f32_16x16x32_bf16 v[46:49], v[50:53], v[6:9], v[46:49]
	ds_read2_b64 v[50:53], v122 offset0:176 offset1:180
	s_waitcnt lgkmcnt(0)
	v_mfma_f32_16x16x32_bf16 v[46:49], v[50:53], v[10:13], v[46:49]
	ds_read2_b64 v[50:53], v122 offset0:184 offset1:188
	s_waitcnt lgkmcnt(0)
	v_mfma_f32_16x16x32_bf16 v[46:49], v[50:53], v[14:17], v[46:49]
	ds_read2_b64 v[50:53], v123 offset0:216 offset1:220
	ds_read2_b64 v[54:57], v123 offset0:208 offset1:212
	ds_read2_b64 v[58:61], v123 offset0:200 offset1:204
	ds_read2_b64 v[106:109], v123 offset0:192 offset1:196
	s_waitcnt lgkmcnt(0)
	v_mfma_f32_16x16x32_bf16 v[62:65], v[106:109], v[2:5], v[62:65]
	v_mfma_f32_16x16x32_bf16 v[58:61], v[58:61], v[6:9], v[62:65]
	v_mfma_f32_16x16x32_bf16 v[54:57], v[54:57], v[10:13], v[58:61]
	v_mfma_f32_16x16x32_bf16 v[50:53], v[50:53], v[14:17], v[54:57]
	s_nop 5
	ds_read2_b64 v[58:61], v124 offset0:8 offset1:12
	ds_read2_b64 v[54:57], v124 offset1:4
	s_waitcnt lgkmcnt(0)
	v_mfma_f32_16x16x32_bf16 v[54:57], v[54:57], v[2:5], v[66:69]
	v_mfma_f32_16x16x32_bf16 v[54:57], v[58:61], v[6:9], v[54:57]
	ds_read2_b64 v[58:61], v124 offset0:16 offset1:20
	s_waitcnt lgkmcnt(0)
	v_mfma_f32_16x16x32_bf16 v[54:57], v[58:61], v[10:13], v[54:57]
	ds_read2_b64 v[58:61], v124 offset0:24 offset1:28
	s_waitcnt lgkmcnt(0)
	v_mfma_f32_16x16x32_bf16 v[54:57], v[58:61], v[14:17], v[54:57]
	ds_read2_b64 v[58:61], v125 offset0:56 offset1:60
	ds_read2_b64 v[62:65], v125 offset0:48 offset1:52
	ds_read2_b64 v[66:69], v125 offset0:40 offset1:44
	ds_read2_b64 v[106:109], v125 offset0:32 offset1:36
	s_waitcnt lgkmcnt(0)
	v_mfma_f32_16x16x32_bf16 v[90:93], v[106:109], v[2:5], v[90:93]
	v_mfma_f32_16x16x32_bf16 v[66:69], v[66:69], v[6:9], v[90:93]
	v_mfma_f32_16x16x32_bf16 v[62:65], v[62:65], v[10:13], v[66:69]
	v_mfma_f32_16x16x32_bf16 v[58:61], v[58:61], v[14:17], v[62:65]
	s_nop 5
	ds_read2_b64 v[66:69], v131 offset0:72 offset1:76
	ds_read2_b64 v[62:65], v131 offset0:64 offset1:68
	s_waitcnt lgkmcnt(0)
	v_mfma_f32_16x16x32_bf16 v[62:65], v[62:65], v[2:5], v[78:81]
	v_mfma_f32_16x16x32_bf16 v[62:65], v[66:69], v[6:9], v[62:65]
	ds_read2_b64 v[66:69], v131 offset0:80 offset1:84
	s_waitcnt lgkmcnt(0)
	v_mfma_f32_16x16x32_bf16 v[62:65], v[66:69], v[10:13], v[62:65]
	ds_read2_b64 v[66:69], v131 offset0:88 offset1:92
	s_waitcnt lgkmcnt(0)
	v_mfma_f32_16x16x32_bf16 v[62:65], v[66:69], v[14:17], v[62:65]
	ds_read2_b64 v[66:69], v130 offset0:120 offset1:124
	ds_read2_b64 v[78:81], v130 offset0:112 offset1:116
	ds_read2_b64 v[90:93], v130 offset0:104 offset1:108
	ds_read2_b64 v[106:109], v130 offset0:96 offset1:100
	s_waitcnt lgkmcnt(0)
	v_mfma_f32_16x16x32_bf16 v[86:89], v[106:109], v[2:5], v[86:89]
	v_mfma_f32_16x16x32_bf16 v[86:89], v[90:93], v[6:9], v[86:89]
	v_mfma_f32_16x16x32_bf16 v[78:81], v[78:81], v[10:13], v[86:89]
	v_mfma_f32_16x16x32_bf16 v[66:69], v[66:69], v[14:17], v[78:81]
	s_nop 6
	ds_read2_b64 v[78:81], v129 offset0:128 offset1:132
	s_waitcnt lgkmcnt(0)
	v_mfma_f32_16x16x32_bf16 v[74:77], v[78:81], v[2:5], v[74:77]
	ds_read2_b64 v[78:81], v129 offset0:136 offset1:140
	s_waitcnt lgkmcnt(0)
	v_mfma_f32_16x16x32_bf16 v[74:77], v[78:81], v[6:9], v[74:77]
	ds_read2_b64 v[78:81], v129 offset0:144 offset1:148
	s_waitcnt lgkmcnt(0)
	v_mfma_f32_16x16x32_bf16 v[74:77], v[78:81], v[10:13], v[74:77]
	ds_read2_b64 v[78:81], v129 offset0:152 offset1:156
	s_waitcnt lgkmcnt(0)
	v_mfma_f32_16x16x32_bf16 v[74:77], v[78:81], v[14:17], v[74:77]
	ds_read2_b64 v[78:81], v128 offset0:184 offset1:188
	ds_read2_b64 v[86:89], v128 offset0:176 offset1:180
	ds_read2_b64 v[90:93], v128 offset0:168 offset1:172
	ds_read2_b64 v[106:109], v128 offset0:160 offset1:164
	s_waitcnt lgkmcnt(0)
	v_mfma_f32_16x16x32_bf16 v[82:85], v[106:109], v[2:5], v[82:85]
	v_mfma_f32_16x16x32_bf16 v[82:85], v[90:93], v[6:9], v[82:85]
	v_mfma_f32_16x16x32_bf16 v[82:85], v[86:89], v[10:13], v[82:85]
	v_mfma_f32_16x16x32_bf16 v[78:81], v[78:81], v[14:17], v[82:85]
	s_nop 6
	ds_read2_b64 v[82:85], v127 offset0:192 offset1:196
	s_waitcnt lgkmcnt(0)
	v_mfma_f32_16x16x32_bf16 v[70:73], v[82:85], v[2:5], v[70:73]
	ds_read2_b64 v[82:85], v127 offset0:200 offset1:204
	s_waitcnt lgkmcnt(0)
	v_mfma_f32_16x16x32_bf16 v[70:73], v[82:85], v[6:9], v[70:73]
	ds_read2_b64 v[82:85], v127 offset0:208 offset1:212
	s_waitcnt lgkmcnt(0)
	v_mfma_f32_16x16x32_bf16 v[70:73], v[82:85], v[10:13], v[70:73]
	ds_read2_b64 v[82:85], v127 offset0:216 offset1:220
	s_waitcnt lgkmcnt(0)
	v_mfma_f32_16x16x32_bf16 v[70:73], v[82:85], v[14:17], v[70:73]
	ds_read2_b64 v[82:85], v126 offset0:248 offset1:252
	ds_read2_b64 v[86:89], v126 offset0:240 offset1:244
	ds_read2_b64 v[90:93], v126 offset0:232 offset1:236
	ds_read2_b64 v[106:109], v126 offset0:224 offset1:228
	s_waitcnt lgkmcnt(0)
; __device__ __forceinline__ unsigned pk2(float lo, float hi) { return f2bf(lo) | (f2bf(hi) << 16); }
; __device__ __forceinline__ void xattn_lds(const Ctx& C, const bf16* P, int cqoff, const bf16* MEMKV, const bf16* MEMVT, bf16* CAT, int ldc, int catoff, int u0, int ustride) {
;     ...
;         const float inv = 1.f / l;
;     ...
;         bf16* op = CAT + (size_t)qrow * ldc + catoff + xh * 256 + 4 * g;
; #pragma unroll
;         for (int dt = 0; dt < 16; ++dt) { v2u ow; ow.x = pk2(o[dt][0] * inv, o[dt][1] * inv); ow.y = pk2(o[dt][2] * inv, o[dt][3] * inv); *(v2u*)(op + dt * 16) = ow; }
	v_mfma_f32_16x16x32_bf16 v[2:5], v[106:109], v[2:5], v[42:45]
	v_mfma_f32_16x16x32_bf16 v[2:5], v[90:93], v[6:9], v[2:5]
	v_div_scale_f32 v6, s[0:1], v177, v177, 1.0
	v_rcp_f32_e32 v7, v6
	v_mfma_f32_16x16x32_bf16 v[2:5], v[86:89], v[10:13], v[2:5]
	v_mov_b32_e32 v11, v40
	v_mov_b32_e32 v40, v39
	v_fma_f32 v8, -v6, v7, 1.0
	v_fmac_f32_e32 v7, v8, v7
	v_div_scale_f32 v8, vcc, 1.0, v177, 1.0
	v_mul_f32_e32 v9, v8, v7
	v_fma_f32 v10, -v6, v9, v8
	v_fmac_f32_e32 v9, v10, v7
	v_fma_f32 v6, -v6, v9, v8
	v_div_fmas_f32 v6, v6, v7, v9
	v_div_fixup_f32 v8, v6, v177, 1.0
	v_mov_b32_e32 v10, v38
	v_pk_mul_f32 v[10:11], v[8:9], v[10:11] op_sel_hi:[0,1]
	v_mfma_f32_16x16x32_bf16 v[2:5], v[82:85], v[14:17], v[2:5]
	v_mul_f32_e64 v12, v8, v40
	v_mul_f32_e64 v13, v8, v41
	v_and_b32_sdwa v9, v11, v176 dst_sel:DWORD dst_unused:UNUSED_PAD src0_sel:WORD_1 src1_sel:DWORD
	v_and_b32_sdwa v14, v10, v176 dst_sel:DWORD dst_unused:UNUSED_PAD src0_sel:WORD_1 src1_sel:DWORD
	v_lshlrev_b64 v[6:7], 13, v[104:105]
	v_add3_u32 v10, v10, v14, s22
	v_add3_u32 v9, v11, v9, s22
	v_and_b32_sdwa v11, v13, v176 dst_sel:DWORD dst_unused:UNUSED_PAD src0_sel:WORD_1 src1_sel:DWORD
	v_and_b32_sdwa v14, v12, v176 dst_sel:DWORD dst_unused:UNUSED_PAD src0_sel:WORD_1 src1_sel:DWORD
	v_lshl_add_u64 v[6:7], s[8:9], 0, v[6:7]
	v_add3_u32 v11, v13, v11, s22
	v_add3_u32 v12, v12, v14, s22
	v_lshl_add_u64 v[6:7], v[6:7], 0, s[10:11]
	v_and_b32_e32 v11, 0xffff0000, v11
	v_and_b32_e32 v12, 0xffff0000, v12
	v_lshl_add_u64 v[6:7], v[6:7], 0, v[102:103]
	v_or_b32_sdwa v11, v11, v9 dst_sel:DWORD dst_unused:UNUSED_PAD src0_sel:DWORD src1_sel:WORD_1
	v_or_b32_sdwa v10, v12, v10 dst_sel:DWORD dst_unused:UNUSED_PAD src0_sel:DWORD src1_sel:WORD_1
	global_store_dwordx2 v[6:7], v[10:11], off
	v_mov_b32_e32 v10, v34
	v_mov_b32_e32 v11, v36
	v_pk_mul_f32 v[10:11], v[8:9], v[10:11] op_sel_hi:[0,1]
	v_mov_b32_e32 v36, v35
	v_pk_mul_f32 v[12:13], v[8:9], v[36:37] op_sel_hi:[0,1]
	v_and_b32_sdwa v9, v11, v176 dst_sel:DWORD dst_unused:UNUSED_PAD src0_sel:WORD_1 src1_sel:DWORD
	v_and_b32_sdwa v14, v10, v176 dst_sel:DWORD dst_unused:UNUSED_PAD src0_sel:WORD_1 src1_sel:DWORD
	v_add3_u32 v10, v10, v14, s22
	v_add3_u32 v9, v11, v9, s22
	v_and_b32_sdwa v11, v13, v176 dst_sel:DWORD dst_unused:UNUSED_PAD src0_sel:WORD_1 src1_sel:DWORD
	v_and_b32_sdwa v14, v12, v176 dst_sel:DWORD dst_unused:UNUSED_PAD src0_sel:WORD_1 src1_sel:DWORD
	v_add3_u32 v11, v13, v11, s22
	v_add3_u32 v12, v12, v14, s22
	v_and_b32_e32 v11, 0xffff0000, v11
	v_and_b32_e32 v12, 0xffff0000, v12
	v_or_b32_sdwa v11, v11, v9 dst_sel:DWORD dst_unused:UNUSED_PAD src0_sel:DWORD src1_sel:WORD_1
	v_or_b32_sdwa v10, v12, v10 dst_sel:DWORD dst_unused:UNUSED_PAD src0_sel:DWORD src1_sel:WORD_1
	global_store_dwordx2 v[6:7], v[10:11], off offset:32
	v_mov_b32_e32 v10, v30
	v_mov_b32_e32 v11, v32
	v_pk_mul_f32 v[10:11], v[8:9], v[10:11] op_sel_hi:[0,1]
	v_mov_b32_e32 v32, v31
	v_pk_mul_f32 v[12:13], v[8:9], v[32:33] op_sel_hi:[0,1]
	v_and_b32_sdwa v9, v11, v176 dst_sel:DWORD dst_unused:UNUSED_PAD src0_sel:WORD_1 src1_sel:DWORD
	v_and_b32_sdwa v14, v10, v176 dst_sel:DWORD dst_unused:UNUSED_PAD src0_sel:WORD_1 src1_sel:DWORD
	v_add3_u32 v10, v10, v14, s22
	v_add3_u32 v9, v11, v9, s22
	v_and_b32_sdwa v11, v13, v176 dst_sel:DWORD dst_unused:UNUSED_PAD src0_sel:WORD_1 src1_sel:DWORD
	v_and_b32_sdwa v14, v12, v176 dst_sel:DWORD dst_unused:UNUSED_PAD src0_sel:WORD_1 src1_sel:DWORD
	v_add3_u32 v11, v13, v11, s22
	v_add3_u32 v12, v12, v14, s22
	v_and_b32_e32 v11, 0xffff0000, v11
	v_and_b32_e32 v12, 0xffff0000, v12
	v_or_b32_sdwa v11, v11, v9 dst_sel:DWORD dst_unused:UNUSED_PAD src0_sel:DWORD src1_sel:WORD_1
	v_or_b32_sdwa v10, v12, v10 dst_sel:DWORD dst_unused:UNUSED_PAD src0_sel:DWORD src1_sel:WORD_1
	global_store_dwordx2 v[6:7], v[10:11], off offset:64
	v_mov_b32_e32 v10, v26
	v_mov_b32_e32 v11, v28
	v_pk_mul_f32 v[10:11], v[8:9], v[10:11] op_sel_hi:[0,1]
	v_mov_b32_e32 v28, v27
	v_pk_mul_f32 v[12:13], v[8:9], v[28:29] op_sel_hi:[0,1]
	v_and_b32_sdwa v9, v11, v176 dst_sel:DWORD dst_unused:UNUSED_PAD src0_sel:WORD_1 src1_sel:DWORD
	v_and_b32_sdwa v14, v10, v176 dst_sel:DWORD dst_unused:UNUSED_PAD src0_sel:WORD_1 src1_sel:DWORD
	v_add3_u32 v10, v10, v14, s22
	v_add3_u32 v9, v11, v9, s22
	v_and_b32_sdwa v11, v13, v176 dst_sel:DWORD dst_unused:UNUSED_PAD src0_sel:WORD_1 src1_sel:DWORD
	v_and_b32_sdwa v14, v12, v176 dst_sel:DWORD dst_unused:UNUSED_PAD src0_sel:WORD_1 src1_sel:DWORD
	v_add3_u32 v11, v13, v11, s22
	v_add3_u32 v12, v12, v14, s22
	v_and_b32_e32 v11, 0xffff0000, v11
	v_and_b32_e32 v12, 0xffff0000, v12
	v_or_b32_sdwa v11, v11, v9 dst_sel:DWORD dst_unused:UNUSED_PAD src0_sel:DWORD src1_sel:WORD_1
	v_or_b32_sdwa v10, v12, v10 dst_sel:DWORD dst_unused:UNUSED_PAD src0_sel:DWORD src1_sel:WORD_1
	global_store_dwordx2 v[6:7], v[10:11], off offset:96
	v_mov_b32_e32 v10, v22
	v_mov_b32_e32 v11, v24
	v_pk_mul_f32 v[10:11], v[8:9], v[10:11] op_sel_hi:[0,1]
	v_mov_b32_e32 v24, v23
	v_pk_mul_f32 v[12:13], v[8:9], v[24:25] op_sel_hi:[0,1]
	v_and_b32_sdwa v9, v11, v176 dst_sel:DWORD dst_unused:UNUSED_PAD src0_sel:WORD_1 src1_sel:DWORD
	v_and_b32_sdwa v14, v10, v176 dst_sel:DWORD dst_unused:UNUSED_PAD src0_sel:WORD_1 src1_sel:DWORD
	v_add3_u32 v10, v10, v14, s22
	v_add3_u32 v9, v11, v9, s22
	v_and_b32_sdwa v11, v13, v176 dst_sel:DWORD dst_unused:UNUSED_PAD src0_sel:WORD_1 src1_sel:DWORD
	v_and_b32_sdwa v14, v12, v176 dst_sel:DWORD dst_unused:UNUSED_PAD src0_sel:WORD_1 src1_sel:DWORD
	v_add3_u32 v11, v13, v11, s22
	v_add3_u32 v12, v12, v14, s22
	v_and_b32_e32 v11, 0xffff0000, v11
	v_and_b32_e32 v12, 0xffff0000, v12
	v_or_b32_sdwa v11, v11, v9 dst_sel:DWORD dst_unused:UNUSED_PAD src0_sel:DWORD src1_sel:WORD_1
; __device__ __forceinline__ unsigned pk2(float lo, float hi) { return f2bf(lo) | (f2bf(hi) << 16); }
; __device__ __forceinline__ void xattn_lds(const Ctx& C, const bf16* P, int cqoff, const bf16* MEMKV, const bf16* MEMVT, bf16* CAT, int ldc, int catoff, int u0, int ustride) {
;     ...
;         for (int dt = 0; dt < 16; ++dt) { v2u ow; ow.x = pk2(o[dt][0] * inv, o[dt][1] * inv); ow.y = pk2(o[dt][2] * inv, o[dt][3] * inv); *(v2u*)(op + dt * 16) = ow; }
	v_or_b32_sdwa v10, v12, v10 dst_sel:DWORD dst_unused:UNUSED_PAD src0_sel:DWORD src1_sel:WORD_1
	global_store_dwordx2 v[6:7], v[10:11], off offset:128
	v_mov_b32_e32 v10, v18
	v_mov_b32_e32 v11, v20
	v_pk_mul_f32 v[10:11], v[8:9], v[10:11] op_sel_hi:[0,1]
	v_mov_b32_e32 v20, v19
	v_pk_mul_f32 v[12:13], v[8:9], v[20:21] op_sel_hi:[0,1]
	v_and_b32_sdwa v9, v11, v176 dst_sel:DWORD dst_unused:UNUSED_PAD src0_sel:WORD_1 src1_sel:DWORD
	v_and_b32_sdwa v14, v10, v176 dst_sel:DWORD dst_unused:UNUSED_PAD src0_sel:WORD_1 src1_sel:DWORD
	v_add3_u32 v10, v10, v14, s22
	v_add3_u32 v9, v11, v9, s22
	v_and_b32_sdwa v11, v13, v176 dst_sel:DWORD dst_unused:UNUSED_PAD src0_sel:WORD_1 src1_sel:DWORD
	v_and_b32_sdwa v14, v12, v176 dst_sel:DWORD dst_unused:UNUSED_PAD src0_sel:WORD_1 src1_sel:DWORD
	v_add3_u32 v11, v13, v11, s22
	v_add3_u32 v12, v12, v14, s22
	v_and_b32_e32 v11, 0xffff0000, v11
	v_and_b32_e32 v12, 0xffff0000, v12
	v_or_b32_sdwa v11, v11, v9 dst_sel:DWORD dst_unused:UNUSED_PAD src0_sel:DWORD src1_sel:WORD_1
	v_or_b32_sdwa v10, v12, v10 dst_sel:DWORD dst_unused:UNUSED_PAD src0_sel:DWORD src1_sel:WORD_1
	global_store_dwordx2 v[6:7], v[10:11], off offset:160
	v_mov_b32_e32 v10, v46
	v_mov_b32_e32 v11, v48
	v_pk_mul_f32 v[10:11], v[8:9], v[10:11] op_sel_hi:[0,1]
	v_mov_b32_e32 v48, v47
	v_pk_mul_f32 v[12:13], v[8:9], v[48:49] op_sel_hi:[0,1]
	v_and_b32_sdwa v9, v11, v176 dst_sel:DWORD dst_unused:UNUSED_PAD src0_sel:WORD_1 src1_sel:DWORD
	v_and_b32_sdwa v14, v10, v176 dst_sel:DWORD dst_unused:UNUSED_PAD src0_sel:WORD_1 src1_sel:DWORD
	v_add3_u32 v10, v10, v14, s22
	v_add3_u32 v9, v11, v9, s22
	v_and_b32_sdwa v11, v13, v176 dst_sel:DWORD dst_unused:UNUSED_PAD src0_sel:WORD_1 src1_sel:DWORD
	v_and_b32_sdwa v14, v12, v176 dst_sel:DWORD dst_unused:UNUSED_PAD src0_sel:WORD_1 src1_sel:DWORD
	v_add3_u32 v11, v13, v11, s22
	v_add3_u32 v12, v12, v14, s22
	v_and_b32_e32 v11, 0xffff0000, v11
	v_and_b32_e32 v12, 0xffff0000, v12
	v_or_b32_sdwa v11, v11, v9 dst_sel:DWORD dst_unused:UNUSED_PAD src0_sel:DWORD src1_sel:WORD_1
	v_or_b32_sdwa v10, v12, v10 dst_sel:DWORD dst_unused:UNUSED_PAD src0_sel:DWORD src1_sel:WORD_1
	global_store_dwordx2 v[6:7], v[10:11], off offset:192
	v_mov_b32_e32 v10, v50
	v_mov_b32_e32 v11, v52
	v_pk_mul_f32 v[10:11], v[8:9], v[10:11] op_sel_hi:[0,1]
	v_mov_b32_e32 v52, v51
	v_pk_mul_f32 v[12:13], v[8:9], v[52:53] op_sel_hi:[0,1]
	v_and_b32_sdwa v9, v11, v176 dst_sel:DWORD dst_unused:UNUSED_PAD src0_sel:WORD_1 src1_sel:DWORD
	v_and_b32_sdwa v14, v10, v176 dst_sel:DWORD dst_unused:UNUSED_PAD src0_sel:WORD_1 src1_sel:DWORD
	v_add3_u32 v10, v10, v14, s22
	v_add3_u32 v9, v11, v9, s22
	v_and_b32_sdwa v11, v13, v176 dst_sel:DWORD dst_unused:UNUSED_PAD src0_sel:WORD_1 src1_sel:DWORD
	v_and_b32_sdwa v14, v12, v176 dst_sel:DWORD dst_unused:UNUSED_PAD src0_sel:WORD_1 src1_sel:DWORD
	v_add3_u32 v11, v13, v11, s22
	v_add3_u32 v12, v12, v14, s22
	v_and_b32_e32 v11, 0xffff0000, v11
	v_and_b32_e32 v12, 0xffff0000, v12
	v_or_b32_sdwa v11, v11, v9 dst_sel:DWORD dst_unused:UNUSED_PAD src0_sel:DWORD src1_sel:WORD_1
	v_or_b32_sdwa v10, v12, v10 dst_sel:DWORD dst_unused:UNUSED_PAD src0_sel:DWORD src1_sel:WORD_1
	global_store_dwordx2 v[6:7], v[10:11], off offset:224
	v_mov_b32_e32 v10, v54
	v_mov_b32_e32 v11, v56
	v_pk_mul_f32 v[10:11], v[8:9], v[10:11] op_sel_hi:[0,1]
	v_mov_b32_e32 v56, v55
	v_pk_mul_f32 v[12:13], v[8:9], v[56:57] op_sel_hi:[0,1]
	v_and_b32_sdwa v9, v11, v176 dst_sel:DWORD dst_unused:UNUSED_PAD src0_sel:WORD_1 src1_sel:DWORD
	v_and_b32_sdwa v14, v10, v176 dst_sel:DWORD dst_unused:UNUSED_PAD src0_sel:WORD_1 src1_sel:DWORD
	v_add3_u32 v10, v10, v14, s22
	v_add3_u32 v9, v11, v9, s22
	v_and_b32_sdwa v11, v13, v176 dst_sel:DWORD dst_unused:UNUSED_PAD src0_sel:WORD_1 src1_sel:DWORD
	v_and_b32_sdwa v14, v12, v176 dst_sel:DWORD dst_unused:UNUSED_PAD src0_sel:WORD_1 src1_sel:DWORD
	v_add3_u32 v11, v13, v11, s22
	v_add3_u32 v12, v12, v14, s22
	v_and_b32_e32 v11, 0xffff0000, v11
	v_and_b32_e32 v12, 0xffff0000, v12
	v_or_b32_sdwa v11, v11, v9 dst_sel:DWORD dst_unused:UNUSED_PAD src0_sel:DWORD src1_sel:WORD_1
	v_or_b32_sdwa v10, v12, v10 dst_sel:DWORD dst_unused:UNUSED_PAD src0_sel:DWORD src1_sel:WORD_1
	global_store_dwordx2 v[6:7], v[10:11], off offset:256
	v_mov_b32_e32 v10, v58
	v_mov_b32_e32 v11, v60
	v_pk_mul_f32 v[10:11], v[8:9], v[10:11] op_sel_hi:[0,1]
	v_mov_b32_e32 v60, v59
	v_pk_mul_f32 v[12:13], v[8:9], v[60:61] op_sel_hi:[0,1]
	v_and_b32_sdwa v9, v11, v176 dst_sel:DWORD dst_unused:UNUSED_PAD src0_sel:WORD_1 src1_sel:DWORD
	v_and_b32_sdwa v14, v10, v176 dst_sel:DWORD dst_unused:UNUSED_PAD src0_sel:WORD_1 src1_sel:DWORD
	v_add3_u32 v10, v10, v14, s22
	v_add3_u32 v9, v11, v9, s22
	v_and_b32_sdwa v11, v13, v176 dst_sel:DWORD dst_unused:UNUSED_PAD src0_sel:WORD_1 src1_sel:DWORD
	v_and_b32_sdwa v14, v12, v176 dst_sel:DWORD dst_unused:UNUSED_PAD src0_sel:WORD_1 src1_sel:DWORD
	v_add3_u32 v11, v13, v11, s22
	v_add3_u32 v12, v12, v14, s22
	v_and_b32_e32 v11, 0xffff0000, v11
	v_and_b32_e32 v12, 0xffff0000, v12
	v_or_b32_sdwa v11, v11, v9 dst_sel:DWORD dst_unused:UNUSED_PAD src0_sel:DWORD src1_sel:WORD_1
	v_or_b32_sdwa v10, v12, v10 dst_sel:DWORD dst_unused:UNUSED_PAD src0_sel:DWORD src1_sel:WORD_1
	global_store_dwordx2 v[6:7], v[10:11], off offset:288
	v_mov_b32_e32 v10, v62
	v_mov_b32_e32 v11, v64
	v_pk_mul_f32 v[10:11], v[8:9], v[10:11] op_sel_hi:[0,1]
	v_mov_b32_e32 v64, v63
	v_pk_mul_f32 v[12:13], v[8:9], v[64:65] op_sel_hi:[0,1]
	v_and_b32_sdwa v9, v11, v176 dst_sel:DWORD dst_unused:UNUSED_PAD src0_sel:WORD_1 src1_sel:DWORD
	v_and_b32_sdwa v14, v10, v176 dst_sel:DWORD dst_unused:UNUSED_PAD src0_sel:WORD_1 src1_sel:DWORD
	v_add3_u32 v10, v10, v14, s22
; __device__ __forceinline__ unsigned pk2(float lo, float hi) { return f2bf(lo) | (f2bf(hi) << 16); }
; __device__ __forceinline__ void xattn_lds(const Ctx& C, const bf16* P, int cqoff, const bf16* MEMKV, const bf16* MEMVT, bf16* CAT, int ldc, int catoff, int u0, int ustride) {
;     ...
;     for (int u = u0; u < 256; u += ustride) {
;     ...
;         for (int dt = 0; dt < 16; ++dt) { v2u ow; ow.x = pk2(o[dt][0] * inv, o[dt][1] * inv); ow.y = pk2(o[dt][2] * inv, o[dt][3] * inv); *(v2u*)(op + dt * 16) = ow; }
	v_add3_u32 v9, v11, v9, s22
	v_and_b32_sdwa v11, v13, v176 dst_sel:DWORD dst_unused:UNUSED_PAD src0_sel:WORD_1 src1_sel:DWORD
	v_and_b32_sdwa v14, v12, v176 dst_sel:DWORD dst_unused:UNUSED_PAD src0_sel:WORD_1 src1_sel:DWORD
	v_add3_u32 v11, v13, v11, s22
	v_add3_u32 v12, v12, v14, s22
	v_and_b32_e32 v11, 0xffff0000, v11
	v_and_b32_e32 v12, 0xffff0000, v12
	v_or_b32_sdwa v11, v11, v9 dst_sel:DWORD dst_unused:UNUSED_PAD src0_sel:DWORD src1_sel:WORD_1
	v_or_b32_sdwa v10, v12, v10 dst_sel:DWORD dst_unused:UNUSED_PAD src0_sel:DWORD src1_sel:WORD_1
	global_store_dwordx2 v[6:7], v[10:11], off offset:320
	v_mov_b32_e32 v10, v66
	v_mov_b32_e32 v11, v68
	v_pk_mul_f32 v[10:11], v[8:9], v[10:11] op_sel_hi:[0,1]
	v_mov_b32_e32 v68, v67
	v_pk_mul_f32 v[12:13], v[8:9], v[68:69] op_sel_hi:[0,1]
	v_and_b32_sdwa v9, v11, v176 dst_sel:DWORD dst_unused:UNUSED_PAD src0_sel:WORD_1 src1_sel:DWORD
	v_and_b32_sdwa v14, v10, v176 dst_sel:DWORD dst_unused:UNUSED_PAD src0_sel:WORD_1 src1_sel:DWORD
	v_add3_u32 v10, v10, v14, s22
	v_add3_u32 v9, v11, v9, s22
	v_and_b32_sdwa v11, v13, v176 dst_sel:DWORD dst_unused:UNUSED_PAD src0_sel:WORD_1 src1_sel:DWORD
	v_and_b32_sdwa v14, v12, v176 dst_sel:DWORD dst_unused:UNUSED_PAD src0_sel:WORD_1 src1_sel:DWORD
	v_add3_u32 v11, v13, v11, s22
	v_add3_u32 v12, v12, v14, s22
	v_and_b32_e32 v11, 0xffff0000, v11
	v_and_b32_e32 v12, 0xffff0000, v12
	v_or_b32_sdwa v11, v11, v9 dst_sel:DWORD dst_unused:UNUSED_PAD src0_sel:DWORD src1_sel:WORD_1
	v_or_b32_sdwa v10, v12, v10 dst_sel:DWORD dst_unused:UNUSED_PAD src0_sel:DWORD src1_sel:WORD_1
	global_store_dwordx2 v[6:7], v[10:11], off offset:352
	v_mov_b32_e32 v10, v74
	v_mov_b32_e32 v11, v76
	v_pk_mul_f32 v[10:11], v[8:9], v[10:11] op_sel_hi:[0,1]
	v_mov_b32_e32 v76, v75
	v_pk_mul_f32 v[12:13], v[8:9], v[76:77] op_sel_hi:[0,1]
	v_and_b32_sdwa v9, v11, v176 dst_sel:DWORD dst_unused:UNUSED_PAD src0_sel:WORD_1 src1_sel:DWORD
	v_and_b32_sdwa v14, v10, v176 dst_sel:DWORD dst_unused:UNUSED_PAD src0_sel:WORD_1 src1_sel:DWORD
	v_add3_u32 v10, v10, v14, s22
	v_add3_u32 v9, v11, v9, s22
	v_and_b32_sdwa v11, v13, v176 dst_sel:DWORD dst_unused:UNUSED_PAD src0_sel:WORD_1 src1_sel:DWORD
	v_and_b32_sdwa v14, v12, v176 dst_sel:DWORD dst_unused:UNUSED_PAD src0_sel:WORD_1 src1_sel:DWORD
	v_add3_u32 v11, v13, v11, s22
	v_add3_u32 v12, v12, v14, s22
	v_and_b32_e32 v11, 0xffff0000, v11
	v_and_b32_e32 v12, 0xffff0000, v12
	v_or_b32_sdwa v11, v11, v9 dst_sel:DWORD dst_unused:UNUSED_PAD src0_sel:DWORD src1_sel:WORD_1
	v_or_b32_sdwa v10, v12, v10 dst_sel:DWORD dst_unused:UNUSED_PAD src0_sel:DWORD src1_sel:WORD_1
	global_store_dwordx2 v[6:7], v[10:11], off offset:384
	v_mov_b32_e32 v10, v78
	v_mov_b32_e32 v11, v80
	v_pk_mul_f32 v[10:11], v[8:9], v[10:11] op_sel_hi:[0,1]
	v_mov_b32_e32 v80, v79
	v_pk_mul_f32 v[12:13], v[8:9], v[80:81] op_sel_hi:[0,1]
	v_and_b32_sdwa v9, v11, v176 dst_sel:DWORD dst_unused:UNUSED_PAD src0_sel:WORD_1 src1_sel:DWORD
	v_and_b32_sdwa v14, v10, v176 dst_sel:DWORD dst_unused:UNUSED_PAD src0_sel:WORD_1 src1_sel:DWORD
	v_add3_u32 v10, v10, v14, s22
	v_add3_u32 v9, v11, v9, s22
	v_and_b32_sdwa v11, v13, v176 dst_sel:DWORD dst_unused:UNUSED_PAD src0_sel:WORD_1 src1_sel:DWORD
	v_and_b32_sdwa v14, v12, v176 dst_sel:DWORD dst_unused:UNUSED_PAD src0_sel:WORD_1 src1_sel:DWORD
	v_add3_u32 v11, v13, v11, s22
	v_add3_u32 v12, v12, v14, s22
	v_and_b32_e32 v11, 0xffff0000, v11
	v_and_b32_e32 v12, 0xffff0000, v12
	v_or_b32_sdwa v11, v11, v9 dst_sel:DWORD dst_unused:UNUSED_PAD src0_sel:DWORD src1_sel:WORD_1
	v_or_b32_sdwa v10, v12, v10 dst_sel:DWORD dst_unused:UNUSED_PAD src0_sel:DWORD src1_sel:WORD_1
	global_store_dwordx2 v[6:7], v[10:11], off offset:416
	v_mov_b32_e32 v10, v70
	v_mov_b32_e32 v11, v72
	v_pk_mul_f32 v[10:11], v[8:9], v[10:11] op_sel_hi:[0,1]
	v_mov_b32_e32 v72, v71
	v_pk_mul_f32 v[12:13], v[8:9], v[72:73] op_sel_hi:[0,1]
	v_and_b32_sdwa v9, v11, v176 dst_sel:DWORD dst_unused:UNUSED_PAD src0_sel:WORD_1 src1_sel:DWORD
	v_and_b32_sdwa v14, v10, v176 dst_sel:DWORD dst_unused:UNUSED_PAD src0_sel:WORD_1 src1_sel:DWORD
	v_add3_u32 v10, v10, v14, s22
	v_add3_u32 v9, v11, v9, s22
	v_and_b32_sdwa v11, v13, v176 dst_sel:DWORD dst_unused:UNUSED_PAD src0_sel:WORD_1 src1_sel:DWORD
	v_and_b32_sdwa v14, v12, v176 dst_sel:DWORD dst_unused:UNUSED_PAD src0_sel:WORD_1 src1_sel:DWORD
	v_add3_u32 v11, v13, v11, s22
	v_add3_u32 v12, v12, v14, s22
	v_and_b32_e32 v11, 0xffff0000, v11
	v_and_b32_e32 v12, 0xffff0000, v12
	v_or_b32_sdwa v11, v11, v9 dst_sel:DWORD dst_unused:UNUSED_PAD src0_sel:DWORD src1_sel:WORD_1
	v_or_b32_sdwa v10, v12, v10 dst_sel:DWORD dst_unused:UNUSED_PAD src0_sel:DWORD src1_sel:WORD_1
	global_store_dwordx2 v[6:7], v[10:11], off offset:448
	v_mov_b32_e32 v11, v4
	v_mov_b32_e32 v4, v3
	v_mov_b32_e32 v10, v2
	v_pk_mul_f32 v[2:3], v[8:9], v[4:5] op_sel_hi:[0,1]
	v_pk_mul_f32 v[10:11], v[8:9], v[10:11] op_sel_hi:[0,1]
	v_and_b32_sdwa v8, v3, v176 dst_sel:DWORD dst_unused:UNUSED_PAD src0_sel:WORD_1 src1_sel:DWORD
	v_and_b32_sdwa v9, v2, v176 dst_sel:DWORD dst_unused:UNUSED_PAD src0_sel:WORD_1 src1_sel:DWORD
	v_and_b32_sdwa v4, v11, v176 dst_sel:DWORD dst_unused:UNUSED_PAD src0_sel:WORD_1 src1_sel:DWORD
	v_and_b32_sdwa v5, v10, v176 dst_sel:DWORD dst_unused:UNUSED_PAD src0_sel:WORD_1 src1_sel:DWORD
	v_add3_u32 v3, v3, v8, s22
	v_add3_u32 v2, v2, v9, s22
	v_add3_u32 v5, v10, v5, s22
	v_add3_u32 v4, v11, v4, s22
	v_and_b32_e32 v3, 0xffff0000, v3
	v_and_b32_e32 v2, 0xffff0000, v2
	v_or_b32_sdwa v3, v3, v4 dst_sel:DWORD dst_unused:UNUSED_PAD src0_sel:DWORD src1_sel:WORD_1
	v_or_b32_sdwa v2, v2, v5 dst_sel:DWORD dst_unused:UNUSED_PAD src0_sel:DWORD src1_sel:WORD_1
	global_store_dwordx2 v[6:7], v[2:3], off offset:480
	s_cbranch_scc1 .LBB0_1331
